# stack: off-diagonal stick-breaking body + MLA loop half-step stagger of waves 4-7 with priority raise on the QK MFMA burst + s_setprio hoisted over the pre-MFMA barrier in the GEMM K-loops
# speedup vs baseline: 1.0037x; 1.0037x over previous
;     __device__ __forceinline__ bool next(int i, Unit& u) const { if (!S.next(i, u)) return false; if (u.pn >= 4) u.pn += 2; return true; }
; #define PG8_STAGE(bufoff, gbase, voff) do { _Pragma("unroll") for (int _i = 0; _i < 2; ++_i) \
;         __builtin_amdgcn_global_load_lds((const unsigned*)((const char*)(gbase) + (voff)[_i]), (PG8_LAS unsigned*)(lds + (bufoff) + ldsw + _i * 8192), 16, 0, 0); } while (0)
; #define PG8_LDA(dst, b, h) do { _Pragma("unroll") for (int m = 0; m < 4; ++m) _Pragma("unroll") for (int k = 0; k < 2; ++k) dst[m][k] = *(const PG8_LAS bf16x8*)(lds + PG8_SA(b, h) + aoff + m * 2048 + k * 1024); } while (0)
; template <class Epi, class Sched, bool ALIGN_EPI = false, bool SP2 = false>
; __device__ __forceinline__ void gemm_phase(PG8_LAS unsigned char* lds, const Gemm g, const Sched& S, const Epi& E) {
;     ...
;         const bool has_next = S.next(ui + 1, nxt);
;         if constexpr (Epi::LDS_PF) { if (has_next) E.prefetch(nxt, lds + STAGE_BYTES + ((ui + 1) % 3) * 4096, wid, lane); }
;         const char* nA = has_next ? (const char*)g.A + (size_t)nxt.pm * tstepA : cA; const char* nB = has_next ? (const char*)g.Bt + (size_t)nxt.pn * tstepB : cB;
;         for (int t = 0; t < nt; t += 2) {
;             const bool last = (t == nt - 2);
;             const char* a1 = cA + (size_t)(t + 1) * kstep;
;             const char* a2 = last ? nA : cA + (size_t)(t + 2) * kstep; const char* b2 = last ? nB : cB + (size_t)(t + 2) * kstep;
;             const char* a3 = a2 + kstep; const char* b3 = b2 + kstep;
;             if (last && has_next) S.a_ready(nxt);
;             if constexpr (SP2) {
;             PG8_LDB(B0, 0, 0); PG8_LDB(B1, 0, 1); PG8_SCHED; PG8_LDA(At, 0, 0); PG8_STAGE(PG8_SA(1, 1), a1 + hstepA, voffA);
;             PG8_WAIT_V(8); PG8_WAIT_L(0); PG8_BAR; PG8_MMA(0, 0, At, B0); PG8_MMA(0, 1, At, B1); PG8_BAR; PG8_SCHED;
;             PG8_LDA(At, 0, 1); PG8_STAGE(PG8_SB(0, 0), b2, voffB); PG8_STAGE(PG8_SB(0, 1), b2 + hstepB, voffB); PG8_STAGE(PG8_SA(0, 0), a2, voffA);
;     ...
; #pragma unroll
;         for (int a = 0; a < 2; ++a)
; #pragma unroll
;             for (int b = 0; b < 2; ++b)
; #pragma unroll
;                 for (int m = 0; m < 4; ++m)
; #pragma unroll
;                     for (int n = 0; n < 2; ++n) acc[a][b][m][n] = (f32x4){0.f, 0.f, 0.f, 0.f};
;         cur = nxt; cA = nA; cB = nB; ++ui;
.LBB0_144:
	s_ashr_i32 s21, s20, 31
	s_lshl_b64 s[0:1], s[20:21], 19
	v_readlane_b32 s22, v253, 23
	v_readlane_b32 s23, v253, 24
	s_add_u32 s22, s22, s0
	s_addc_u32 s23, s23, s1
	s_and_b64 s[0:1], s[6:7], exec
	s_cselect_b32 s5, s23, s29
	s_cselect_b32 s21, s22, s28
	s_ashr_i32 s19, s18, 31
	s_lshl_b64 s[0:1], s[18:19], 19
	s_add_u32 s24, s8, s0
	s_addc_u32 s25, s9, s1
	s_and_b64 s[0:1], s[6:7], exec
	s_cselect_b32 s19, s25, s31
	s_cselect_b32 s48, s24, s30
	s_add_u32 s28, s28, 0x40080
	s_addc_u32 s29, s29, 0
	s_add_u32 s49, s30, 0x100
	v_mov_b32_e32 v2, 0
	s_addc_u32 s50, s31, 0
	s_mov_b32 s51, -2
	v_mov_b32_e32 v3, v2
	v_mov_b32_e32 v4, v2
	v_mov_b32_e32 v5, v2
	v_mov_b32_e32 v6, v2
	v_mov_b32_e32 v7, v2
	v_mov_b32_e32 v8, v2
	v_mov_b32_e32 v9, v2
	v_mov_b32_e32 v10, v2
	v_mov_b32_e32 v11, v2
	v_mov_b32_e32 v12, v2
	v_mov_b32_e32 v13, v2
	v_mov_b32_e32 v18, v2
	v_mov_b32_e32 v19, v2
	v_mov_b32_e32 v20, v2
	v_mov_b32_e32 v21, v2
	v_mov_b32_e32 v26, v2
	v_mov_b32_e32 v27, v2
	v_mov_b32_e32 v28, v2
	v_mov_b32_e32 v29, v2
	v_mov_b32_e32 v34, v2
	v_mov_b32_e32 v35, v2
	v_mov_b32_e32 v36, v2
	v_mov_b32_e32 v37, v2
	v_mov_b32_e32 v42, v2
	v_mov_b32_e32 v43, v2
	v_mov_b32_e32 v44, v2
	v_mov_b32_e32 v45, v2
	v_mov_b32_e32 v50, v2
	v_mov_b32_e32 v51, v2
	v_mov_b32_e32 v52, v2
	v_mov_b32_e32 v53, v2
	v_mov_b32_e32 v14, v2
	v_mov_b32_e32 v15, v2
	v_mov_b32_e32 v16, v2
	v_mov_b32_e32 v17, v2
	v_mov_b32_e32 v22, v2
	v_mov_b32_e32 v23, v2
	v_mov_b32_e32 v24, v2
	v_mov_b32_e32 v25, v2
	v_mov_b32_e32 v30, v2
	v_mov_b32_e32 v31, v2
	v_mov_b32_e32 v32, v2
	v_mov_b32_e32 v33, v2
	v_mov_b32_e32 v38, v2
	v_mov_b32_e32 v39, v2
	v_mov_b32_e32 v40, v2
	v_mov_b32_e32 v41, v2
	v_mov_b32_e32 v46, v2
	v_mov_b32_e32 v47, v2
	v_mov_b32_e32 v48, v2
	v_mov_b32_e32 v49, v2
	v_mov_b32_e32 v54, v2
	v_mov_b32_e32 v55, v2
	v_mov_b32_e32 v56, v2
	v_mov_b32_e32 v57, v2
	v_mov_b32_e32 v58, v2
	v_mov_b32_e32 v59, v2
	v_mov_b32_e32 v60, v2
	v_mov_b32_e32 v61, v2
	v_mov_b32_e32 v62, v2
	v_mov_b32_e32 v63, v2
	v_mov_b32_e32 v64, v2
	v_mov_b32_e32 v65, v2
	v_mov_b32_e32 v66, v2
	v_mov_b32_e32 v67, v2
	v_mov_b32_e32 v68, v2
	v_mov_b32_e32 v69, v2
	v_mov_b32_e32 v70, v2
	v_mov_b32_e32 v71, v2
	v_mov_b32_e32 v72, v2
	v_mov_b32_e32 v73, v2
	v_mov_b32_e32 v74, v2
	v_mov_b32_e32 v75, v2
	v_mov_b32_e32 v76, v2
	v_mov_b32_e32 v77, v2
	v_mov_b32_e32 v82, v2
	v_mov_b32_e32 v83, v2
	v_mov_b32_e32 v84, v2
	v_mov_b32_e32 v85, v2
	v_mov_b32_e32 v90, v2
	v_mov_b32_e32 v91, v2
	v_mov_b32_e32 v92, v2
	v_mov_b32_e32 v93, v2
	v_mov_b32_e32 v98, v2
	v_mov_b32_e32 v99, v2
	v_mov_b32_e32 v100, v2
	v_mov_b32_e32 v101, v2
	v_mov_b32_e32 v106, v2
	v_mov_b32_e32 v107, v2
	v_mov_b32_e32 v108, v2
	v_mov_b32_e32 v109, v2
	v_mov_b32_e32 v114, v2
	v_mov_b32_e32 v115, v2
	v_mov_b32_e32 v116, v2
	v_mov_b32_e32 v117, v2
	v_mov_b32_e32 v78, v2
	v_mov_b32_e32 v79, v2
	v_mov_b32_e32 v80, v2
	v_mov_b32_e32 v81, v2
	v_mov_b32_e32 v86, v2
	v_mov_b32_e32 v87, v2
	v_mov_b32_e32 v88, v2
	v_mov_b32_e32 v89, v2
	v_mov_b32_e32 v94, v2
	v_mov_b32_e32 v95, v2
	v_mov_b32_e32 v96, v2
	v_mov_b32_e32 v97, v2
	v_mov_b32_e32 v102, v2
	v_mov_b32_e32 v103, v2
	v_mov_b32_e32 v104, v2
	v_mov_b32_e32 v105, v2
	v_mov_b32_e32 v110, v2
	v_mov_b32_e32 v111, v2
	v_mov_b32_e32 v112, v2
	v_mov_b32_e32 v113, v2
	v_mov_b32_e32 v118, v2
	v_mov_b32_e32 v119, v2
	v_mov_b32_e32 v120, v2
	v_mov_b32_e32 v121, v2
	v_mov_b32_e32 v122, v2
	v_mov_b32_e32 v123, v2
	v_mov_b32_e32 v124, v2
	v_mov_b32_e32 v125, v2
	v_mov_b32_e32 v126, v2
	v_mov_b32_e32 v127, v2
	v_mov_b32_e32 v128, v2
	v_mov_b32_e32 v129, v2
.LBB0_145:
	ds_read_b128 v[146:149], v151
	ds_read_b128 v[156:159], v151 offset:1024
	ds_read_b128 v[160:163], v151 offset:2048
	ds_read_b128 v[164:167], v151 offset:3072
	ds_read_b128 v[168:171], v152
	ds_read_b128 v[172:175], v152 offset:1024
	ds_read_b128 v[176:179], v152 offset:2048
	ds_read_b128 v[180:183], v152 offset:3072
	s_add_u32 s0, s28, 0xfffc0080
	s_addc_u32 s1, s29, -1
	s_cmp_eq_u32 s51, 12
	s_cselect_b32 s35, s5, s1
	s_cselect_b32 s34, s21, s0
	s_cselect_b32 s31, s19, s50
	s_cselect_b32 s30, s48, s49
	v_lshl_add_u64 v[216:217], s[28:29], 0, v[138:139]
	s_add_i32 m0, s27, 0xc000
	ds_read_b128 v[184:187], v153
	ds_read_b128 v[188:191], v153 offset:1024
	ds_read_b128 v[192:195], v153 offset:2048
	ds_read_b128 v[196:199], v153 offset:3072
	ds_read_b128 v[200:203], v153 offset:4096
	ds_read_b128 v[204:207], v153 offset:5120
	ds_read_b128 v[208:211], v153 offset:6144
	ds_read_b128 v[212:215], v153 offset:7168
	global_load_lds_dwordx4 v[216:217], off
	v_lshl_add_u64 v[216:217], s[28:29], 0, v[140:141]
	s_add_i32 m0, s27, 0xe000
	s_nop 0
	global_load_lds_dwordx4 v[216:217], off
	s_waitcnt vmcnt(8)
	s_waitcnt lgkmcnt(0)
	s_setprio 1
	s_barrier
; #define PG8_STAGE(bufoff, gbase, voff) do { _Pragma("unroll") for (int _i = 0; _i < 2; ++_i) \
;         __builtin_amdgcn_global_load_lds((const unsigned*)((const char*)(gbase) + (voff)[_i]), (PG8_LAS unsigned*)(lds + (bufoff) + ldsw + _i * 8192), 16, 0, 0); } while (0)
; #define PG8_LDA(dst, b, h) do { _Pragma("unroll") for (int m = 0; m < 4; ++m) _Pragma("unroll") for (int k = 0; k < 2; ++k) dst[m][k] = *(const PG8_LAS bf16x8*)(lds + PG8_SA(b, h) + aoff + m * 2048 + k * 1024); } while (0)
; #define PG8_LDB(dst, b, h) do { _Pragma("unroll") for (int n = 0; n < 2; ++n) _Pragma("unroll") for (int k = 0; k < 2; ++k) dst[n][k] = *(const PG8_LAS bf16x8*)(lds + PG8_SB(b, h) + boff + n * 2048 + k * 1024); } while (0)
; #define PG8_MMA(ai, bj, At, Bt) do { __builtin_amdgcn_s_setprio(1); _Pragma("unroll") for (int m = 0; m < 4; ++m) _Pragma("unroll") for (int n = 0; n < 2; ++n) _Pragma("unroll") for (int k = 0; k < 2; ++k) \
;         acc[ai][bj][m][n] = __builtin_amdgcn_mfma_f32_16x16x32_bf16(Bt[n][k], At[m][k], acc[ai][bj][m][n], 0, 0, 0); __builtin_amdgcn_s_setprio(0); } while (0)
; #define PG8_WAIT_V(n) asm volatile("s_waitcnt vmcnt(" #n ")" ::: "memory")
; #define PG8_WAIT_L(n) asm volatile("s_waitcnt lgkmcnt(" #n ")" ::: "memory")
; #define PG8_BAR __builtin_amdgcn_s_barrier()
; #define PG8_SCHED __builtin_amdgcn_sched_barrier(0)
; template <class Epi, class Sched, bool ALIGN_EPI = false, bool SP2 = false>
; __device__ __forceinline__ void gemm_phase(PG8_LAS unsigned char* lds, const Gemm g, const Sched& S, const Epi& E) {
;     ...
;             PG8_LDB(B0, 0, 0); PG8_LDB(B1, 0, 1); PG8_SCHED; PG8_LDA(At, 0, 0); PG8_STAGE(PG8_SA(1, 1), a1 + hstepA, voffA);
;             PG8_WAIT_V(8); PG8_WAIT_L(0); PG8_BAR; PG8_MMA(0, 0, At, B0); PG8_MMA(0, 1, At, B1); PG8_BAR; PG8_SCHED;
;             PG8_LDA(At, 0, 1); PG8_STAGE(PG8_SB(0, 0), b2, voffB); PG8_STAGE(PG8_SB(0, 1), b2 + hstepB, voffB); PG8_STAGE(PG8_SA(0, 0), a2, voffA);
;             PG8_WAIT_V(8); PG8_WAIT_L(0); PG8_BAR; PG8_MMA(1, 0, At, B0); PG8_MMA(1, 1, At, B1); PG8_BAR; PG8_SCHED;
	v_mfma_f32_16x16x32_bf16 v[126:129], v[146:149], v[184:187], v[126:129]
	v_mfma_f32_16x16x32_bf16 v[122:125], v[160:163], v[184:187], v[122:125]
	v_mfma_f32_16x16x32_bf16 v[118:121], v[146:149], v[192:195], v[118:121]
	v_mfma_f32_16x16x32_bf16 v[110:113], v[160:163], v[192:195], v[110:113]
	v_mfma_f32_16x16x32_bf16 v[102:105], v[146:149], v[200:203], v[102:105]
	v_mfma_f32_16x16x32_bf16 v[94:97], v[160:163], v[200:203], v[94:97]
	v_mfma_f32_16x16x32_bf16 v[86:89], v[146:149], v[208:211], v[86:89]
	v_mfma_f32_16x16x32_bf16 v[78:81], v[160:163], v[208:211], v[78:81]
	v_mfma_f32_16x16x32_bf16 v[126:129], v[156:159], v[188:191], v[126:129]
	v_mfma_f32_16x16x32_bf16 v[122:125], v[164:167], v[188:191], v[122:125]
	v_mfma_f32_16x16x32_bf16 v[118:121], v[156:159], v[196:199], v[118:121]
	v_mfma_f32_16x16x32_bf16 v[110:113], v[164:167], v[196:199], v[110:113]
	v_mfma_f32_16x16x32_bf16 v[102:105], v[156:159], v[204:207], v[102:105]
	v_mfma_f32_16x16x32_bf16 v[94:97], v[164:167], v[204:207], v[94:97]
	v_mfma_f32_16x16x32_bf16 v[86:89], v[156:159], v[212:215], v[86:89]
	v_mfma_f32_16x16x32_bf16 v[78:81], v[164:167], v[212:215], v[78:81]
	s_setprio 0
	s_setprio 1
	v_mfma_f32_16x16x32_bf16 v[114:117], v[168:171], v[184:187], v[114:117]
	v_mfma_f32_16x16x32_bf16 v[106:109], v[176:179], v[184:187], v[106:109]
	v_mfma_f32_16x16x32_bf16 v[98:101], v[168:171], v[192:195], v[98:101]
	v_mfma_f32_16x16x32_bf16 v[90:93], v[176:179], v[192:195], v[90:93]
	v_mfma_f32_16x16x32_bf16 v[82:85], v[168:171], v[200:203], v[82:85]
	v_mfma_f32_16x16x32_bf16 v[74:77], v[176:179], v[200:203], v[74:77]
	v_mfma_f32_16x16x32_bf16 v[70:73], v[168:171], v[208:211], v[70:73]
	v_mfma_f32_16x16x32_bf16 v[66:69], v[176:179], v[208:211], v[66:69]
	v_mfma_f32_16x16x32_bf16 v[114:117], v[172:175], v[188:191], v[114:117]
	v_mfma_f32_16x16x32_bf16 v[106:109], v[180:183], v[188:191], v[106:109]
	v_mfma_f32_16x16x32_bf16 v[98:101], v[172:175], v[196:199], v[98:101]
	v_mfma_f32_16x16x32_bf16 v[90:93], v[180:183], v[196:199], v[90:93]
	v_mfma_f32_16x16x32_bf16 v[82:85], v[172:175], v[204:207], v[82:85]
	v_mfma_f32_16x16x32_bf16 v[74:77], v[180:183], v[204:207], v[74:77]
	v_mfma_f32_16x16x32_bf16 v[70:73], v[172:175], v[212:215], v[70:73]
	v_mfma_f32_16x16x32_bf16 v[66:69], v[180:183], v[212:215], v[66:69]
	s_setprio 0
	s_barrier
	s_add_i32 s0, s43, s3
	v_lshl_add_u64 v[216:217], s[30:31], 0, v[134:135]
	s_mov_b32 m0, s0
	ds_read_b128 v[184:187], v153 offset:16384
	ds_read_b128 v[188:191], v153 offset:17408
	ds_read_b128 v[192:195], v153 offset:18432
	ds_read_b128 v[196:199], v153 offset:19456
	ds_read_b128 v[200:203], v153 offset:20480
	ds_read_b128 v[204:207], v153 offset:21504
	ds_read_b128 v[208:211], v153 offset:22528
	ds_read_b128 v[212:215], v153 offset:23552
	global_load_lds_dwordx4 v[216:217], off
	s_add_i32 m0, s0, 0x2000
	s_add_u32 s0, s30, 0x40000
	v_lshl_add_u64 v[218:219], s[30:31], 0, v[130:131]
	s_addc_u32 s1, s31, 0
	s_add_i32 s2, s44, s3
	global_load_lds_dwordx4 v[218:219], off
	v_lshl_add_u64 v[220:221], s[0:1], 0, v[134:135]
	s_mov_b32 m0, s2
	v_lshl_add_u64 v[222:223], s[34:35], 0, v[132:133]
	global_load_lds_dwordx4 v[220:221], off
	v_lshl_add_u64 v[220:221], s[0:1], 0, v[130:131]
	s_add_i32 m0, s2, 0x2000
	s_nop 0
	global_load_lds_dwordx4 v[220:221], off
	v_lshl_add_u64 v[220:221], s[34:35], 0, v[136:137]
	s_mov_b32 m0, s27
	s_nop 0
	global_load_lds_dwordx4 v[220:221], off
	s_mov_b32 m0, s36
	s_nop 0
	global_load_lds_dwordx4 v[222:223], off
	s_waitcnt vmcnt(8)
	s_waitcnt lgkmcnt(0)
	s_setprio 1
	s_barrier
	v_mfma_f32_16x16x32_bf16 v[62:65], v[146:149], v[184:187], v[62:65]
	v_mfma_f32_16x16x32_bf16 v[58:61], v[160:163], v[184:187], v[58:61]
	v_mfma_f32_16x16x32_bf16 v[54:57], v[146:149], v[192:195], v[54:57]
	v_mfma_f32_16x16x32_bf16 v[46:49], v[160:163], v[192:195], v[46:49]
	v_mfma_f32_16x16x32_bf16 v[38:41], v[146:149], v[200:203], v[38:41]
	v_mfma_f32_16x16x32_bf16 v[30:33], v[160:163], v[200:203], v[30:33]
	v_mfma_f32_16x16x32_bf16 v[22:25], v[146:149], v[208:211], v[22:25]
	v_mfma_f32_16x16x32_bf16 v[14:17], v[160:163], v[208:211], v[14:17]
	v_mfma_f32_16x16x32_bf16 v[62:65], v[156:159], v[188:191], v[62:65]
	v_mfma_f32_16x16x32_bf16 v[58:61], v[164:167], v[188:191], v[58:61]
	v_mfma_f32_16x16x32_bf16 v[54:57], v[156:159], v[196:199], v[54:57]
	v_mfma_f32_16x16x32_bf16 v[46:49], v[164:167], v[196:199], v[46:49]
	v_mfma_f32_16x16x32_bf16 v[38:41], v[156:159], v[204:207], v[38:41]
	v_mfma_f32_16x16x32_bf16 v[30:33], v[164:167], v[204:207], v[30:33]
	v_mfma_f32_16x16x32_bf16 v[22:25], v[156:159], v[212:215], v[22:25]
	v_mfma_f32_16x16x32_bf16 v[14:17], v[164:167], v[212:215], v[14:17]
	s_setprio 0
	s_setprio 1
	v_mfma_f32_16x16x32_bf16 v[50:53], v[168:171], v[184:187], v[50:53]
	v_mfma_f32_16x16x32_bf16 v[42:45], v[176:179], v[184:187], v[42:45]
	v_mfma_f32_16x16x32_bf16 v[34:37], v[168:171], v[192:195], v[34:37]
	v_mfma_f32_16x16x32_bf16 v[26:29], v[176:179], v[192:195], v[26:29]
	v_mfma_f32_16x16x32_bf16 v[18:21], v[168:171], v[200:203], v[18:21]
	v_mfma_f32_16x16x32_bf16 v[10:13], v[176:179], v[200:203], v[10:13]
	v_mfma_f32_16x16x32_bf16 v[6:9], v[168:171], v[208:211], v[6:9]
	v_mfma_f32_16x16x32_bf16 v[2:5], v[176:179], v[208:211], v[2:5]
	v_mfma_f32_16x16x32_bf16 v[50:53], v[172:175], v[188:191], v[50:53]
	v_mfma_f32_16x16x32_bf16 v[42:45], v[180:183], v[188:191], v[42:45]
	v_mfma_f32_16x16x32_bf16 v[34:37], v[172:175], v[196:199], v[34:37]
	v_mfma_f32_16x16x32_bf16 v[26:29], v[180:183], v[196:199], v[26:29]
	v_mfma_f32_16x16x32_bf16 v[18:21], v[172:175], v[204:207], v[18:21]
	v_mfma_f32_16x16x32_bf16 v[10:13], v[180:183], v[204:207], v[10:13]
	v_mfma_f32_16x16x32_bf16 v[6:9], v[172:175], v[212:215], v[6:9]
	v_mfma_f32_16x16x32_bf16 v[2:5], v[180:183], v[212:215], v[2:5]
	s_setprio 0
	s_barrier
; #define PG8_STAGE(bufoff, gbase, voff) do { _Pragma("unroll") for (int _i = 0; _i < 2; ++_i) \
;         __builtin_amdgcn_global_load_lds((const unsigned*)((const char*)(gbase) + (voff)[_i]), (PG8_LAS unsigned*)(lds + (bufoff) + ldsw + _i * 8192), 16, 0, 0); } while (0)
; #define PG8_LDA(dst, b, h) do { _Pragma("unroll") for (int m = 0; m < 4; ++m) _Pragma("unroll") for (int k = 0; k < 2; ++k) dst[m][k] = *(const PG8_LAS bf16x8*)(lds + PG8_SA(b, h) + aoff + m * 2048 + k * 1024); } while (0)
; #define PG8_LDB(dst, b, h) do { _Pragma("unroll") for (int n = 0; n < 2; ++n) _Pragma("unroll") for (int k = 0; k < 2; ++k) dst[n][k] = *(const PG8_LAS bf16x8*)(lds + PG8_SB(b, h) + boff + n * 2048 + k * 1024); } while (0)
; #define PG8_MMA(ai, bj, At, Bt) do { __builtin_amdgcn_s_setprio(1); _Pragma("unroll") for (int m = 0; m < 4; ++m) _Pragma("unroll") for (int n = 0; n < 2; ++n) _Pragma("unroll") for (int k = 0; k < 2; ++k) \
;         acc[ai][bj][m][n] = __builtin_amdgcn_mfma_f32_16x16x32_bf16(Bt[n][k], At[m][k], acc[ai][bj][m][n], 0, 0, 0); __builtin_amdgcn_s_setprio(0); } while (0)
; #define PG8_WAIT_V(n) asm volatile("s_waitcnt vmcnt(" #n ")" ::: "memory")
; #define PG8_WAIT_L(n) asm volatile("s_waitcnt lgkmcnt(" #n ")" ::: "memory")
; #define PG8_BAR __builtin_amdgcn_s_barrier()
; #define PG8_SCHED __builtin_amdgcn_sched_barrier(0)
; template <class Epi, class Sched, bool ALIGN_EPI = false, bool SP2 = false>
; __device__ __forceinline__ void gemm_phase(PG8_LAS unsigned char* lds, const Gemm g, const Sched& S, const Epi& E) {
;     ...
;         for (int t = 0; t < nt; t += 2) {
;     ...
;             PG8_LDB(B0, 1, 0); PG8_LDB(B1, 1, 1); PG8_SCHED; PG8_LDA(At, 1, 0); PG8_STAGE(PG8_SA(0, 1), a2 + hstepA, voffA);
;             PG8_WAIT_V(8); PG8_WAIT_L(0); PG8_BAR; PG8_MMA(0, 0, At, B0); PG8_MMA(0, 1, At, B1); PG8_BAR; PG8_SCHED;
;             PG8_LDA(At, 1, 1); PG8_STAGE(PG8_SB(1, 0), b3, voffB); PG8_STAGE(PG8_SB(1, 1), b3 + hstepB, voffB); PG8_STAGE(PG8_SA(1, 0), a3, voffA);
;             PG8_WAIT_V(8); PG8_WAIT_L(0); PG8_BAR; PG8_MMA(1, 0, At, B0); PG8_MMA(1, 1, At, B1); PG8_BAR; PG8_SCHED;
;     ...
;         if constexpr (ALIGN_EPI) { if (wr == 0) PG8_BAR; }
	ds_read_b128 v[146:149], v154
	ds_read_b128 v[156:159], v154 offset:1024
	ds_read_b128 v[160:163], v154 offset:2048
	ds_read_b128 v[164:167], v154 offset:3072
	ds_read_b128 v[168:171], v155
	ds_read_b128 v[172:175], v155 offset:1024
	ds_read_b128 v[176:179], v155 offset:2048
	ds_read_b128 v[180:183], v155 offset:3072
	s_add_u32 s0, s34, 0x40000
	s_addc_u32 s1, s35, 0
	s_mov_b32 m0, s37
	v_lshl_add_u64 v[224:225], s[0:1], 0, v[136:137]
	ds_read_b128 v[184:187], v153 offset:32768
	ds_read_b128 v[188:191], v153 offset:33792
	ds_read_b128 v[192:195], v153 offset:34816
	ds_read_b128 v[196:199], v153 offset:35840
	ds_read_b128 v[200:203], v153 offset:36864
	ds_read_b128 v[204:207], v153 offset:37888
	ds_read_b128 v[208:211], v153 offset:38912
	ds_read_b128 v[212:215], v153 offset:39936
	global_load_lds_dwordx4 v[224:225], off
	v_lshl_add_u64 v[224:225], s[0:1], 0, v[132:133]
	s_mov_b32 m0, s38
	s_nop 0
	global_load_lds_dwordx4 v[224:225], off
	s_waitcnt vmcnt(8)
	s_waitcnt lgkmcnt(0)
	s_setprio 1
	s_barrier
	v_mfma_f32_16x16x32_bf16 v[126:129], v[146:149], v[184:187], v[126:129]
	v_mfma_f32_16x16x32_bf16 v[122:125], v[160:163], v[184:187], v[122:125]
	v_mfma_f32_16x16x32_bf16 v[118:121], v[146:149], v[192:195], v[118:121]
	v_mfma_f32_16x16x32_bf16 v[110:113], v[160:163], v[192:195], v[110:113]
	v_mfma_f32_16x16x32_bf16 v[102:105], v[146:149], v[200:203], v[102:105]
	v_mfma_f32_16x16x32_bf16 v[94:97], v[160:163], v[200:203], v[94:97]
	v_mfma_f32_16x16x32_bf16 v[86:89], v[146:149], v[208:211], v[86:89]
	v_mfma_f32_16x16x32_bf16 v[78:81], v[160:163], v[208:211], v[78:81]
	v_mfma_f32_16x16x32_bf16 v[126:129], v[156:159], v[188:191], v[126:129]
	v_mfma_f32_16x16x32_bf16 v[122:125], v[164:167], v[188:191], v[122:125]
	v_mfma_f32_16x16x32_bf16 v[118:121], v[156:159], v[196:199], v[118:121]
	v_mfma_f32_16x16x32_bf16 v[110:113], v[164:167], v[196:199], v[110:113]
	v_mfma_f32_16x16x32_bf16 v[102:105], v[156:159], v[204:207], v[102:105]
	v_mfma_f32_16x16x32_bf16 v[94:97], v[164:167], v[204:207], v[94:97]
	v_mfma_f32_16x16x32_bf16 v[86:89], v[156:159], v[212:215], v[86:89]
	v_mfma_f32_16x16x32_bf16 v[78:81], v[164:167], v[212:215], v[78:81]
	s_setprio 0
	s_setprio 1
	v_mfma_f32_16x16x32_bf16 v[114:117], v[168:171], v[184:187], v[114:117]
	v_mfma_f32_16x16x32_bf16 v[106:109], v[176:179], v[184:187], v[106:109]
	v_mfma_f32_16x16x32_bf16 v[98:101], v[168:171], v[192:195], v[98:101]
	v_mfma_f32_16x16x32_bf16 v[90:93], v[176:179], v[192:195], v[90:93]
	v_mfma_f32_16x16x32_bf16 v[82:85], v[168:171], v[200:203], v[82:85]
	v_mfma_f32_16x16x32_bf16 v[74:77], v[176:179], v[200:203], v[74:77]
	v_mfma_f32_16x16x32_bf16 v[70:73], v[168:171], v[208:211], v[70:73]
	v_mfma_f32_16x16x32_bf16 v[66:69], v[176:179], v[208:211], v[66:69]
	v_mfma_f32_16x16x32_bf16 v[114:117], v[172:175], v[188:191], v[114:117]
	v_mfma_f32_16x16x32_bf16 v[106:109], v[180:183], v[188:191], v[106:109]
	v_mfma_f32_16x16x32_bf16 v[98:101], v[172:175], v[196:199], v[98:101]
	v_mfma_f32_16x16x32_bf16 v[90:93], v[180:183], v[196:199], v[90:93]
	v_mfma_f32_16x16x32_bf16 v[82:85], v[172:175], v[204:207], v[82:85]
	v_mfma_f32_16x16x32_bf16 v[74:77], v[180:183], v[204:207], v[74:77]
	v_mfma_f32_16x16x32_bf16 v[70:73], v[172:175], v[212:215], v[70:73]
	v_mfma_f32_16x16x32_bf16 v[66:69], v[180:183], v[212:215], v[66:69]
	s_setprio 0
	s_barrier
	s_add_i32 s0, s45, s3
	v_lshl_add_u64 v[216:217], v[216:217], 0, s[10:11]
	s_mov_b32 m0, s0
	ds_read_b128 v[184:187], v153 offset:49152
	ds_read_b128 v[188:191], v153 offset:50176
	ds_read_b128 v[192:195], v153 offset:51200
	ds_read_b128 v[196:199], v153 offset:52224
	ds_read_b128 v[200:203], v153 offset:53248
	ds_read_b128 v[204:207], v153 offset:54272
	ds_read_b128 v[208:211], v153 offset:55296
	ds_read_b128 v[212:215], v153 offset:56320
	global_load_lds_dwordx4 v[216:217], off
	s_add_i32 m0, s0, 0x2000
	s_add_u32 s0, s30, 0x40080
	v_lshl_add_u64 v[216:217], v[218:219], 0, s[10:11]
	s_addc_u32 s1, s31, 0
	s_add_i32 s2, s46, s3
	global_load_lds_dwordx4 v[216:217], off
	v_lshl_add_u64 v[216:217], s[0:1], 0, v[134:135]
	s_mov_b32 m0, s2
	s_nop 0
	global_load_lds_dwordx4 v[216:217], off
	v_lshl_add_u64 v[216:217], s[0:1], 0, v[130:131]
	s_add_i32 m0, s2, 0x2000
	s_nop 0
	global_load_lds_dwordx4 v[216:217], off
	v_lshl_add_u64 v[216:217], v[220:221], 0, s[10:11]
	s_mov_b32 m0, s39
	s_nop 0
	global_load_lds_dwordx4 v[216:217], off
	v_lshl_add_u64 v[216:217], v[222:223], 0, s[10:11]
	s_mov_b32 m0, s40
	s_nop 0
	global_load_lds_dwordx4 v[216:217], off
	s_waitcnt vmcnt(8)
	s_waitcnt lgkmcnt(0)
	s_setprio 1
	s_barrier
	v_mfma_f32_16x16x32_bf16 v[62:65], v[146:149], v[184:187], v[62:65]
	v_mfma_f32_16x16x32_bf16 v[58:61], v[160:163], v[184:187], v[58:61]
	v_mfma_f32_16x16x32_bf16 v[54:57], v[146:149], v[192:195], v[54:57]
	v_mfma_f32_16x16x32_bf16 v[46:49], v[160:163], v[192:195], v[46:49]
	v_mfma_f32_16x16x32_bf16 v[38:41], v[146:149], v[200:203], v[38:41]
	v_mfma_f32_16x16x32_bf16 v[30:33], v[160:163], v[200:203], v[30:33]
	v_mfma_f32_16x16x32_bf16 v[22:25], v[146:149], v[208:211], v[22:25]
	v_mfma_f32_16x16x32_bf16 v[14:17], v[160:163], v[208:211], v[14:17]
	v_mfma_f32_16x16x32_bf16 v[62:65], v[156:159], v[188:191], v[62:65]
	v_mfma_f32_16x16x32_bf16 v[58:61], v[164:167], v[188:191], v[58:61]
	v_mfma_f32_16x16x32_bf16 v[54:57], v[156:159], v[196:199], v[54:57]
	v_mfma_f32_16x16x32_bf16 v[46:49], v[164:167], v[196:199], v[46:49]
	v_mfma_f32_16x16x32_bf16 v[38:41], v[156:159], v[204:207], v[38:41]
	v_mfma_f32_16x16x32_bf16 v[30:33], v[164:167], v[204:207], v[30:33]
	v_mfma_f32_16x16x32_bf16 v[22:25], v[156:159], v[212:215], v[22:25]
	v_mfma_f32_16x16x32_bf16 v[14:17], v[164:167], v[212:215], v[14:17]
	s_setprio 0
	s_setprio 1
	v_mfma_f32_16x16x32_bf16 v[50:53], v[168:171], v[184:187], v[50:53]
	v_mfma_f32_16x16x32_bf16 v[42:45], v[176:179], v[184:187], v[42:45]
	v_mfma_f32_16x16x32_bf16 v[34:37], v[168:171], v[192:195], v[34:37]
	v_mfma_f32_16x16x32_bf16 v[26:29], v[176:179], v[192:195], v[26:29]
	v_mfma_f32_16x16x32_bf16 v[18:21], v[168:171], v[200:203], v[18:21]
	v_mfma_f32_16x16x32_bf16 v[10:13], v[176:179], v[200:203], v[10:13]
	v_mfma_f32_16x16x32_bf16 v[6:9], v[168:171], v[208:211], v[6:9]
	v_mfma_f32_16x16x32_bf16 v[2:5], v[176:179], v[208:211], v[2:5]
	v_mfma_f32_16x16x32_bf16 v[50:53], v[172:175], v[188:191], v[50:53]
	v_mfma_f32_16x16x32_bf16 v[42:45], v[180:183], v[188:191], v[42:45]
	v_mfma_f32_16x16x32_bf16 v[34:37], v[172:175], v[196:199], v[34:37]
	v_mfma_f32_16x16x32_bf16 v[26:29], v[180:183], v[196:199], v[26:29]
	v_mfma_f32_16x16x32_bf16 v[18:21], v[172:175], v[204:207], v[18:21]
	v_mfma_f32_16x16x32_bf16 v[10:13], v[180:183], v[204:207], v[10:13]
	v_mfma_f32_16x16x32_bf16 v[6:9], v[172:175], v[212:215], v[6:9]
	v_mfma_f32_16x16x32_bf16 v[2:5], v[180:183], v[212:215], v[2:5]
	s_setprio 0
	s_barrier
	s_add_i32 s51, s51, 2
	s_add_u32 s28, s28, 0x100
	s_addc_u32 s29, s29, 0
	s_add_u32 s49, s49, 0x100
	s_addc_u32 s50, s50, 0
	s_cmp_gt_u32 s51, 13
	s_cbranch_scc0 .LBB0_145
	s_and_b64 vcc, exec, s[16:17]
	s_cbranch_vccz .LBB0_148
	s_barrier

;     __device__ __forceinline__ bool next(int i, Unit& u) const { if (!S.next(i, u)) return false; if (u.pn >= 4) u.pn += 2; return true; }
; #define PG8_STAGE(bufoff, gbase, voff) do { _Pragma("unroll") for (int _i = 0; _i < 2; ++_i) \
;         __builtin_amdgcn_global_load_lds((const unsigned*)((const char*)(gbase) + (voff)[_i]), (PG8_LAS unsigned*)(lds + (bufoff) + ldsw + _i * 8192), 16, 0, 0); } while (0)
; #define PG8_LDA(dst, b, h) do { _Pragma("unroll") for (int m = 0; m < 4; ++m) _Pragma("unroll") for (int k = 0; k < 2; ++k) dst[m][k] = *(const PG8_LAS bf16x8*)(lds + PG8_SA(b, h) + aoff + m * 2048 + k * 1024); } while (0)
; template <class Epi, class Sched, bool ALIGN_EPI = false, bool SP2 = false>
; __device__ __forceinline__ void gemm_phase(PG8_LAS unsigned char* lds, const Gemm g, const Sched& S, const Epi& E) {
;     ...
;         const bool has_next = S.next(ui + 1, nxt);
;         if constexpr (Epi::LDS_PF) { if (has_next) E.prefetch(nxt, lds + STAGE_BYTES + ((ui + 1) % 3) * 4096, wid, lane); }
;         const char* nA = has_next ? (const char*)g.A + (size_t)nxt.pm * tstepA : cA; const char* nB = has_next ? (const char*)g.Bt + (size_t)nxt.pn * tstepB : cB;
;         for (int t = 0; t < nt; t += 2) {
;             const bool last = (t == nt - 2);
;             const char* a1 = cA + (size_t)(t + 1) * kstep;
;             const char* a2 = last ? nA : cA + (size_t)(t + 2) * kstep; const char* b2 = last ? nB : cB + (size_t)(t + 2) * kstep;
;             const char* a3 = a2 + kstep; const char* b3 = b2 + kstep;
;             if (last && has_next) S.a_ready(nxt);
;             if constexpr (SP2) {
;             PG8_LDB(B0, 0, 0); PG8_LDB(B1, 0, 1); PG8_SCHED; PG8_LDA(At, 0, 0); PG8_STAGE(PG8_SA(1, 1), a1 + hstepA, voffA);
;             PG8_WAIT_V(8); PG8_WAIT_L(0); PG8_BAR; PG8_MMA(0, 0, At, B0); PG8_MMA(0, 1, At, B1); PG8_BAR; PG8_SCHED;
;             PG8_LDA(At, 0, 1); PG8_STAGE(PG8_SB(0, 0), b2, voffB); PG8_STAGE(PG8_SB(0, 1), b2 + hstepB, voffB); PG8_STAGE(PG8_SA(0, 0), a2, voffA);
;     ...
; #pragma unroll
;         for (int a = 0; a < 2; ++a)
; #pragma unroll
;             for (int b = 0; b < 2; ++b)
; #pragma unroll
;                 for (int m = 0; m < 4; ++m)
; #pragma unroll
;                     for (int n = 0; n < 2; ++n) acc[a][b][m][n] = (f32x4){0.f, 0.f, 0.f, 0.f};
;         cur = nxt; cA = nA; cB = nB; ++ui;
.LBB0_610:
	s_ashr_i32 s21, s20, 31
	s_lshl_b64 s[0:1], s[20:21], 19
	v_readlane_b32 s22, v253, 29
	v_readlane_b32 s23, v253, 30
	s_add_u32 s22, s22, s0
	s_addc_u32 s23, s23, s1
	s_and_b64 s[0:1], s[6:7], exec
	s_cselect_b32 s5, s23, s29
	s_cselect_b32 s21, s22, s28
	s_ashr_i32 s19, s18, 31
	s_lshl_b64 s[0:1], s[18:19], 19
	v_readlane_b32 s24, v253, 16
	v_readlane_b32 s25, v253, 17
	s_add_u32 s24, s24, s0
	s_addc_u32 s25, s25, s1
	s_and_b64 s[0:1], s[6:7], exec
	s_cselect_b32 s19, s25, s31
	s_cselect_b32 s49, s24, s30
	s_add_u32 s28, s28, 0x40080
	s_addc_u32 s29, s29, 0
	s_add_u32 s50, s30, 0x100
	v_mov_b32_e32 v2, 0
	s_addc_u32 s51, s31, 0
	s_mov_b32 s67, -2
	v_mov_b32_e32 v3, v2
	v_mov_b32_e32 v4, v2
	v_mov_b32_e32 v5, v2
	v_mov_b32_e32 v6, v2
	v_mov_b32_e32 v7, v2
	v_mov_b32_e32 v8, v2
	v_mov_b32_e32 v9, v2
	v_mov_b32_e32 v14, v2
	v_mov_b32_e32 v15, v2
	v_mov_b32_e32 v16, v2
	v_mov_b32_e32 v17, v2
	v_mov_b32_e32 v22, v2
	v_mov_b32_e32 v23, v2
	v_mov_b32_e32 v24, v2
	v_mov_b32_e32 v25, v2
	s_waitcnt vmcnt(0)
	v_mov_b32_e32 v30, v2
	v_mov_b32_e32 v31, v2
	v_mov_b32_e32 v32, v2
	v_mov_b32_e32 v33, v2
	v_mov_b32_e32 v38, v2
	v_mov_b32_e32 v39, v2
	v_mov_b32_e32 v40, v2
	v_mov_b32_e32 v41, v2
	v_mov_b32_e32 v42, v2
	v_mov_b32_e32 v43, v2
	v_mov_b32_e32 v44, v2
	v_mov_b32_e32 v45, v2
	v_mov_b32_e32 v46, v2
	v_mov_b32_e32 v47, v2
	v_mov_b32_e32 v48, v2
	v_mov_b32_e32 v49, v2
	v_mov_b32_e32 v10, v2
	v_mov_b32_e32 v11, v2
	v_mov_b32_e32 v12, v2
	v_mov_b32_e32 v13, v2
	v_mov_b32_e32 v18, v2
	v_mov_b32_e32 v19, v2
	v_mov_b32_e32 v20, v2
	v_mov_b32_e32 v21, v2
	v_mov_b32_e32 v26, v2
	v_mov_b32_e32 v27, v2
	v_mov_b32_e32 v28, v2
	v_mov_b32_e32 v29, v2
	v_mov_b32_e32 v34, v2
	v_mov_b32_e32 v35, v2
	v_mov_b32_e32 v36, v2
	v_mov_b32_e32 v37, v2
	v_mov_b32_e32 v50, v2
	v_mov_b32_e32 v51, v2
	v_mov_b32_e32 v52, v2
	v_mov_b32_e32 v53, v2
	v_mov_b32_e32 v54, v2
	v_mov_b32_e32 v55, v2
	v_mov_b32_e32 v56, v2
	v_mov_b32_e32 v57, v2
	v_mov_b32_e32 v58, v2
	v_mov_b32_e32 v59, v2
	v_mov_b32_e32 v60, v2
	v_mov_b32_e32 v61, v2
	v_mov_b32_e32 v62, v2
	v_mov_b32_e32 v63, v2
	v_mov_b32_e32 v64, v2
	v_mov_b32_e32 v65, v2
	v_mov_b32_e32 v66, v2
	v_mov_b32_e32 v67, v2
	v_mov_b32_e32 v68, v2
	v_mov_b32_e32 v69, v2
	v_mov_b32_e32 v70, v2
	v_mov_b32_e32 v71, v2
	v_mov_b32_e32 v72, v2
	v_mov_b32_e32 v73, v2
	v_mov_b32_e32 v78, v2
	v_mov_b32_e32 v79, v2
	v_mov_b32_e32 v80, v2
	v_mov_b32_e32 v81, v2
	v_mov_b32_e32 v86, v2
	v_mov_b32_e32 v87, v2
	v_mov_b32_e32 v88, v2
	v_mov_b32_e32 v89, v2
	v_mov_b32_e32 v90, v2
	v_mov_b32_e32 v91, v2
	v_mov_b32_e32 v92, v2
	v_mov_b32_e32 v93, v2
	v_mov_b32_e32 v94, v2
	v_mov_b32_e32 v95, v2
	v_mov_b32_e32 v96, v2
	v_mov_b32_e32 v97, v2
	v_mov_b32_e32 v98, v2
	v_mov_b32_e32 v99, v2
	v_mov_b32_e32 v100, v2
	v_mov_b32_e32 v101, v2
	v_mov_b32_e32 v106, v2
	v_mov_b32_e32 v107, v2
	v_mov_b32_e32 v108, v2
	v_mov_b32_e32 v109, v2
	v_mov_b32_e32 v74, v2
	v_mov_b32_e32 v75, v2
	v_mov_b32_e32 v76, v2
	v_mov_b32_e32 v77, v2
	v_mov_b32_e32 v82, v2
	v_mov_b32_e32 v83, v2
	v_mov_b32_e32 v84, v2
	v_mov_b32_e32 v85, v2
	v_mov_b32_e32 v102, v2
	v_mov_b32_e32 v103, v2
	v_mov_b32_e32 v104, v2
	v_mov_b32_e32 v105, v2
	v_mov_b32_e32 v110, v2
	v_mov_b32_e32 v111, v2
	v_mov_b32_e32 v112, v2
	v_mov_b32_e32 v113, v2
	v_mov_b32_e32 v114, v2
	v_mov_b32_e32 v115, v2
	v_mov_b32_e32 v116, v2
	v_mov_b32_e32 v117, v2
	v_mov_b32_e32 v118, v2
	v_mov_b32_e32 v119, v2
	v_mov_b32_e32 v120, v2
	v_mov_b32_e32 v121, v2
	v_mov_b32_e32 v122, v2
	v_mov_b32_e32 v123, v2
	v_mov_b32_e32 v124, v2
	v_mov_b32_e32 v125, v2
	v_mov_b32_e32 v126, v2
	v_mov_b32_e32 v127, v2
	v_mov_b32_e32 v128, v2
	v_mov_b32_e32 v129, v2
.LBB0_611:
	ds_read_b128 v[130:133], v161
	ds_read_b128 v[134:137], v161 offset:1024
	ds_read_b128 v[154:157], v161 offset:2048
	ds_read_b128 v[166:169], v161 offset:3072
	ds_read_b128 v[170:173], v162
	ds_read_b128 v[174:177], v162 offset:1024
	ds_read_b128 v[178:181], v162 offset:2048
	ds_read_b128 v[182:185], v162 offset:3072
	s_add_u32 s0, s28, 0xfffc0080
	s_addc_u32 s1, s29, -1
	s_cmp_eq_u32 s67, 12
	s_cselect_b32 s35, s5, s1
	s_cselect_b32 s34, s21, s0
	s_cselect_b32 s31, s19, s51
	s_cselect_b32 s30, s49, s50
	v_lshl_add_u64 v[158:159], s[28:29], 0, v[146:147]
	s_add_i32 m0, s27, 0xc000
	ds_read_b128 v[186:189], v163
	ds_read_b128 v[190:193], v163 offset:1024
	ds_read_b128 v[194:197], v163 offset:2048
	ds_read_b128 v[198:201], v163 offset:3072
	ds_read_b128 v[202:205], v163 offset:4096
	ds_read_b128 v[206:209], v163 offset:5120
	ds_read_b128 v[210:213], v163 offset:6144
	ds_read_b128 v[214:217], v163 offset:7168
	global_load_lds_dwordx4 v[158:159], off
	v_lshl_add_u64 v[158:159], s[28:29], 0, v[148:149]
	s_add_i32 m0, s27, 0xe000
	s_nop 0
	global_load_lds_dwordx4 v[158:159], off
	s_waitcnt vmcnt(8)
	s_waitcnt lgkmcnt(0)
	s_setprio 1
	s_barrier
; #define PG8_STAGE(bufoff, gbase, voff) do { _Pragma("unroll") for (int _i = 0; _i < 2; ++_i) \
;         __builtin_amdgcn_global_load_lds((const unsigned*)((const char*)(gbase) + (voff)[_i]), (PG8_LAS unsigned*)(lds + (bufoff) + ldsw + _i * 8192), 16, 0, 0); } while (0)
; #define PG8_LDA(dst, b, h) do { _Pragma("unroll") for (int m = 0; m < 4; ++m) _Pragma("unroll") for (int k = 0; k < 2; ++k) dst[m][k] = *(const PG8_LAS bf16x8*)(lds + PG8_SA(b, h) + aoff + m * 2048 + k * 1024); } while (0)
; #define PG8_LDB(dst, b, h) do { _Pragma("unroll") for (int n = 0; n < 2; ++n) _Pragma("unroll") for (int k = 0; k < 2; ++k) dst[n][k] = *(const PG8_LAS bf16x8*)(lds + PG8_SB(b, h) + boff + n * 2048 + k * 1024); } while (0)
; #define PG8_MMA(ai, bj, At, Bt) do { __builtin_amdgcn_s_setprio(1); _Pragma("unroll") for (int m = 0; m < 4; ++m) _Pragma("unroll") for (int n = 0; n < 2; ++n) _Pragma("unroll") for (int k = 0; k < 2; ++k) \
;         acc[ai][bj][m][n] = __builtin_amdgcn_mfma_f32_16x16x32_bf16(Bt[n][k], At[m][k], acc[ai][bj][m][n], 0, 0, 0); __builtin_amdgcn_s_setprio(0); } while (0)
; #define PG8_WAIT_V(n) asm volatile("s_waitcnt vmcnt(" #n ")" ::: "memory")
; #define PG8_WAIT_L(n) asm volatile("s_waitcnt lgkmcnt(" #n ")" ::: "memory")
; #define PG8_BAR __builtin_amdgcn_s_barrier()
; #define PG8_SCHED __builtin_amdgcn_sched_barrier(0)
; template <class Epi, class Sched, bool ALIGN_EPI = false, bool SP2 = false>
; __device__ __forceinline__ void gemm_phase(PG8_LAS unsigned char* lds, const Gemm g, const Sched& S, const Epi& E) {
;     ...
;             PG8_LDB(B0, 0, 0); PG8_LDB(B1, 0, 1); PG8_SCHED; PG8_LDA(At, 0, 0); PG8_STAGE(PG8_SA(1, 1), a1 + hstepA, voffA);
;             PG8_WAIT_V(8); PG8_WAIT_L(0); PG8_BAR; PG8_MMA(0, 0, At, B0); PG8_MMA(0, 1, At, B1); PG8_BAR; PG8_SCHED;
;             PG8_LDA(At, 0, 1); PG8_STAGE(PG8_SB(0, 0), b2, voffB); PG8_STAGE(PG8_SB(0, 1), b2 + hstepB, voffB); PG8_STAGE(PG8_SA(0, 0), a2, voffA);
;             PG8_WAIT_V(8); PG8_WAIT_L(0); PG8_BAR; PG8_MMA(1, 0, At, B0); PG8_MMA(1, 1, At, B1); PG8_BAR; PG8_SCHED;
	v_mfma_f32_16x16x32_bf16 v[126:129], v[130:133], v[186:189], v[126:129]
	v_mfma_f32_16x16x32_bf16 v[122:125], v[154:157], v[186:189], v[122:125]
	v_mfma_f32_16x16x32_bf16 v[118:121], v[130:133], v[194:197], v[118:121]
	v_mfma_f32_16x16x32_bf16 v[114:117], v[154:157], v[194:197], v[114:117]
	v_mfma_f32_16x16x32_bf16 v[110:113], v[130:133], v[202:205], v[110:113]
	v_mfma_f32_16x16x32_bf16 v[102:105], v[154:157], v[202:205], v[102:105]
	v_mfma_f32_16x16x32_bf16 v[82:85], v[130:133], v[210:213], v[82:85]
	v_mfma_f32_16x16x32_bf16 v[74:77], v[154:157], v[210:213], v[74:77]
	v_mfma_f32_16x16x32_bf16 v[126:129], v[134:137], v[190:193], v[126:129]
	v_mfma_f32_16x16x32_bf16 v[122:125], v[166:169], v[190:193], v[122:125]
	v_mfma_f32_16x16x32_bf16 v[118:121], v[134:137], v[198:201], v[118:121]
	v_mfma_f32_16x16x32_bf16 v[114:117], v[166:169], v[198:201], v[114:117]
	v_mfma_f32_16x16x32_bf16 v[110:113], v[134:137], v[206:209], v[110:113]
	v_mfma_f32_16x16x32_bf16 v[102:105], v[166:169], v[206:209], v[102:105]
	v_mfma_f32_16x16x32_bf16 v[82:85], v[134:137], v[214:217], v[82:85]
	v_mfma_f32_16x16x32_bf16 v[74:77], v[166:169], v[214:217], v[74:77]
	s_setprio 0
	s_setprio 1
	v_mfma_f32_16x16x32_bf16 v[106:109], v[170:173], v[186:189], v[106:109]
	v_mfma_f32_16x16x32_bf16 v[98:101], v[178:181], v[186:189], v[98:101]
	v_mfma_f32_16x16x32_bf16 v[94:97], v[170:173], v[194:197], v[94:97]
	v_mfma_f32_16x16x32_bf16 v[90:93], v[178:181], v[194:197], v[90:93]
	v_mfma_f32_16x16x32_bf16 v[86:89], v[170:173], v[202:205], v[86:89]
	v_mfma_f32_16x16x32_bf16 v[78:81], v[178:181], v[202:205], v[78:81]
	v_mfma_f32_16x16x32_bf16 v[70:73], v[170:173], v[210:213], v[70:73]
	v_mfma_f32_16x16x32_bf16 v[66:69], v[178:181], v[210:213], v[66:69]
	v_mfma_f32_16x16x32_bf16 v[106:109], v[174:177], v[190:193], v[106:109]
	v_mfma_f32_16x16x32_bf16 v[98:101], v[182:185], v[190:193], v[98:101]
	v_mfma_f32_16x16x32_bf16 v[94:97], v[174:177], v[198:201], v[94:97]
	v_mfma_f32_16x16x32_bf16 v[90:93], v[182:185], v[198:201], v[90:93]
	v_mfma_f32_16x16x32_bf16 v[86:89], v[174:177], v[206:209], v[86:89]
	v_mfma_f32_16x16x32_bf16 v[78:81], v[182:185], v[206:209], v[78:81]
	v_mfma_f32_16x16x32_bf16 v[70:73], v[174:177], v[214:217], v[70:73]
	v_mfma_f32_16x16x32_bf16 v[66:69], v[182:185], v[214:217], v[66:69]
	s_setprio 0
	s_barrier
	s_add_i32 s0, s45, s17
	v_lshl_add_u64 v[158:159], s[30:31], 0, v[140:141]
	s_mov_b32 m0, s0
	ds_read_b128 v[186:189], v163 offset:16384
	ds_read_b128 v[190:193], v163 offset:17408
	ds_read_b128 v[194:197], v163 offset:18432
	ds_read_b128 v[198:201], v163 offset:19456
	ds_read_b128 v[202:205], v163 offset:20480
	ds_read_b128 v[206:209], v163 offset:21504
	ds_read_b128 v[210:213], v163 offset:22528
	ds_read_b128 v[214:217], v163 offset:23552
	global_load_lds_dwordx4 v[158:159], off
	s_add_i32 m0, s0, 0x2000
	s_add_u32 s0, s30, 0x40000
	v_lshl_add_u64 v[218:219], s[30:31], 0, v[144:145]
	s_addc_u32 s1, s31, 0
	s_add_i32 s2, s46, s17
	global_load_lds_dwordx4 v[218:219], off
	v_lshl_add_u64 v[220:221], s[0:1], 0, v[140:141]
	s_mov_b32 m0, s2
	v_lshl_add_u64 v[222:223], s[34:35], 0, v[142:143]
	global_load_lds_dwordx4 v[220:221], off
	v_lshl_add_u64 v[220:221], s[0:1], 0, v[144:145]
	s_add_i32 m0, s2, 0x2000
	s_nop 0
	global_load_lds_dwordx4 v[220:221], off
	v_lshl_add_u64 v[220:221], s[34:35], 0, v[138:139]
	s_mov_b32 m0, s27
	s_nop 0
	global_load_lds_dwordx4 v[220:221], off
	s_mov_b32 m0, s38
	s_nop 0
	global_load_lds_dwordx4 v[222:223], off
	s_waitcnt vmcnt(8)
	s_waitcnt lgkmcnt(0)
	s_setprio 1
	s_barrier
	v_mfma_f32_16x16x32_bf16 v[62:65], v[130:133], v[186:189], v[62:65]
	v_mfma_f32_16x16x32_bf16 v[58:61], v[154:157], v[186:189], v[58:61]
	v_mfma_f32_16x16x32_bf16 v[54:57], v[130:133], v[194:197], v[54:57]
	v_mfma_f32_16x16x32_bf16 v[50:53], v[154:157], v[194:197], v[50:53]
	v_mfma_f32_16x16x32_bf16 v[34:37], v[130:133], v[202:205], v[34:37]
	v_mfma_f32_16x16x32_bf16 v[26:29], v[154:157], v[202:205], v[26:29]
	v_mfma_f32_16x16x32_bf16 v[18:21], v[130:133], v[210:213], v[18:21]
	v_mfma_f32_16x16x32_bf16 v[10:13], v[154:157], v[210:213], v[10:13]
	v_mfma_f32_16x16x32_bf16 v[62:65], v[134:137], v[190:193], v[62:65]
	v_mfma_f32_16x16x32_bf16 v[58:61], v[166:169], v[190:193], v[58:61]
	v_mfma_f32_16x16x32_bf16 v[54:57], v[134:137], v[198:201], v[54:57]
	v_mfma_f32_16x16x32_bf16 v[50:53], v[166:169], v[198:201], v[50:53]
	v_mfma_f32_16x16x32_bf16 v[34:37], v[134:137], v[206:209], v[34:37]
	v_mfma_f32_16x16x32_bf16 v[26:29], v[166:169], v[206:209], v[26:29]
	v_mfma_f32_16x16x32_bf16 v[18:21], v[134:137], v[214:217], v[18:21]
	v_mfma_f32_16x16x32_bf16 v[10:13], v[166:169], v[214:217], v[10:13]
	s_setprio 0
	s_setprio 1
	v_mfma_f32_16x16x32_bf16 v[46:49], v[170:173], v[186:189], v[46:49]
	v_mfma_f32_16x16x32_bf16 v[42:45], v[178:181], v[186:189], v[42:45]
	v_mfma_f32_16x16x32_bf16 v[38:41], v[170:173], v[194:197], v[38:41]
	v_mfma_f32_16x16x32_bf16 v[30:33], v[178:181], v[194:197], v[30:33]
	v_mfma_f32_16x16x32_bf16 v[22:25], v[170:173], v[202:205], v[22:25]
	v_mfma_f32_16x16x32_bf16 v[14:17], v[178:181], v[202:205], v[14:17]
	v_mfma_f32_16x16x32_bf16 v[6:9], v[170:173], v[210:213], v[6:9]
	v_mfma_f32_16x16x32_bf16 v[2:5], v[178:181], v[210:213], v[2:5]
	v_mfma_f32_16x16x32_bf16 v[46:49], v[174:177], v[190:193], v[46:49]
	v_mfma_f32_16x16x32_bf16 v[42:45], v[182:185], v[190:193], v[42:45]
	v_mfma_f32_16x16x32_bf16 v[38:41], v[174:177], v[198:201], v[38:41]
	v_mfma_f32_16x16x32_bf16 v[30:33], v[182:185], v[198:201], v[30:33]
	v_mfma_f32_16x16x32_bf16 v[22:25], v[174:177], v[206:209], v[22:25]
	v_mfma_f32_16x16x32_bf16 v[14:17], v[182:185], v[206:209], v[14:17]
	v_mfma_f32_16x16x32_bf16 v[6:9], v[174:177], v[214:217], v[6:9]
	v_mfma_f32_16x16x32_bf16 v[2:5], v[182:185], v[214:217], v[2:5]
	s_setprio 0
	s_barrier
; #define PG8_STAGE(bufoff, gbase, voff) do { _Pragma("unroll") for (int _i = 0; _i < 2; ++_i) \
;         __builtin_amdgcn_global_load_lds((const unsigned*)((const char*)(gbase) + (voff)[_i]), (PG8_LAS unsigned*)(lds + (bufoff) + ldsw + _i * 8192), 16, 0, 0); } while (0)
; #define PG8_LDA(dst, b, h) do { _Pragma("unroll") for (int m = 0; m < 4; ++m) _Pragma("unroll") for (int k = 0; k < 2; ++k) dst[m][k] = *(const PG8_LAS bf16x8*)(lds + PG8_SA(b, h) + aoff + m * 2048 + k * 1024); } while (0)
; #define PG8_LDB(dst, b, h) do { _Pragma("unroll") for (int n = 0; n < 2; ++n) _Pragma("unroll") for (int k = 0; k < 2; ++k) dst[n][k] = *(const PG8_LAS bf16x8*)(lds + PG8_SB(b, h) + boff + n * 2048 + k * 1024); } while (0)
; #define PG8_MMA(ai, bj, At, Bt) do { __builtin_amdgcn_s_setprio(1); _Pragma("unroll") for (int m = 0; m < 4; ++m) _Pragma("unroll") for (int n = 0; n < 2; ++n) _Pragma("unroll") for (int k = 0; k < 2; ++k) \
;         acc[ai][bj][m][n] = __builtin_amdgcn_mfma_f32_16x16x32_bf16(Bt[n][k], At[m][k], acc[ai][bj][m][n], 0, 0, 0); __builtin_amdgcn_s_setprio(0); } while (0)
; #define PG8_WAIT_V(n) asm volatile("s_waitcnt vmcnt(" #n ")" ::: "memory")
; #define PG8_WAIT_L(n) asm volatile("s_waitcnt lgkmcnt(" #n ")" ::: "memory")
; #define PG8_BAR __builtin_amdgcn_s_barrier()
; #define PG8_SCHED __builtin_amdgcn_sched_barrier(0)
; template <class Epi, class Sched, bool ALIGN_EPI = false, bool SP2 = false>
; __device__ __forceinline__ void gemm_phase(PG8_LAS unsigned char* lds, const Gemm g, const Sched& S, const Epi& E) {
;     ...
;         for (int t = 0; t < nt; t += 2) {
;     ...
;             PG8_LDB(B0, 1, 0); PG8_LDB(B1, 1, 1); PG8_SCHED; PG8_LDA(At, 1, 0); PG8_STAGE(PG8_SA(0, 1), a2 + hstepA, voffA);
;             PG8_WAIT_V(8); PG8_WAIT_L(0); PG8_BAR; PG8_MMA(0, 0, At, B0); PG8_MMA(0, 1, At, B1); PG8_BAR; PG8_SCHED;
;             PG8_LDA(At, 1, 1); PG8_STAGE(PG8_SB(1, 0), b3, voffB); PG8_STAGE(PG8_SB(1, 1), b3 + hstepB, voffB); PG8_STAGE(PG8_SA(1, 0), a3, voffA);
;             PG8_WAIT_V(8); PG8_WAIT_L(0); PG8_BAR; PG8_MMA(1, 0, At, B0); PG8_MMA(1, 1, At, B1); PG8_BAR; PG8_SCHED;
;     ...
;         if constexpr (ALIGN_EPI) { if (wr == 0) PG8_BAR; }
	ds_read_b128 v[130:133], v164
	ds_read_b128 v[134:137], v164 offset:1024
	ds_read_b128 v[154:157], v164 offset:2048
	ds_read_b128 v[166:169], v164 offset:3072
	ds_read_b128 v[170:173], v165
	ds_read_b128 v[174:177], v165 offset:1024
	ds_read_b128 v[178:181], v165 offset:2048
	ds_read_b128 v[182:185], v165 offset:3072
	s_add_u32 s0, s34, 0x40000
	s_addc_u32 s1, s35, 0
	s_mov_b32 m0, s39
	v_lshl_add_u64 v[224:225], s[0:1], 0, v[138:139]
	ds_read_b128 v[186:189], v163 offset:32768
	ds_read_b128 v[190:193], v163 offset:33792
	ds_read_b128 v[194:197], v163 offset:34816
	ds_read_b128 v[198:201], v163 offset:35840
	ds_read_b128 v[202:205], v163 offset:36864
	ds_read_b128 v[206:209], v163 offset:37888
	ds_read_b128 v[210:213], v163 offset:38912
	ds_read_b128 v[214:217], v163 offset:39936
	global_load_lds_dwordx4 v[224:225], off
	v_lshl_add_u64 v[224:225], s[0:1], 0, v[142:143]
	s_mov_b32 m0, s40
	s_nop 0
	global_load_lds_dwordx4 v[224:225], off
	s_waitcnt vmcnt(8)
	s_waitcnt lgkmcnt(0)
	s_setprio 1
	s_barrier
	v_mfma_f32_16x16x32_bf16 v[126:129], v[130:133], v[186:189], v[126:129]
	v_mfma_f32_16x16x32_bf16 v[122:125], v[154:157], v[186:189], v[122:125]
	v_mfma_f32_16x16x32_bf16 v[118:121], v[130:133], v[194:197], v[118:121]
	v_mfma_f32_16x16x32_bf16 v[114:117], v[154:157], v[194:197], v[114:117]
	v_mfma_f32_16x16x32_bf16 v[110:113], v[130:133], v[202:205], v[110:113]
	v_mfma_f32_16x16x32_bf16 v[102:105], v[154:157], v[202:205], v[102:105]
	v_mfma_f32_16x16x32_bf16 v[82:85], v[130:133], v[210:213], v[82:85]
	v_mfma_f32_16x16x32_bf16 v[74:77], v[154:157], v[210:213], v[74:77]
	v_mfma_f32_16x16x32_bf16 v[126:129], v[134:137], v[190:193], v[126:129]
	v_mfma_f32_16x16x32_bf16 v[122:125], v[166:169], v[190:193], v[122:125]
	v_mfma_f32_16x16x32_bf16 v[118:121], v[134:137], v[198:201], v[118:121]
	v_mfma_f32_16x16x32_bf16 v[114:117], v[166:169], v[198:201], v[114:117]
	v_mfma_f32_16x16x32_bf16 v[110:113], v[134:137], v[206:209], v[110:113]
	v_mfma_f32_16x16x32_bf16 v[102:105], v[166:169], v[206:209], v[102:105]
	v_mfma_f32_16x16x32_bf16 v[82:85], v[134:137], v[214:217], v[82:85]
	v_mfma_f32_16x16x32_bf16 v[74:77], v[166:169], v[214:217], v[74:77]
	s_setprio 0
	s_setprio 1
	v_mfma_f32_16x16x32_bf16 v[106:109], v[170:173], v[186:189], v[106:109]
	v_mfma_f32_16x16x32_bf16 v[98:101], v[178:181], v[186:189], v[98:101]
	v_mfma_f32_16x16x32_bf16 v[94:97], v[170:173], v[194:197], v[94:97]
	v_mfma_f32_16x16x32_bf16 v[90:93], v[178:181], v[194:197], v[90:93]
	v_mfma_f32_16x16x32_bf16 v[86:89], v[170:173], v[202:205], v[86:89]
	v_mfma_f32_16x16x32_bf16 v[78:81], v[178:181], v[202:205], v[78:81]
	v_mfma_f32_16x16x32_bf16 v[70:73], v[170:173], v[210:213], v[70:73]
	v_mfma_f32_16x16x32_bf16 v[66:69], v[178:181], v[210:213], v[66:69]
	v_mfma_f32_16x16x32_bf16 v[106:109], v[174:177], v[190:193], v[106:109]
	v_mfma_f32_16x16x32_bf16 v[98:101], v[182:185], v[190:193], v[98:101]
	v_mfma_f32_16x16x32_bf16 v[94:97], v[174:177], v[198:201], v[94:97]
	v_mfma_f32_16x16x32_bf16 v[90:93], v[182:185], v[198:201], v[90:93]
	v_mfma_f32_16x16x32_bf16 v[86:89], v[174:177], v[206:209], v[86:89]
	v_mfma_f32_16x16x32_bf16 v[78:81], v[182:185], v[206:209], v[78:81]
	v_mfma_f32_16x16x32_bf16 v[70:73], v[174:177], v[214:217], v[70:73]
	v_mfma_f32_16x16x32_bf16 v[66:69], v[182:185], v[214:217], v[66:69]
	s_setprio 0
	s_barrier
	s_add_i32 s0, s47, s17
	v_lshl_add_u64 v[158:159], v[158:159], 0, s[8:9]
	s_mov_b32 m0, s0
	ds_read_b128 v[186:189], v163 offset:49152
	ds_read_b128 v[190:193], v163 offset:50176
	ds_read_b128 v[194:197], v163 offset:51200
	ds_read_b128 v[198:201], v163 offset:52224
	ds_read_b128 v[202:205], v163 offset:53248
	ds_read_b128 v[206:209], v163 offset:54272
	ds_read_b128 v[210:213], v163 offset:55296
	ds_read_b128 v[214:217], v163 offset:56320
	global_load_lds_dwordx4 v[158:159], off
	s_add_i32 m0, s0, 0x2000
	s_add_u32 s0, s30, 0x40080
	v_lshl_add_u64 v[158:159], v[218:219], 0, s[8:9]
	s_addc_u32 s1, s31, 0
	s_add_i32 s2, s48, s17
	global_load_lds_dwordx4 v[158:159], off
	v_lshl_add_u64 v[158:159], s[0:1], 0, v[140:141]
	s_mov_b32 m0, s2
	s_nop 0
	global_load_lds_dwordx4 v[158:159], off
	v_lshl_add_u64 v[158:159], s[0:1], 0, v[144:145]
	s_add_i32 m0, s2, 0x2000
	s_nop 0
	global_load_lds_dwordx4 v[158:159], off
	v_lshl_add_u64 v[158:159], v[220:221], 0, s[8:9]
	s_mov_b32 m0, s41
	s_nop 0
	global_load_lds_dwordx4 v[158:159], off
	v_lshl_add_u64 v[158:159], v[222:223], 0, s[8:9]
	s_mov_b32 m0, s42
	s_nop 0
	global_load_lds_dwordx4 v[158:159], off
	s_waitcnt vmcnt(8)
	s_waitcnt lgkmcnt(0)
	s_setprio 1
	s_barrier
	v_mfma_f32_16x16x32_bf16 v[62:65], v[130:133], v[186:189], v[62:65]
	v_mfma_f32_16x16x32_bf16 v[58:61], v[154:157], v[186:189], v[58:61]
	v_mfma_f32_16x16x32_bf16 v[54:57], v[130:133], v[194:197], v[54:57]
	v_mfma_f32_16x16x32_bf16 v[50:53], v[154:157], v[194:197], v[50:53]
	v_mfma_f32_16x16x32_bf16 v[34:37], v[130:133], v[202:205], v[34:37]
	v_mfma_f32_16x16x32_bf16 v[26:29], v[154:157], v[202:205], v[26:29]
	v_mfma_f32_16x16x32_bf16 v[18:21], v[130:133], v[210:213], v[18:21]
	v_mfma_f32_16x16x32_bf16 v[10:13], v[154:157], v[210:213], v[10:13]
	v_mfma_f32_16x16x32_bf16 v[62:65], v[134:137], v[190:193], v[62:65]
	v_mfma_f32_16x16x32_bf16 v[58:61], v[166:169], v[190:193], v[58:61]
	v_mfma_f32_16x16x32_bf16 v[54:57], v[134:137], v[198:201], v[54:57]
	v_mfma_f32_16x16x32_bf16 v[50:53], v[166:169], v[198:201], v[50:53]
	v_mfma_f32_16x16x32_bf16 v[34:37], v[134:137], v[206:209], v[34:37]
	v_mfma_f32_16x16x32_bf16 v[26:29], v[166:169], v[206:209], v[26:29]
	v_mfma_f32_16x16x32_bf16 v[18:21], v[134:137], v[214:217], v[18:21]
	v_mfma_f32_16x16x32_bf16 v[10:13], v[166:169], v[214:217], v[10:13]
	s_setprio 0
	s_setprio 1
	v_mfma_f32_16x16x32_bf16 v[46:49], v[170:173], v[186:189], v[46:49]
	v_mfma_f32_16x16x32_bf16 v[42:45], v[178:181], v[186:189], v[42:45]
	v_mfma_f32_16x16x32_bf16 v[38:41], v[170:173], v[194:197], v[38:41]
	v_mfma_f32_16x16x32_bf16 v[30:33], v[178:181], v[194:197], v[30:33]
	v_mfma_f32_16x16x32_bf16 v[22:25], v[170:173], v[202:205], v[22:25]
	v_mfma_f32_16x16x32_bf16 v[14:17], v[178:181], v[202:205], v[14:17]
	v_mfma_f32_16x16x32_bf16 v[6:9], v[170:173], v[210:213], v[6:9]
	v_mfma_f32_16x16x32_bf16 v[2:5], v[178:181], v[210:213], v[2:5]
	v_mfma_f32_16x16x32_bf16 v[46:49], v[174:177], v[190:193], v[46:49]
	v_mfma_f32_16x16x32_bf16 v[42:45], v[182:185], v[190:193], v[42:45]
	v_mfma_f32_16x16x32_bf16 v[38:41], v[174:177], v[198:201], v[38:41]
	v_mfma_f32_16x16x32_bf16 v[30:33], v[182:185], v[198:201], v[30:33]
	v_mfma_f32_16x16x32_bf16 v[22:25], v[174:177], v[206:209], v[22:25]
	v_mfma_f32_16x16x32_bf16 v[14:17], v[182:185], v[206:209], v[14:17]
	v_mfma_f32_16x16x32_bf16 v[6:9], v[174:177], v[214:217], v[6:9]
	v_mfma_f32_16x16x32_bf16 v[2:5], v[182:185], v[214:217], v[2:5]
	s_setprio 0
	s_barrier
	s_add_i32 s67, s67, 2
	s_add_u32 s28, s28, 0x100
	s_addc_u32 s29, s29, 0
	s_add_u32 s50, s50, 0x100
	s_addc_u32 s51, s51, 0
	s_cmp_gt_u32 s67, 13
	s_cbranch_scc0 .LBB0_611
	s_and_b64 vcc, exec, s[14:15]
	s_cbranch_vccz .LBB0_614
	s_barrier

;     __device__ __forceinline__ bool next(int i, Unit& u) const { if (!S.next(i, u)) return false; if (u.pn >= 4) u.pn += 2; return true; }
; #define PG8_STAGE(bufoff, gbase, voff) do { _Pragma("unroll") for (int _i = 0; _i < 2; ++_i) \
;         __builtin_amdgcn_global_load_lds((const unsigned*)((const char*)(gbase) + (voff)[_i]), (PG8_LAS unsigned*)(lds + (bufoff) + ldsw + _i * 8192), 16, 0, 0); } while (0)
; #define PG8_LDA(dst, b, h) do { _Pragma("unroll") for (int m = 0; m < 4; ++m) _Pragma("unroll") for (int k = 0; k < 2; ++k) dst[m][k] = *(const PG8_LAS bf16x8*)(lds + PG8_SA(b, h) + aoff + m * 2048 + k * 1024); } while (0)
; template <class Epi, class Sched, bool ALIGN_EPI = false, bool SP2 = false>
; __device__ __forceinline__ void gemm_phase(PG8_LAS unsigned char* lds, const Gemm g, const Sched& S, const Epi& E) {
;     ...
;         const bool has_next = S.next(ui + 1, nxt);
;         if constexpr (Epi::LDS_PF) { if (has_next) E.prefetch(nxt, lds + STAGE_BYTES + ((ui + 1) % 3) * 4096, wid, lane); }
;         const char* nA = has_next ? (const char*)g.A + (size_t)nxt.pm * tstepA : cA; const char* nB = has_next ? (const char*)g.Bt + (size_t)nxt.pn * tstepB : cB;
;         for (int t = 0; t < nt; t += 2) {
;             const bool last = (t == nt - 2);
;             const char* a1 = cA + (size_t)(t + 1) * kstep;
;             const char* a2 = last ? nA : cA + (size_t)(t + 2) * kstep; const char* b2 = last ? nB : cB + (size_t)(t + 2) * kstep;
;             const char* a3 = a2 + kstep; const char* b3 = b2 + kstep;
;             if (last && has_next) S.a_ready(nxt);
;             if constexpr (SP2) {
;             PG8_LDB(B0, 0, 0); PG8_LDB(B1, 0, 1); PG8_SCHED; PG8_LDA(At, 0, 0); PG8_STAGE(PG8_SA(1, 1), a1 + hstepA, voffA);
;             PG8_WAIT_V(8); PG8_WAIT_L(0); PG8_BAR; PG8_MMA(0, 0, At, B0); PG8_MMA(0, 1, At, B1); PG8_BAR; PG8_SCHED;
;             PG8_LDA(At, 0, 1); PG8_STAGE(PG8_SB(0, 0), b2, voffB); PG8_STAGE(PG8_SB(0, 1), b2 + hstepB, voffB); PG8_STAGE(PG8_SA(0, 0), a2, voffA);
;     ...
; #pragma unroll
;         for (int a = 0; a < 2; ++a)
; #pragma unroll
;             for (int b = 0; b < 2; ++b)
; #pragma unroll
;                 for (int m = 0; m < 4; ++m)
; #pragma unroll
;                     for (int n = 0; n < 2; ++n) acc[a][b][m][n] = (f32x4){0.f, 0.f, 0.f, 0.f};
;         cur = nxt; cA = nA; cB = nB; ++ui;
.LBB0_1106:
	s_ashr_i32 s47, s46, 31
	s_lshl_b64 s[0:1], s[46:47], 19
	v_readlane_b32 s18, v253, 31
	v_readlane_b32 s19, v253, 32
	s_add_u32 s66, s18, s0
	s_addc_u32 s67, s19, s1
	s_and_b64 s[0:1], s[12:13], exec
	s_cselect_b32 s5, s67, s73
	s_cselect_b32 s15, s66, s72
	s_add_u32 s18, s72, 0x100
	v_mov_b32_e32 v2, 0
	s_addc_u32 s19, s73, 0
	s_mov_b32 s20, -2
	v_mov_b32_e32 v3, v2
	v_mov_b32_e32 v4, v2
	v_mov_b32_e32 v5, v2
	v_mov_b32_e32 v6, v2
	v_mov_b32_e32 v7, v2
	v_mov_b32_e32 v8, v2
	v_mov_b32_e32 v9, v2
	v_mov_b32_e32 v22, v2
	v_mov_b32_e32 v23, v2
	v_mov_b32_e32 v24, v2
	v_mov_b32_e32 v25, v2
	v_mov_b32_e32 v38, v2
	v_mov_b32_e32 v39, v2
	v_mov_b32_e32 v40, v2
	v_mov_b32_e32 v41, v2
	v_mov_b32_e32 v46, v2
	v_mov_b32_e32 v47, v2
	v_mov_b32_e32 v48, v2
	v_mov_b32_e32 v49, v2
	v_mov_b32_e32 v54, v2
	v_mov_b32_e32 v55, v2
	v_mov_b32_e32 v56, v2
	v_mov_b32_e32 v57, v2
	v_mov_b32_e32 v58, v2
	v_mov_b32_e32 v59, v2
	v_mov_b32_e32 v60, v2
	v_mov_b32_e32 v61, v2
	v_mov_b32_e32 v62, v2
	v_mov_b32_e32 v63, v2
	v_mov_b32_e32 v64, v2
	v_mov_b32_e32 v65, v2
	v_mov_b32_e32 v10, v2
	v_mov_b32_e32 v11, v2
	v_mov_b32_e32 v12, v2
	v_mov_b32_e32 v13, v2
	v_mov_b32_e32 v26, v2
	v_mov_b32_e32 v27, v2
	v_mov_b32_e32 v28, v2
	v_mov_b32_e32 v29, v2
	v_mov_b32_e32 v14, v2
	v_mov_b32_e32 v15, v2
	v_mov_b32_e32 v16, v2
	v_mov_b32_e32 v17, v2
	v_mov_b32_e32 v30, v2
	v_mov_b32_e32 v31, v2
	v_mov_b32_e32 v32, v2
	v_mov_b32_e32 v33, v2
	v_mov_b32_e32 v18, v2
	v_mov_b32_e32 v19, v2
	v_mov_b32_e32 v20, v2
	v_mov_b32_e32 v21, v2
	v_mov_b32_e32 v34, v2
	v_mov_b32_e32 v35, v2
	v_mov_b32_e32 v36, v2
	v_mov_b32_e32 v37, v2
	v_mov_b32_e32 v42, v2
	v_mov_b32_e32 v43, v2
	v_mov_b32_e32 v44, v2
	v_mov_b32_e32 v45, v2
	v_mov_b32_e32 v50, v2
	v_mov_b32_e32 v51, v2
	v_mov_b32_e32 v52, v2
	v_mov_b32_e32 v53, v2
	v_mov_b32_e32 v66, v2
	v_mov_b32_e32 v67, v2
	v_mov_b32_e32 v68, v2
	v_mov_b32_e32 v69, v2
	v_mov_b32_e32 v70, v2
	v_mov_b32_e32 v71, v2
	v_mov_b32_e32 v72, v2
	v_mov_b32_e32 v73, v2
	v_mov_b32_e32 v86, v2
	v_mov_b32_e32 v87, v2
	v_mov_b32_e32 v88, v2
	v_mov_b32_e32 v89, v2
	v_mov_b32_e32 v102, v2
	v_mov_b32_e32 v103, v2
	v_mov_b32_e32 v104, v2
	v_mov_b32_e32 v105, v2
	v_mov_b32_e32 v110, v2
	v_mov_b32_e32 v111, v2
	v_mov_b32_e32 v112, v2
	v_mov_b32_e32 v113, v2
	v_mov_b32_e32 v118, v2
	v_mov_b32_e32 v119, v2
	v_mov_b32_e32 v120, v2
	v_mov_b32_e32 v121, v2
	v_mov_b32_e32 v122, v2
	v_mov_b32_e32 v123, v2
	v_mov_b32_e32 v124, v2
	v_mov_b32_e32 v125, v2
	v_mov_b32_e32 v158, v2
	v_mov_b32_e32 v159, v2
	v_mov_b32_e32 v160, v2
	v_mov_b32_e32 v161, v2
	v_mov_b32_e32 v74, v2
	v_mov_b32_e32 v75, v2
	v_mov_b32_e32 v76, v2
	v_mov_b32_e32 v77, v2
	v_mov_b32_e32 v90, v2
	v_mov_b32_e32 v91, v2
	v_mov_b32_e32 v92, v2
	v_mov_b32_e32 v93, v2
	v_mov_b32_e32 v78, v2
	v_mov_b32_e32 v79, v2
	v_mov_b32_e32 v80, v2
	v_mov_b32_e32 v81, v2
	v_mov_b32_e32 v94, v2
	v_mov_b32_e32 v95, v2
	v_mov_b32_e32 v96, v2
	v_mov_b32_e32 v97, v2
	v_mov_b32_e32 v82, v2
	v_mov_b32_e32 v83, v2
	v_mov_b32_e32 v84, v2
	v_mov_b32_e32 v85, v2
	v_mov_b32_e32 v98, v2
	v_mov_b32_e32 v99, v2
	v_mov_b32_e32 v100, v2
	v_mov_b32_e32 v101, v2
	v_mov_b32_e32 v106, v2
	v_mov_b32_e32 v107, v2
	v_mov_b32_e32 v108, v2
	v_mov_b32_e32 v109, v2
	v_mov_b32_e32 v114, v2
	v_mov_b32_e32 v115, v2
	v_mov_b32_e32 v116, v2
	v_mov_b32_e32 v117, v2
.LBB0_1107:
	ds_read_b128 v[126:129], v205
	ds_read_b128 v[130:133], v205 offset:1024
	ds_read_b128 v[134:137], v205 offset:2048
	ds_read_b128 v[138:141], v205 offset:3072
	ds_read_b128 v[142:145], v206
	ds_read_b128 v[146:149], v206 offset:1024
	ds_read_b128 v[150:153], v206 offset:2048
	ds_read_b128 v[154:157], v206 offset:3072
	s_add_u32 s12, s70, 0x100
	s_addc_u32 s13, s71, 0
	s_cmp_eq_u32 s20, 12
	s_cselect_b32 s79, s51, s13
	s_cselect_b32 s78, s50, s12
	s_cselect_b32 s73, s5, s19
	s_cselect_b32 s72, s15, s18
	v_lshl_add_u64 v[226:227], s[70:71], 0, v[192:193]
	s_add_i32 m0, s80, 0xc000
	ds_read_b128 v[162:165], v207
	ds_read_b128 v[166:169], v207 offset:1024
	ds_read_b128 v[170:173], v207 offset:2048
	ds_read_b128 v[174:177], v207 offset:3072
	ds_read_b128 v[210:213], v207 offset:4096
	ds_read_b128 v[214:217], v207 offset:5120
	ds_read_b128 v[218:221], v207 offset:6144
	ds_read_b128 v[222:225], v207 offset:7168
	global_load_lds_dwordx4 v[226:227], off
	v_lshl_add_u64 v[226:227], s[70:71], 0, v[194:195]
	s_add_i32 m0, s80, 0xe000
	s_nop 0
	global_load_lds_dwordx4 v[226:227], off
	s_waitcnt vmcnt(8)
	s_waitcnt lgkmcnt(0)
	s_setprio 1
	s_barrier
	v_mfma_f32_16x16x32_bf16 v[114:117], v[126:129], v[162:165], v[114:117]
	v_mfma_f32_16x16x32_bf16 v[106:109], v[134:137], v[162:165], v[106:109]
	v_mfma_f32_16x16x32_bf16 v[98:101], v[126:129], v[170:173], v[98:101]
	v_mfma_f32_16x16x32_bf16 v[82:85], v[134:137], v[170:173], v[82:85]
	v_mfma_f32_16x16x32_bf16 v[94:97], v[126:129], v[210:213], v[94:97]
	v_mfma_f32_16x16x32_bf16 v[78:81], v[134:137], v[210:213], v[78:81]
	v_mfma_f32_16x16x32_bf16 v[90:93], v[126:129], v[218:221], v[90:93]
	v_mfma_f32_16x16x32_bf16 v[74:77], v[134:137], v[218:221], v[74:77]
	v_mfma_f32_16x16x32_bf16 v[114:117], v[130:133], v[166:169], v[114:117]
	v_mfma_f32_16x16x32_bf16 v[106:109], v[138:141], v[166:169], v[106:109]
	v_mfma_f32_16x16x32_bf16 v[98:101], v[130:133], v[174:177], v[98:101]
	v_mfma_f32_16x16x32_bf16 v[82:85], v[138:141], v[174:177], v[82:85]
	v_mfma_f32_16x16x32_bf16 v[94:97], v[130:133], v[214:217], v[94:97]
	v_mfma_f32_16x16x32_bf16 v[78:81], v[138:141], v[214:217], v[78:81]
	v_mfma_f32_16x16x32_bf16 v[90:93], v[130:133], v[222:225], v[90:93]
	v_mfma_f32_16x16x32_bf16 v[74:77], v[138:141], v[222:225], v[74:77]
	s_setprio 0
	s_setprio 1
	v_mfma_f32_16x16x32_bf16 v[158:161], v[142:145], v[162:165], v[158:161]
	v_mfma_f32_16x16x32_bf16 v[122:125], v[150:153], v[162:165], v[122:125]
	v_mfma_f32_16x16x32_bf16 v[118:121], v[142:145], v[170:173], v[118:121]
	v_mfma_f32_16x16x32_bf16 v[110:113], v[150:153], v[170:173], v[110:113]
	v_mfma_f32_16x16x32_bf16 v[102:105], v[142:145], v[210:213], v[102:105]
	v_mfma_f32_16x16x32_bf16 v[86:89], v[150:153], v[210:213], v[86:89]
	v_mfma_f32_16x16x32_bf16 v[70:73], v[142:145], v[218:221], v[70:73]
	v_mfma_f32_16x16x32_bf16 v[66:69], v[150:153], v[218:221], v[66:69]
	v_mfma_f32_16x16x32_bf16 v[158:161], v[146:149], v[166:169], v[158:161]
	v_mfma_f32_16x16x32_bf16 v[122:125], v[154:157], v[166:169], v[122:125]
	v_mfma_f32_16x16x32_bf16 v[118:121], v[146:149], v[174:177], v[118:121]
	v_mfma_f32_16x16x32_bf16 v[110:113], v[154:157], v[174:177], v[110:113]
	v_mfma_f32_16x16x32_bf16 v[102:105], v[146:149], v[214:217], v[102:105]
	v_mfma_f32_16x16x32_bf16 v[86:89], v[154:157], v[214:217], v[86:89]
	v_mfma_f32_16x16x32_bf16 v[70:73], v[146:149], v[222:225], v[70:73]
	v_mfma_f32_16x16x32_bf16 v[66:69], v[154:157], v[222:225], v[66:69]
	s_setprio 0
	s_barrier
; #define PG8_STAGE(bufoff, gbase, voff) do { _Pragma("unroll") for (int _i = 0; _i < 2; ++_i) \
;         __builtin_amdgcn_global_load_lds((const unsigned*)((const char*)(gbase) + (voff)[_i]), (PG8_LAS unsigned*)(lds + (bufoff) + ldsw + _i * 8192), 16, 0, 0); } while (0)
; #define PG8_LDA(dst, b, h) do { _Pragma("unroll") for (int m = 0; m < 4; ++m) _Pragma("unroll") for (int k = 0; k < 2; ++k) dst[m][k] = *(const PG8_LAS bf16x8*)(lds + PG8_SA(b, h) + aoff + m * 2048 + k * 1024); } while (0)
; #define PG8_LDB(dst, b, h) do { _Pragma("unroll") for (int n = 0; n < 2; ++n) _Pragma("unroll") for (int k = 0; k < 2; ++k) dst[n][k] = *(const PG8_LAS bf16x8*)(lds + PG8_SB(b, h) + boff + n * 2048 + k * 1024); } while (0)
; #define PG8_MMA(ai, bj, At, Bt) do { __builtin_amdgcn_s_setprio(1); _Pragma("unroll") for (int m = 0; m < 4; ++m) _Pragma("unroll") for (int n = 0; n < 2; ++n) _Pragma("unroll") for (int k = 0; k < 2; ++k) \
;         acc[ai][bj][m][n] = __builtin_amdgcn_mfma_f32_16x16x32_bf16(Bt[n][k], At[m][k], acc[ai][bj][m][n], 0, 0, 0); __builtin_amdgcn_s_setprio(0); } while (0)
; #define PG8_WAIT_V(n) asm volatile("s_waitcnt vmcnt(" #n ")" ::: "memory")
; #define PG8_WAIT_L(n) asm volatile("s_waitcnt lgkmcnt(" #n ")" ::: "memory")
; #define PG8_BAR __builtin_amdgcn_s_barrier()
; #define PG8_SCHED __builtin_amdgcn_sched_barrier(0)
; template <class Epi, class Sched, bool ALIGN_EPI = false, bool SP2 = false>
; __device__ __forceinline__ void gemm_phase(PG8_LAS unsigned char* lds, const Gemm g, const Sched& S, const Epi& E) {
;     ...
;             PG8_LDA(At, 0, 1); PG8_STAGE(PG8_SB(0, 0), b2, voffB); PG8_STAGE(PG8_SB(0, 1), b2 + hstepB, voffB); PG8_STAGE(PG8_SA(0, 0), a2, voffA);
;             PG8_WAIT_V(8); PG8_WAIT_L(0); PG8_BAR; PG8_MMA(1, 0, At, B0); PG8_MMA(1, 1, At, B1); PG8_BAR; PG8_SCHED;
;             PG8_LDB(B0, 1, 0); PG8_LDB(B1, 1, 1); PG8_SCHED; PG8_LDA(At, 1, 0); PG8_STAGE(PG8_SA(0, 1), a2 + hstepA, voffA);
	s_add_i32 s0, s88, s69
	v_lshl_add_u64 v[226:227], s[72:73], 0, v[180:181]
	s_mov_b32 m0, s0
	ds_read_b128 v[162:165], v207 offset:16384
	ds_read_b128 v[166:169], v207 offset:17408
	ds_read_b128 v[170:173], v207 offset:18432
	ds_read_b128 v[174:177], v207 offset:19456
	ds_read_b128 v[210:213], v207 offset:20480
	ds_read_b128 v[214:217], v207 offset:21504
	ds_read_b128 v[218:221], v207 offset:22528
	ds_read_b128 v[222:225], v207 offset:23552
	global_load_lds_dwordx4 v[226:227], off
	s_add_i32 m0, s0, 0x2000
	s_add_u32 s0, s72, 0x40000
	v_lshl_add_u64 v[228:229], s[72:73], 0, v[184:185]
	s_addc_u32 s1, s73, 0
	s_add_i32 s2, s89, s69
	global_load_lds_dwordx4 v[228:229], off
	v_lshl_add_u64 v[230:231], s[0:1], 0, v[180:181]
	s_mov_b32 m0, s2
	v_lshl_add_u64 v[232:233], s[78:79], 0, v[182:183]
	global_load_lds_dwordx4 v[230:231], off
	v_lshl_add_u64 v[230:231], s[0:1], 0, v[184:185]
	s_add_i32 m0, s2, 0x2000
	s_nop 0
	global_load_lds_dwordx4 v[230:231], off
	v_lshl_add_u64 v[230:231], s[78:79], 0, v[178:179]
	s_mov_b32 m0, s80
	s_nop 0
	global_load_lds_dwordx4 v[230:231], off
	s_mov_b32 m0, s81
	s_nop 0
	global_load_lds_dwordx4 v[232:233], off
	s_waitcnt vmcnt(8)
	s_waitcnt lgkmcnt(0)
	s_setprio 1
	s_barrier
	v_mfma_f32_16x16x32_bf16 v[50:53], v[126:129], v[162:165], v[50:53]
	v_mfma_f32_16x16x32_bf16 v[42:45], v[134:137], v[162:165], v[42:45]
	v_mfma_f32_16x16x32_bf16 v[34:37], v[126:129], v[170:173], v[34:37]
	v_mfma_f32_16x16x32_bf16 v[18:21], v[134:137], v[170:173], v[18:21]
	v_mfma_f32_16x16x32_bf16 v[30:33], v[126:129], v[210:213], v[30:33]
	v_mfma_f32_16x16x32_bf16 v[14:17], v[134:137], v[210:213], v[14:17]
	v_mfma_f32_16x16x32_bf16 v[26:29], v[126:129], v[218:221], v[26:29]
	v_mfma_f32_16x16x32_bf16 v[10:13], v[134:137], v[218:221], v[10:13]
	v_mfma_f32_16x16x32_bf16 v[50:53], v[130:133], v[166:169], v[50:53]
	v_mfma_f32_16x16x32_bf16 v[42:45], v[138:141], v[166:169], v[42:45]
	v_mfma_f32_16x16x32_bf16 v[34:37], v[130:133], v[174:177], v[34:37]
	v_mfma_f32_16x16x32_bf16 v[18:21], v[138:141], v[174:177], v[18:21]
	v_mfma_f32_16x16x32_bf16 v[30:33], v[130:133], v[214:217], v[30:33]
	v_mfma_f32_16x16x32_bf16 v[14:17], v[138:141], v[214:217], v[14:17]
	v_mfma_f32_16x16x32_bf16 v[26:29], v[130:133], v[222:225], v[26:29]
	v_mfma_f32_16x16x32_bf16 v[10:13], v[138:141], v[222:225], v[10:13]
	s_setprio 0
	s_setprio 1
	v_mfma_f32_16x16x32_bf16 v[62:65], v[142:145], v[162:165], v[62:65]
	v_mfma_f32_16x16x32_bf16 v[58:61], v[150:153], v[162:165], v[58:61]
	v_mfma_f32_16x16x32_bf16 v[54:57], v[142:145], v[170:173], v[54:57]
	v_mfma_f32_16x16x32_bf16 v[46:49], v[150:153], v[170:173], v[46:49]
	v_mfma_f32_16x16x32_bf16 v[38:41], v[142:145], v[210:213], v[38:41]
	v_mfma_f32_16x16x32_bf16 v[22:25], v[150:153], v[210:213], v[22:25]
	v_mfma_f32_16x16x32_bf16 v[6:9], v[142:145], v[218:221], v[6:9]
	v_mfma_f32_16x16x32_bf16 v[2:5], v[150:153], v[218:221], v[2:5]
	v_mfma_f32_16x16x32_bf16 v[62:65], v[146:149], v[166:169], v[62:65]
	v_mfma_f32_16x16x32_bf16 v[58:61], v[154:157], v[166:169], v[58:61]
	v_mfma_f32_16x16x32_bf16 v[54:57], v[146:149], v[174:177], v[54:57]
	v_mfma_f32_16x16x32_bf16 v[46:49], v[154:157], v[174:177], v[46:49]
	v_mfma_f32_16x16x32_bf16 v[38:41], v[146:149], v[214:217], v[38:41]
	v_mfma_f32_16x16x32_bf16 v[22:25], v[154:157], v[214:217], v[22:25]
	v_mfma_f32_16x16x32_bf16 v[6:9], v[146:149], v[222:225], v[6:9]
	v_mfma_f32_16x16x32_bf16 v[2:5], v[154:157], v[222:225], v[2:5]
	s_setprio 0
	s_barrier
	ds_read_b128 v[126:129], v208
	ds_read_b128 v[130:133], v208 offset:1024
	ds_read_b128 v[134:137], v208 offset:2048
	ds_read_b128 v[138:141], v208 offset:3072
	ds_read_b128 v[142:145], v209
	ds_read_b128 v[146:149], v209 offset:1024
	ds_read_b128 v[150:153], v209 offset:2048
	ds_read_b128 v[154:157], v209 offset:3072
	s_add_u32 s0, s78, 0x40000
	s_addc_u32 s1, s79, 0
	s_mov_b32 m0, s82
	v_lshl_add_u64 v[234:235], s[0:1], 0, v[178:179]
	ds_read_b128 v[162:165], v207 offset:32768
	ds_read_b128 v[166:169], v207 offset:33792
	ds_read_b128 v[170:173], v207 offset:34816
	ds_read_b128 v[174:177], v207 offset:35840
	ds_read_b128 v[210:213], v207 offset:36864
	ds_read_b128 v[214:217], v207 offset:37888
	ds_read_b128 v[218:221], v207 offset:38912
	ds_read_b128 v[222:225], v207 offset:39936
	global_load_lds_dwordx4 v[234:235], off
	v_lshl_add_u64 v[234:235], s[0:1], 0, v[182:183]
	s_mov_b32 m0, s83
	s_nop 0
	global_load_lds_dwordx4 v[234:235], off
	s_waitcnt vmcnt(8)
	s_waitcnt lgkmcnt(0)
	s_setprio 1
	s_barrier
; #define PG8_STAGE(bufoff, gbase, voff) do { _Pragma("unroll") for (int _i = 0; _i < 2; ++_i) \
;         __builtin_amdgcn_global_load_lds((const unsigned*)((const char*)(gbase) + (voff)[_i]), (PG8_LAS unsigned*)(lds + (bufoff) + ldsw + _i * 8192), 16, 0, 0); } while (0)
; #define PG8_LDA(dst, b, h) do { _Pragma("unroll") for (int m = 0; m < 4; ++m) _Pragma("unroll") for (int k = 0; k < 2; ++k) dst[m][k] = *(const PG8_LAS bf16x8*)(lds + PG8_SA(b, h) + aoff + m * 2048 + k * 1024); } while (0)
; #define PG8_MMA(ai, bj, At, Bt) do { __builtin_amdgcn_s_setprio(1); _Pragma("unroll") for (int m = 0; m < 4; ++m) _Pragma("unroll") for (int n = 0; n < 2; ++n) _Pragma("unroll") for (int k = 0; k < 2; ++k) \
;         acc[ai][bj][m][n] = __builtin_amdgcn_mfma_f32_16x16x32_bf16(Bt[n][k], At[m][k], acc[ai][bj][m][n], 0, 0, 0); __builtin_amdgcn_s_setprio(0); } while (0)
; #define PG8_WAIT_V(n) asm volatile("s_waitcnt vmcnt(" #n ")" ::: "memory")
; #define PG8_WAIT_L(n) asm volatile("s_waitcnt lgkmcnt(" #n ")" ::: "memory")
; #define PG8_BAR __builtin_amdgcn_s_barrier()
; #define PG8_SCHED __builtin_amdgcn_sched_barrier(0)
; template <class Epi, class Sched, bool ALIGN_EPI = false, bool SP2 = false>
; __device__ __forceinline__ void gemm_phase(PG8_LAS unsigned char* lds, const Gemm g, const Sched& S, const Epi& E) {
;     ...
;         for (int t = 0; t < nt; t += 2) {
;     ...
;             PG8_WAIT_V(8); PG8_WAIT_L(0); PG8_BAR; PG8_MMA(0, 0, At, B0); PG8_MMA(0, 1, At, B1); PG8_BAR; PG8_SCHED;
;             PG8_LDA(At, 1, 1); PG8_STAGE(PG8_SB(1, 0), b3, voffB); PG8_STAGE(PG8_SB(1, 1), b3 + hstepB, voffB); PG8_STAGE(PG8_SA(1, 0), a3, voffA);
;             PG8_WAIT_V(8); PG8_WAIT_L(0); PG8_BAR; PG8_MMA(1, 0, At, B0); PG8_MMA(1, 1, At, B1); PG8_BAR; PG8_SCHED;
;     ...
;         if constexpr (ALIGN_EPI) { if (wr == 0) PG8_BAR; }
	v_mfma_f32_16x16x32_bf16 v[114:117], v[126:129], v[162:165], v[114:117]
	v_mfma_f32_16x16x32_bf16 v[106:109], v[134:137], v[162:165], v[106:109]
	v_mfma_f32_16x16x32_bf16 v[98:101], v[126:129], v[170:173], v[98:101]
	v_mfma_f32_16x16x32_bf16 v[82:85], v[134:137], v[170:173], v[82:85]
	v_mfma_f32_16x16x32_bf16 v[94:97], v[126:129], v[210:213], v[94:97]
	v_mfma_f32_16x16x32_bf16 v[78:81], v[134:137], v[210:213], v[78:81]
	v_mfma_f32_16x16x32_bf16 v[90:93], v[126:129], v[218:221], v[90:93]
	v_mfma_f32_16x16x32_bf16 v[74:77], v[134:137], v[218:221], v[74:77]
	v_mfma_f32_16x16x32_bf16 v[114:117], v[130:133], v[166:169], v[114:117]
	v_mfma_f32_16x16x32_bf16 v[106:109], v[138:141], v[166:169], v[106:109]
	v_mfma_f32_16x16x32_bf16 v[98:101], v[130:133], v[174:177], v[98:101]
	v_mfma_f32_16x16x32_bf16 v[82:85], v[138:141], v[174:177], v[82:85]
	v_mfma_f32_16x16x32_bf16 v[94:97], v[130:133], v[214:217], v[94:97]
	v_mfma_f32_16x16x32_bf16 v[78:81], v[138:141], v[214:217], v[78:81]
	v_mfma_f32_16x16x32_bf16 v[90:93], v[130:133], v[222:225], v[90:93]
	v_mfma_f32_16x16x32_bf16 v[74:77], v[138:141], v[222:225], v[74:77]
	s_setprio 0
	s_setprio 1
	v_mfma_f32_16x16x32_bf16 v[158:161], v[142:145], v[162:165], v[158:161]
	v_mfma_f32_16x16x32_bf16 v[122:125], v[150:153], v[162:165], v[122:125]
	v_mfma_f32_16x16x32_bf16 v[118:121], v[142:145], v[170:173], v[118:121]
	v_mfma_f32_16x16x32_bf16 v[110:113], v[150:153], v[170:173], v[110:113]
	v_mfma_f32_16x16x32_bf16 v[102:105], v[142:145], v[210:213], v[102:105]
	v_mfma_f32_16x16x32_bf16 v[86:89], v[150:153], v[210:213], v[86:89]
	v_mfma_f32_16x16x32_bf16 v[70:73], v[142:145], v[218:221], v[70:73]
	v_mfma_f32_16x16x32_bf16 v[66:69], v[150:153], v[218:221], v[66:69]
	v_mfma_f32_16x16x32_bf16 v[158:161], v[146:149], v[166:169], v[158:161]
	v_mfma_f32_16x16x32_bf16 v[122:125], v[154:157], v[166:169], v[122:125]
	v_mfma_f32_16x16x32_bf16 v[118:121], v[146:149], v[174:177], v[118:121]
	v_mfma_f32_16x16x32_bf16 v[110:113], v[154:157], v[174:177], v[110:113]
	v_mfma_f32_16x16x32_bf16 v[102:105], v[146:149], v[214:217], v[102:105]
	v_mfma_f32_16x16x32_bf16 v[86:89], v[154:157], v[214:217], v[86:89]
	v_mfma_f32_16x16x32_bf16 v[70:73], v[146:149], v[222:225], v[70:73]
	v_mfma_f32_16x16x32_bf16 v[66:69], v[154:157], v[222:225], v[66:69]
	s_setprio 0
	s_barrier
	s_add_i32 s0, s90, s69
	v_lshl_add_u64 v[226:227], v[226:227], 0, s[38:39]
	s_mov_b32 m0, s0
	ds_read_b128 v[162:165], v207 offset:49152
	ds_read_b128 v[166:169], v207 offset:50176
	ds_read_b128 v[170:173], v207 offset:51200
	ds_read_b128 v[174:177], v207 offset:52224
	ds_read_b128 v[210:213], v207 offset:53248
	ds_read_b128 v[214:217], v207 offset:54272
	ds_read_b128 v[218:221], v207 offset:55296
	ds_read_b128 v[222:225], v207 offset:56320
	global_load_lds_dwordx4 v[226:227], off
	s_add_i32 m0, s0, 0x2000
	s_add_u32 s0, s72, 0x40080
	v_lshl_add_u64 v[226:227], v[228:229], 0, s[38:39]
	s_addc_u32 s1, s73, 0
	s_add_i32 s2, s91, s69
	global_load_lds_dwordx4 v[226:227], off
	v_lshl_add_u64 v[226:227], s[0:1], 0, v[180:181]
	s_mov_b32 m0, s2
	s_nop 0
	global_load_lds_dwordx4 v[226:227], off
	v_lshl_add_u64 v[226:227], s[0:1], 0, v[184:185]
	s_add_i32 m0, s2, 0x2000
	s_nop 0
	global_load_lds_dwordx4 v[226:227], off
	v_lshl_add_u64 v[226:227], v[230:231], 0, s[38:39]
	s_mov_b32 m0, s84
	s_nop 0
	global_load_lds_dwordx4 v[226:227], off
	v_lshl_add_u64 v[226:227], v[232:233], 0, s[38:39]
	s_mov_b32 m0, s85
	s_nop 0
	global_load_lds_dwordx4 v[226:227], off
	s_waitcnt vmcnt(8)
	s_waitcnt lgkmcnt(0)
	s_setprio 1
	s_barrier
	v_mfma_f32_16x16x32_bf16 v[50:53], v[126:129], v[162:165], v[50:53]
	v_mfma_f32_16x16x32_bf16 v[42:45], v[134:137], v[162:165], v[42:45]
	v_mfma_f32_16x16x32_bf16 v[34:37], v[126:129], v[170:173], v[34:37]
	v_mfma_f32_16x16x32_bf16 v[18:21], v[134:137], v[170:173], v[18:21]
	v_mfma_f32_16x16x32_bf16 v[30:33], v[126:129], v[210:213], v[30:33]
	v_mfma_f32_16x16x32_bf16 v[14:17], v[134:137], v[210:213], v[14:17]
	v_mfma_f32_16x16x32_bf16 v[26:29], v[126:129], v[218:221], v[26:29]
	v_mfma_f32_16x16x32_bf16 v[10:13], v[134:137], v[218:221], v[10:13]
	v_mfma_f32_16x16x32_bf16 v[50:53], v[130:133], v[166:169], v[50:53]
	v_mfma_f32_16x16x32_bf16 v[42:45], v[138:141], v[166:169], v[42:45]
	v_mfma_f32_16x16x32_bf16 v[34:37], v[130:133], v[174:177], v[34:37]
	v_mfma_f32_16x16x32_bf16 v[18:21], v[138:141], v[174:177], v[18:21]
	v_mfma_f32_16x16x32_bf16 v[30:33], v[130:133], v[214:217], v[30:33]
	v_mfma_f32_16x16x32_bf16 v[14:17], v[138:141], v[214:217], v[14:17]
	v_mfma_f32_16x16x32_bf16 v[26:29], v[130:133], v[222:225], v[26:29]
	v_mfma_f32_16x16x32_bf16 v[10:13], v[138:141], v[222:225], v[10:13]
	s_setprio 0
	s_setprio 1
	v_mfma_f32_16x16x32_bf16 v[62:65], v[142:145], v[162:165], v[62:65]
	v_mfma_f32_16x16x32_bf16 v[58:61], v[150:153], v[162:165], v[58:61]
	v_mfma_f32_16x16x32_bf16 v[54:57], v[142:145], v[170:173], v[54:57]
	v_mfma_f32_16x16x32_bf16 v[46:49], v[150:153], v[170:173], v[46:49]
	v_mfma_f32_16x16x32_bf16 v[38:41], v[142:145], v[210:213], v[38:41]
	v_mfma_f32_16x16x32_bf16 v[22:25], v[150:153], v[210:213], v[22:25]
	v_mfma_f32_16x16x32_bf16 v[6:9], v[142:145], v[218:221], v[6:9]
	v_mfma_f32_16x16x32_bf16 v[2:5], v[150:153], v[218:221], v[2:5]
	v_mfma_f32_16x16x32_bf16 v[62:65], v[146:149], v[166:169], v[62:65]
	v_mfma_f32_16x16x32_bf16 v[58:61], v[154:157], v[166:169], v[58:61]
	v_mfma_f32_16x16x32_bf16 v[54:57], v[146:149], v[174:177], v[54:57]
	v_mfma_f32_16x16x32_bf16 v[46:49], v[154:157], v[174:177], v[46:49]
	v_mfma_f32_16x16x32_bf16 v[38:41], v[146:149], v[214:217], v[38:41]
	v_mfma_f32_16x16x32_bf16 v[22:25], v[154:157], v[214:217], v[22:25]
	v_mfma_f32_16x16x32_bf16 v[6:9], v[146:149], v[222:225], v[6:9]
	v_mfma_f32_16x16x32_bf16 v[2:5], v[154:157], v[222:225], v[2:5]
	s_setprio 0
	s_barrier
	s_add_i32 s20, s20, 2
	s_add_u32 s18, s18, 0x100
	s_addc_u32 s19, s19, 0
	s_cmp_gt_u32 s20, 13
	s_mov_b64 s[70:71], s[12:13]
	s_cbranch_scc0 .LBB0_1107
	s_and_b64 vcc, exec, s[42:43]
	s_cbranch_vccz .LBB0_1110
	s_barrier

;     __device__ __forceinline__ bool next(int i, Unit& u) const { if (!S.next(i, u)) return false; if (u.pn >= 4) u.pn += 2; return true; }
; #define PG8_STAGE(bufoff, gbase, voff) do { _Pragma("unroll") for (int _i = 0; _i < 2; ++_i) \
;         __builtin_amdgcn_global_load_lds((const unsigned*)((const char*)(gbase) + (voff)[_i]), (PG8_LAS unsigned*)(lds + (bufoff) + ldsw + _i * 8192), 16, 0, 0); } while (0)
; #define PG8_LDA(dst, b, h) do { _Pragma("unroll") for (int m = 0; m < 4; ++m) _Pragma("unroll") for (int k = 0; k < 2; ++k) dst[m][k] = *(const PG8_LAS bf16x8*)(lds + PG8_SA(b, h) + aoff + m * 2048 + k * 1024); } while (0)
; template <class Epi, class Sched, bool ALIGN_EPI = false, bool SP2 = false>
; __device__ __forceinline__ void gemm_phase(PG8_LAS unsigned char* lds, const Gemm g, const Sched& S, const Epi& E) {
;     ...
;         const bool has_next = S.next(ui + 1, nxt);
;         if constexpr (Epi::LDS_PF) { if (has_next) E.prefetch(nxt, lds + STAGE_BYTES + ((ui + 1) % 3) * 4096, wid, lane); }
;         const char* nA = has_next ? (const char*)g.A + (size_t)nxt.pm * tstepA : cA; const char* nB = has_next ? (const char*)g.Bt + (size_t)nxt.pn * tstepB : cB;
;         for (int t = 0; t < nt; t += 2) {
;             const bool last = (t == nt - 2);
;             const char* a1 = cA + (size_t)(t + 1) * kstep;
;             const char* a2 = last ? nA : cA + (size_t)(t + 2) * kstep; const char* b2 = last ? nB : cB + (size_t)(t + 2) * kstep;
;             const char* a3 = a2 + kstep; const char* b3 = b2 + kstep;
;             if (last && has_next) S.a_ready(nxt);
;             if constexpr (SP2) {
;             PG8_LDB(B0, 0, 0); PG8_LDB(B1, 0, 1); PG8_SCHED; PG8_LDA(At, 0, 0); PG8_STAGE(PG8_SA(1, 1), a1 + hstepA, voffA);
;             PG8_WAIT_V(8); PG8_WAIT_L(0); PG8_BAR; PG8_MMA(0, 0, At, B0); PG8_MMA(0, 1, At, B1); PG8_BAR; PG8_SCHED;
;             PG8_LDA(At, 0, 1); PG8_STAGE(PG8_SB(0, 0), b2, voffB); PG8_STAGE(PG8_SB(0, 1), b2 + hstepB, voffB); PG8_STAGE(PG8_SA(0, 0), a2, voffA);
;     ...
; #pragma unroll
;         for (int a = 0; a < 2; ++a)
; #pragma unroll
;             for (int b = 0; b < 2; ++b)
; #pragma unroll
;                 for (int m = 0; m < 4; ++m)
; #pragma unroll
;                     for (int n = 0; n < 2; ++n) acc[a][b][m][n] = (f32x4){0.f, 0.f, 0.f, 0.f};
;         cur = nxt; cA = nA; cB = nB; ++ui;
.LBB0_1197:
	s_add_u32 s4, s70, 0x100
	v_mov_b32_e32 v2, 0
	s_addc_u32 s5, s71, 0
	s_mov_b32 s7, -2
	v_mov_b32_e32 v3, v2
	v_mov_b32_e32 v4, v2
	v_mov_b32_e32 v5, v2
	v_mov_b32_e32 v6, v2
	v_mov_b32_e32 v7, v2
	v_mov_b32_e32 v8, v2
	v_mov_b32_e32 v9, v2
	v_mov_b32_e32 v18, v2
	v_mov_b32_e32 v19, v2
	v_mov_b32_e32 v20, v2
	v_mov_b32_e32 v21, v2
	v_mov_b32_e32 v22, v2
	v_mov_b32_e32 v23, v2
	v_mov_b32_e32 v24, v2
	v_mov_b32_e32 v25, v2
	v_mov_b32_e32 v34, v2
	v_mov_b32_e32 v35, v2
	v_mov_b32_e32 v36, v2
	v_mov_b32_e32 v37, v2
	v_mov_b32_e32 v38, v2
	v_mov_b32_e32 v39, v2
	v_mov_b32_e32 v40, v2
	v_mov_b32_e32 v41, v2
	v_mov_b32_e32 v50, v2
	v_mov_b32_e32 v51, v2
	v_mov_b32_e32 v52, v2
	v_mov_b32_e32 v53, v2
	v_mov_b32_e32 v54, v2
	v_mov_b32_e32 v55, v2
	v_mov_b32_e32 v56, v2
	v_mov_b32_e32 v57, v2
	v_mov_b32_e32 v10, v2
	v_mov_b32_e32 v11, v2
	v_mov_b32_e32 v12, v2
	v_mov_b32_e32 v13, v2
	v_mov_b32_e32 v14, v2
	v_mov_b32_e32 v15, v2
	v_mov_b32_e32 v16, v2
	v_mov_b32_e32 v17, v2
	v_mov_b32_e32 v26, v2
	v_mov_b32_e32 v27, v2
	v_mov_b32_e32 v28, v2
	v_mov_b32_e32 v29, v2
	v_mov_b32_e32 v30, v2
	v_mov_b32_e32 v31, v2
	v_mov_b32_e32 v32, v2
	v_mov_b32_e32 v33, v2
	v_mov_b32_e32 v42, v2
	v_mov_b32_e32 v43, v2
	v_mov_b32_e32 v44, v2
	v_mov_b32_e32 v45, v2
	v_mov_b32_e32 v46, v2
	v_mov_b32_e32 v47, v2
	v_mov_b32_e32 v48, v2
	v_mov_b32_e32 v49, v2
	v_mov_b32_e32 v58, v2
	v_mov_b32_e32 v59, v2
	v_mov_b32_e32 v60, v2
	v_mov_b32_e32 v61, v2
	v_mov_b32_e32 v62, v2
	v_mov_b32_e32 v63, v2
	v_mov_b32_e32 v64, v2
	v_mov_b32_e32 v65, v2
	v_mov_b32_e32 v66, v2
	v_mov_b32_e32 v67, v2
	v_mov_b32_e32 v68, v2
	v_mov_b32_e32 v69, v2
	v_mov_b32_e32 v70, v2
	v_mov_b32_e32 v71, v2
	v_mov_b32_e32 v72, v2
	v_mov_b32_e32 v73, v2
	v_mov_b32_e32 v82, v2
	v_mov_b32_e32 v83, v2
	v_mov_b32_e32 v84, v2
	v_mov_b32_e32 v85, v2
	v_mov_b32_e32 v86, v2
	v_mov_b32_e32 v87, v2
	v_mov_b32_e32 v88, v2
	v_mov_b32_e32 v89, v2
	v_mov_b32_e32 v98, v2
	v_mov_b32_e32 v99, v2
	v_mov_b32_e32 v100, v2
	v_mov_b32_e32 v101, v2
	v_mov_b32_e32 v102, v2
	v_mov_b32_e32 v103, v2
	v_mov_b32_e32 v104, v2
	v_mov_b32_e32 v105, v2
	v_mov_b32_e32 v114, v2
	v_mov_b32_e32 v115, v2
	v_mov_b32_e32 v116, v2
	v_mov_b32_e32 v117, v2
	v_mov_b32_e32 v118, v2
	v_mov_b32_e32 v119, v2
	v_mov_b32_e32 v120, v2
	v_mov_b32_e32 v121, v2
	v_mov_b32_e32 v74, v2
	v_mov_b32_e32 v75, v2
	v_mov_b32_e32 v76, v2
	v_mov_b32_e32 v77, v2
	v_mov_b32_e32 v78, v2
	v_mov_b32_e32 v79, v2
	v_mov_b32_e32 v80, v2
	v_mov_b32_e32 v81, v2
	v_mov_b32_e32 v90, v2
	v_mov_b32_e32 v91, v2
	v_mov_b32_e32 v92, v2
	v_mov_b32_e32 v93, v2
	v_mov_b32_e32 v94, v2
	v_mov_b32_e32 v95, v2
	v_mov_b32_e32 v96, v2
	v_mov_b32_e32 v97, v2
	v_mov_b32_e32 v106, v2
	v_mov_b32_e32 v107, v2
	v_mov_b32_e32 v108, v2
	v_mov_b32_e32 v109, v2
	v_mov_b32_e32 v110, v2
	v_mov_b32_e32 v111, v2
	v_mov_b32_e32 v112, v2
	v_mov_b32_e32 v113, v2
	v_mov_b32_e32 v122, v2
	v_mov_b32_e32 v123, v2
	v_mov_b32_e32 v124, v2
	v_mov_b32_e32 v125, v2
	v_mov_b32_e32 v126, v2
	v_mov_b32_e32 v127, v2
	v_mov_b32_e32 v128, v2
	v_mov_b32_e32 v129, v2
.LBB0_1198:
	ds_read_b128 v[130:133], v207
	ds_read_b128 v[134:137], v207 offset:1024
	ds_read_b128 v[138:141], v207 offset:2048
	ds_read_b128 v[142:145], v207 offset:3072
	ds_read_b128 v[146:149], v208
	ds_read_b128 v[150:153], v208 offset:1024
	ds_read_b128 v[154:157], v208 offset:2048
	ds_read_b128 v[158:161], v208 offset:3072
	s_add_u32 s70, s68, 0x100
	s_addc_u32 s71, s69, 0
	s_cmp_eq_u32 s7, 40
	s_cselect_b32 s77, s13, s71
	s_cselect_b32 s76, s12, s70
	s_cselect_b32 s73, s51, s5
	s_cselect_b32 s72, s50, s4
	v_lshl_add_u64 v[188:189], s[68:69], 0, v[176:177]
	s_add_i32 m0, s78, 0xc000
	ds_read_b128 v[184:187], v209
	ds_read_b128 v[212:215], v209 offset:1024
	ds_read_b128 v[216:219], v209 offset:2048
	ds_read_b128 v[220:223], v209 offset:3072
	ds_read_b128 v[224:227], v209 offset:4096
	ds_read_b128 v[228:231], v209 offset:5120
	ds_read_b128 v[232:235], v209 offset:6144
	ds_read_b128 v[236:239], v209 offset:7168
	global_load_lds_dwordx4 v[188:189], off
	v_lshl_add_u64 v[188:189], s[68:69], 0, v[178:179]
	s_add_i32 m0, s78, 0xe000
	s_nop 0
	global_load_lds_dwordx4 v[188:189], off
	s_waitcnt vmcnt(8)
	s_waitcnt lgkmcnt(0)
	s_setprio 1
	s_barrier
	v_mfma_f32_16x16x32_bf16 v[126:129], v[130:133], v[184:187], v[126:129]
	v_mfma_f32_16x16x32_bf16 v[122:125], v[138:141], v[184:187], v[122:125]
	v_mfma_f32_16x16x32_bf16 v[110:113], v[130:133], v[216:219], v[110:113]
	v_mfma_f32_16x16x32_bf16 v[106:109], v[138:141], v[216:219], v[106:109]
	v_mfma_f32_16x16x32_bf16 v[94:97], v[130:133], v[224:227], v[94:97]
	v_mfma_f32_16x16x32_bf16 v[90:93], v[138:141], v[224:227], v[90:93]
	v_mfma_f32_16x16x32_bf16 v[78:81], v[130:133], v[232:235], v[78:81]
	v_mfma_f32_16x16x32_bf16 v[74:77], v[138:141], v[232:235], v[74:77]
	v_mfma_f32_16x16x32_bf16 v[126:129], v[134:137], v[212:215], v[126:129]
	v_mfma_f32_16x16x32_bf16 v[122:125], v[142:145], v[212:215], v[122:125]
	v_mfma_f32_16x16x32_bf16 v[110:113], v[134:137], v[220:223], v[110:113]
	v_mfma_f32_16x16x32_bf16 v[106:109], v[142:145], v[220:223], v[106:109]
	v_mfma_f32_16x16x32_bf16 v[94:97], v[134:137], v[228:231], v[94:97]
	v_mfma_f32_16x16x32_bf16 v[90:93], v[142:145], v[228:231], v[90:93]
	v_mfma_f32_16x16x32_bf16 v[78:81], v[134:137], v[236:239], v[78:81]
	v_mfma_f32_16x16x32_bf16 v[74:77], v[142:145], v[236:239], v[74:77]
	s_setprio 0
	s_setprio 1
	v_mfma_f32_16x16x32_bf16 v[118:121], v[146:149], v[184:187], v[118:121]
	v_mfma_f32_16x16x32_bf16 v[114:117], v[154:157], v[184:187], v[114:117]
	v_mfma_f32_16x16x32_bf16 v[102:105], v[146:149], v[216:219], v[102:105]
	v_mfma_f32_16x16x32_bf16 v[98:101], v[154:157], v[216:219], v[98:101]
	v_mfma_f32_16x16x32_bf16 v[86:89], v[146:149], v[224:227], v[86:89]
	v_mfma_f32_16x16x32_bf16 v[82:85], v[154:157], v[224:227], v[82:85]
	v_mfma_f32_16x16x32_bf16 v[70:73], v[146:149], v[232:235], v[70:73]
	v_mfma_f32_16x16x32_bf16 v[66:69], v[154:157], v[232:235], v[66:69]
	v_mfma_f32_16x16x32_bf16 v[118:121], v[150:153], v[212:215], v[118:121]
	v_mfma_f32_16x16x32_bf16 v[114:117], v[158:161], v[212:215], v[114:117]
	v_mfma_f32_16x16x32_bf16 v[102:105], v[150:153], v[220:223], v[102:105]
	v_mfma_f32_16x16x32_bf16 v[98:101], v[158:161], v[220:223], v[98:101]
	v_mfma_f32_16x16x32_bf16 v[86:89], v[150:153], v[228:231], v[86:89]
	v_mfma_f32_16x16x32_bf16 v[82:85], v[158:161], v[228:231], v[82:85]
	v_mfma_f32_16x16x32_bf16 v[70:73], v[150:153], v[236:239], v[70:73]
	v_mfma_f32_16x16x32_bf16 v[66:69], v[158:161], v[236:239], v[66:69]
	s_setprio 0
	s_barrier
; #define PG8_STAGE(bufoff, gbase, voff) do { _Pragma("unroll") for (int _i = 0; _i < 2; ++_i) \
;         __builtin_amdgcn_global_load_lds((const unsigned*)((const char*)(gbase) + (voff)[_i]), (PG8_LAS unsigned*)(lds + (bufoff) + ldsw + _i * 8192), 16, 0, 0); } while (0)
; #define PG8_LDA(dst, b, h) do { _Pragma("unroll") for (int m = 0; m < 4; ++m) _Pragma("unroll") for (int k = 0; k < 2; ++k) dst[m][k] = *(const PG8_LAS bf16x8*)(lds + PG8_SA(b, h) + aoff + m * 2048 + k * 1024); } while (0)
; #define PG8_LDB(dst, b, h) do { _Pragma("unroll") for (int n = 0; n < 2; ++n) _Pragma("unroll") for (int k = 0; k < 2; ++k) dst[n][k] = *(const PG8_LAS bf16x8*)(lds + PG8_SB(b, h) + boff + n * 2048 + k * 1024); } while (0)
; #define PG8_MMA(ai, bj, At, Bt) do { __builtin_amdgcn_s_setprio(1); _Pragma("unroll") for (int m = 0; m < 4; ++m) _Pragma("unroll") for (int n = 0; n < 2; ++n) _Pragma("unroll") for (int k = 0; k < 2; ++k) \
;         acc[ai][bj][m][n] = __builtin_amdgcn_mfma_f32_16x16x32_bf16(Bt[n][k], At[m][k], acc[ai][bj][m][n], 0, 0, 0); __builtin_amdgcn_s_setprio(0); } while (0)
; #define PG8_WAIT_V(n) asm volatile("s_waitcnt vmcnt(" #n ")" ::: "memory")
; #define PG8_WAIT_L(n) asm volatile("s_waitcnt lgkmcnt(" #n ")" ::: "memory")
; #define PG8_BAR __builtin_amdgcn_s_barrier()
; #define PG8_SCHED __builtin_amdgcn_sched_barrier(0)
; template <class Epi, class Sched, bool ALIGN_EPI = false, bool SP2 = false>
; __device__ __forceinline__ void gemm_phase(PG8_LAS unsigned char* lds, const Gemm g, const Sched& S, const Epi& E) {
;     ...
;             PG8_LDA(At, 0, 1); PG8_STAGE(PG8_SB(0, 0), b2, voffB); PG8_STAGE(PG8_SB(0, 1), b2 + hstepB, voffB); PG8_STAGE(PG8_SA(0, 0), a2, voffA);
;             PG8_WAIT_V(8); PG8_WAIT_L(0); PG8_BAR; PG8_MMA(1, 0, At, B0); PG8_MMA(1, 1, At, B1); PG8_BAR; PG8_SCHED;
;             PG8_LDB(B0, 1, 0); PG8_LDB(B1, 1, 1); PG8_SCHED; PG8_LDA(At, 1, 0); PG8_STAGE(PG8_SA(0, 1), a2 + hstepA, voffA);
	s_add_i32 s0, s85, s67
	v_lshl_add_u64 v[188:189], s[72:73], 0, v[162:163]
	s_mov_b32 m0, s0
	ds_read_b128 v[184:187], v209 offset:16384
	ds_read_b128 v[212:215], v209 offset:17408
	ds_read_b128 v[216:219], v209 offset:18432
	ds_read_b128 v[220:223], v209 offset:19456
	ds_read_b128 v[224:227], v209 offset:20480
	ds_read_b128 v[228:231], v209 offset:21504
	ds_read_b128 v[232:235], v209 offset:22528
	ds_read_b128 v[236:239], v209 offset:23552
	global_load_lds_dwordx4 v[188:189], off
	s_add_i32 m0, s0, 0x2000
	s_add_u32 s0, s72, 0xb0000
	v_lshl_add_u64 v[240:241], s[72:73], 0, v[168:169]
	s_addc_u32 s1, s73, 0
	s_add_i32 s2, s86, s67
	global_load_lds_dwordx4 v[240:241], off
	v_lshl_add_u64 v[242:243], s[0:1], 0, v[162:163]
	s_mov_b32 m0, s2
	v_lshl_add_u64 v[244:245], s[76:77], 0, v[166:167]
	global_load_lds_dwordx4 v[242:243], off
	v_lshl_add_u64 v[242:243], s[0:1], 0, v[168:169]
	s_add_i32 m0, s2, 0x2000
	s_nop 0
	global_load_lds_dwordx4 v[242:243], off
	v_lshl_add_u64 v[242:243], s[76:77], 0, v[164:165]
	s_mov_b32 m0, s78
	s_nop 0
	global_load_lds_dwordx4 v[242:243], off
	s_mov_b32 m0, s79
	s_nop 0
	global_load_lds_dwordx4 v[244:245], off
	s_waitcnt vmcnt(8)
	s_waitcnt lgkmcnt(0)
	s_setprio 1
	s_barrier
	v_mfma_f32_16x16x32_bf16 v[62:65], v[130:133], v[184:187], v[62:65]
	v_mfma_f32_16x16x32_bf16 v[58:61], v[138:141], v[184:187], v[58:61]
	v_mfma_f32_16x16x32_bf16 v[46:49], v[130:133], v[216:219], v[46:49]
	v_mfma_f32_16x16x32_bf16 v[42:45], v[138:141], v[216:219], v[42:45]
	v_mfma_f32_16x16x32_bf16 v[30:33], v[130:133], v[224:227], v[30:33]
	v_mfma_f32_16x16x32_bf16 v[26:29], v[138:141], v[224:227], v[26:29]
	v_mfma_f32_16x16x32_bf16 v[14:17], v[130:133], v[232:235], v[14:17]
	v_mfma_f32_16x16x32_bf16 v[10:13], v[138:141], v[232:235], v[10:13]
	v_mfma_f32_16x16x32_bf16 v[62:65], v[134:137], v[212:215], v[62:65]
	v_mfma_f32_16x16x32_bf16 v[58:61], v[142:145], v[212:215], v[58:61]
	v_mfma_f32_16x16x32_bf16 v[46:49], v[134:137], v[220:223], v[46:49]
	v_mfma_f32_16x16x32_bf16 v[42:45], v[142:145], v[220:223], v[42:45]
	v_mfma_f32_16x16x32_bf16 v[30:33], v[134:137], v[228:231], v[30:33]
	v_mfma_f32_16x16x32_bf16 v[26:29], v[142:145], v[228:231], v[26:29]
	v_mfma_f32_16x16x32_bf16 v[14:17], v[134:137], v[236:239], v[14:17]
	v_mfma_f32_16x16x32_bf16 v[10:13], v[142:145], v[236:239], v[10:13]
	s_setprio 0
	s_setprio 1
	v_mfma_f32_16x16x32_bf16 v[54:57], v[146:149], v[184:187], v[54:57]
	v_mfma_f32_16x16x32_bf16 v[50:53], v[154:157], v[184:187], v[50:53]
	v_mfma_f32_16x16x32_bf16 v[38:41], v[146:149], v[216:219], v[38:41]
	v_mfma_f32_16x16x32_bf16 v[34:37], v[154:157], v[216:219], v[34:37]
	v_mfma_f32_16x16x32_bf16 v[22:25], v[146:149], v[224:227], v[22:25]
	v_mfma_f32_16x16x32_bf16 v[18:21], v[154:157], v[224:227], v[18:21]
	v_mfma_f32_16x16x32_bf16 v[6:9], v[146:149], v[232:235], v[6:9]
	v_mfma_f32_16x16x32_bf16 v[2:5], v[154:157], v[232:235], v[2:5]
	v_mfma_f32_16x16x32_bf16 v[54:57], v[150:153], v[212:215], v[54:57]
	v_mfma_f32_16x16x32_bf16 v[50:53], v[158:161], v[212:215], v[50:53]
	v_mfma_f32_16x16x32_bf16 v[38:41], v[150:153], v[220:223], v[38:41]
	v_mfma_f32_16x16x32_bf16 v[34:37], v[158:161], v[220:223], v[34:37]
	v_mfma_f32_16x16x32_bf16 v[22:25], v[150:153], v[228:231], v[22:25]
	v_mfma_f32_16x16x32_bf16 v[18:21], v[158:161], v[228:231], v[18:21]
	v_mfma_f32_16x16x32_bf16 v[6:9], v[150:153], v[236:239], v[6:9]
	v_mfma_f32_16x16x32_bf16 v[2:5], v[158:161], v[236:239], v[2:5]
	s_setprio 0
	s_barrier
	ds_read_b128 v[130:133], v210
	ds_read_b128 v[134:137], v210 offset:1024
	ds_read_b128 v[138:141], v210 offset:2048
	ds_read_b128 v[142:145], v210 offset:3072
	ds_read_b128 v[146:149], v211
	ds_read_b128 v[150:153], v211 offset:1024
	ds_read_b128 v[154:157], v211 offset:2048
	ds_read_b128 v[158:161], v211 offset:3072
	s_add_u32 s0, s76, 0xb0000
	s_addc_u32 s1, s77, 0
	s_mov_b32 m0, s80
	v_lshl_add_u64 v[246:247], s[0:1], 0, v[164:165]
	ds_read_b128 v[184:187], v209 offset:32768
	ds_read_b128 v[212:215], v209 offset:33792
	ds_read_b128 v[216:219], v209 offset:34816
	ds_read_b128 v[220:223], v209 offset:35840
	ds_read_b128 v[224:227], v209 offset:36864
	ds_read_b128 v[228:231], v209 offset:37888
	ds_read_b128 v[232:235], v209 offset:38912
	ds_read_b128 v[236:239], v209 offset:39936
	global_load_lds_dwordx4 v[246:247], off
	v_lshl_add_u64 v[246:247], s[0:1], 0, v[166:167]
	s_mov_b32 m0, s81
	s_nop 0
	global_load_lds_dwordx4 v[246:247], off
	s_waitcnt vmcnt(8)
	s_waitcnt lgkmcnt(0)
	s_setprio 1
	s_barrier
; #define PG8_STAGE(bufoff, gbase, voff) do { _Pragma("unroll") for (int _i = 0; _i < 2; ++_i) \
;         __builtin_amdgcn_global_load_lds((const unsigned*)((const char*)(gbase) + (voff)[_i]), (PG8_LAS unsigned*)(lds + (bufoff) + ldsw + _i * 8192), 16, 0, 0); } while (0)
; #define PG8_LDA(dst, b, h) do { _Pragma("unroll") for (int m = 0; m < 4; ++m) _Pragma("unroll") for (int k = 0; k < 2; ++k) dst[m][k] = *(const PG8_LAS bf16x8*)(lds + PG8_SA(b, h) + aoff + m * 2048 + k * 1024); } while (0)
; #define PG8_MMA(ai, bj, At, Bt) do { __builtin_amdgcn_s_setprio(1); _Pragma("unroll") for (int m = 0; m < 4; ++m) _Pragma("unroll") for (int n = 0; n < 2; ++n) _Pragma("unroll") for (int k = 0; k < 2; ++k) \
;         acc[ai][bj][m][n] = __builtin_amdgcn_mfma_f32_16x16x32_bf16(Bt[n][k], At[m][k], acc[ai][bj][m][n], 0, 0, 0); __builtin_amdgcn_s_setprio(0); } while (0)
; #define PG8_WAIT_V(n) asm volatile("s_waitcnt vmcnt(" #n ")" ::: "memory")
; #define PG8_WAIT_L(n) asm volatile("s_waitcnt lgkmcnt(" #n ")" ::: "memory")
; #define PG8_BAR __builtin_amdgcn_s_barrier()
; #define PG8_SCHED __builtin_amdgcn_sched_barrier(0)
; template <class Epi, class Sched, bool ALIGN_EPI = false, bool SP2 = false>
; __device__ __forceinline__ void gemm_phase(PG8_LAS unsigned char* lds, const Gemm g, const Sched& S, const Epi& E) {
;     ...
;         for (int t = 0; t < nt; t += 2) {
;     ...
;             PG8_WAIT_V(8); PG8_WAIT_L(0); PG8_BAR; PG8_MMA(0, 0, At, B0); PG8_MMA(0, 1, At, B1); PG8_BAR; PG8_SCHED;
;             PG8_LDA(At, 1, 1); PG8_STAGE(PG8_SB(1, 0), b3, voffB); PG8_STAGE(PG8_SB(1, 1), b3 + hstepB, voffB); PG8_STAGE(PG8_SA(1, 0), a3, voffA);
;             PG8_WAIT_V(8); PG8_WAIT_L(0); PG8_BAR; PG8_MMA(1, 0, At, B0); PG8_MMA(1, 1, At, B1); PG8_BAR; PG8_SCHED;
;     ...
;         if constexpr (ALIGN_EPI) { if (wr == 0) PG8_BAR; }
	v_mfma_f32_16x16x32_bf16 v[126:129], v[130:133], v[184:187], v[126:129]
	v_mfma_f32_16x16x32_bf16 v[122:125], v[138:141], v[184:187], v[122:125]
	v_mfma_f32_16x16x32_bf16 v[110:113], v[130:133], v[216:219], v[110:113]
	v_mfma_f32_16x16x32_bf16 v[106:109], v[138:141], v[216:219], v[106:109]
	v_mfma_f32_16x16x32_bf16 v[94:97], v[130:133], v[224:227], v[94:97]
	v_mfma_f32_16x16x32_bf16 v[90:93], v[138:141], v[224:227], v[90:93]
	v_mfma_f32_16x16x32_bf16 v[78:81], v[130:133], v[232:235], v[78:81]
	v_mfma_f32_16x16x32_bf16 v[74:77], v[138:141], v[232:235], v[74:77]
	v_mfma_f32_16x16x32_bf16 v[126:129], v[134:137], v[212:215], v[126:129]
	v_mfma_f32_16x16x32_bf16 v[122:125], v[142:145], v[212:215], v[122:125]
	v_mfma_f32_16x16x32_bf16 v[110:113], v[134:137], v[220:223], v[110:113]
	v_mfma_f32_16x16x32_bf16 v[106:109], v[142:145], v[220:223], v[106:109]
	v_mfma_f32_16x16x32_bf16 v[94:97], v[134:137], v[228:231], v[94:97]
	v_mfma_f32_16x16x32_bf16 v[90:93], v[142:145], v[228:231], v[90:93]
	v_mfma_f32_16x16x32_bf16 v[78:81], v[134:137], v[236:239], v[78:81]
	v_mfma_f32_16x16x32_bf16 v[74:77], v[142:145], v[236:239], v[74:77]
	s_setprio 0
	s_setprio 1
	v_mfma_f32_16x16x32_bf16 v[118:121], v[146:149], v[184:187], v[118:121]
	v_mfma_f32_16x16x32_bf16 v[114:117], v[154:157], v[184:187], v[114:117]
	v_mfma_f32_16x16x32_bf16 v[102:105], v[146:149], v[216:219], v[102:105]
	v_mfma_f32_16x16x32_bf16 v[98:101], v[154:157], v[216:219], v[98:101]
	v_mfma_f32_16x16x32_bf16 v[86:89], v[146:149], v[224:227], v[86:89]
	v_mfma_f32_16x16x32_bf16 v[82:85], v[154:157], v[224:227], v[82:85]
	v_mfma_f32_16x16x32_bf16 v[70:73], v[146:149], v[232:235], v[70:73]
	v_mfma_f32_16x16x32_bf16 v[66:69], v[154:157], v[232:235], v[66:69]
	v_mfma_f32_16x16x32_bf16 v[118:121], v[150:153], v[212:215], v[118:121]
	v_mfma_f32_16x16x32_bf16 v[114:117], v[158:161], v[212:215], v[114:117]
	v_mfma_f32_16x16x32_bf16 v[102:105], v[150:153], v[220:223], v[102:105]
	v_mfma_f32_16x16x32_bf16 v[98:101], v[158:161], v[220:223], v[98:101]
	v_mfma_f32_16x16x32_bf16 v[86:89], v[150:153], v[228:231], v[86:89]
	v_mfma_f32_16x16x32_bf16 v[82:85], v[158:161], v[228:231], v[82:85]
	v_mfma_f32_16x16x32_bf16 v[70:73], v[150:153], v[236:239], v[70:73]
	v_mfma_f32_16x16x32_bf16 v[66:69], v[158:161], v[236:239], v[66:69]
	s_setprio 0
	s_barrier
	s_add_i32 s0, s87, s67
	v_lshl_add_u64 v[188:189], v[188:189], 0, s[36:37]
	s_mov_b32 m0, s0
	ds_read_b128 v[184:187], v209 offset:49152
	ds_read_b128 v[212:215], v209 offset:50176
	ds_read_b128 v[216:219], v209 offset:51200
	ds_read_b128 v[220:223], v209 offset:52224
	ds_read_b128 v[224:227], v209 offset:53248
	ds_read_b128 v[228:231], v209 offset:54272
	ds_read_b128 v[232:235], v209 offset:55296
	ds_read_b128 v[236:239], v209 offset:56320
	global_load_lds_dwordx4 v[188:189], off
	s_add_i32 m0, s0, 0x2000
	s_add_u32 s0, s72, 0xb0080
	v_lshl_add_u64 v[188:189], v[240:241], 0, s[36:37]
	s_addc_u32 s1, s73, 0
	s_add_i32 s2, s88, s67
	global_load_lds_dwordx4 v[188:189], off
	v_lshl_add_u64 v[188:189], s[0:1], 0, v[162:163]
	s_mov_b32 m0, s2
	s_nop 0
	global_load_lds_dwordx4 v[188:189], off
	v_lshl_add_u64 v[188:189], s[0:1], 0, v[168:169]
	s_add_i32 m0, s2, 0x2000
	s_nop 0
	global_load_lds_dwordx4 v[188:189], off
	v_lshl_add_u64 v[188:189], v[242:243], 0, s[36:37]
	s_mov_b32 m0, s82
	s_nop 0
	global_load_lds_dwordx4 v[188:189], off
	v_lshl_add_u64 v[188:189], v[244:245], 0, s[36:37]
	s_mov_b32 m0, s83
	s_nop 0
	global_load_lds_dwordx4 v[188:189], off
	s_waitcnt vmcnt(8)
	s_waitcnt lgkmcnt(0)
	s_setprio 1
	s_barrier
	v_mfma_f32_16x16x32_bf16 v[62:65], v[130:133], v[184:187], v[62:65]
	v_mfma_f32_16x16x32_bf16 v[58:61], v[138:141], v[184:187], v[58:61]
	v_mfma_f32_16x16x32_bf16 v[46:49], v[130:133], v[216:219], v[46:49]
	v_mfma_f32_16x16x32_bf16 v[42:45], v[138:141], v[216:219], v[42:45]
	v_mfma_f32_16x16x32_bf16 v[30:33], v[130:133], v[224:227], v[30:33]
	v_mfma_f32_16x16x32_bf16 v[26:29], v[138:141], v[224:227], v[26:29]
	v_mfma_f32_16x16x32_bf16 v[14:17], v[130:133], v[232:235], v[14:17]
	v_mfma_f32_16x16x32_bf16 v[10:13], v[138:141], v[232:235], v[10:13]
	v_mfma_f32_16x16x32_bf16 v[62:65], v[134:137], v[212:215], v[62:65]
	v_mfma_f32_16x16x32_bf16 v[58:61], v[142:145], v[212:215], v[58:61]
	v_mfma_f32_16x16x32_bf16 v[46:49], v[134:137], v[220:223], v[46:49]
	v_mfma_f32_16x16x32_bf16 v[42:45], v[142:145], v[220:223], v[42:45]
	v_mfma_f32_16x16x32_bf16 v[30:33], v[134:137], v[228:231], v[30:33]
	v_mfma_f32_16x16x32_bf16 v[26:29], v[142:145], v[228:231], v[26:29]
	v_mfma_f32_16x16x32_bf16 v[14:17], v[134:137], v[236:239], v[14:17]
	v_mfma_f32_16x16x32_bf16 v[10:13], v[142:145], v[236:239], v[10:13]
	s_setprio 0
	s_setprio 1
	v_mfma_f32_16x16x32_bf16 v[54:57], v[146:149], v[184:187], v[54:57]
	v_mfma_f32_16x16x32_bf16 v[50:53], v[154:157], v[184:187], v[50:53]
	v_mfma_f32_16x16x32_bf16 v[38:41], v[146:149], v[216:219], v[38:41]
	v_mfma_f32_16x16x32_bf16 v[34:37], v[154:157], v[216:219], v[34:37]
	v_mfma_f32_16x16x32_bf16 v[22:25], v[146:149], v[224:227], v[22:25]
	v_mfma_f32_16x16x32_bf16 v[18:21], v[154:157], v[224:227], v[18:21]
	v_mfma_f32_16x16x32_bf16 v[6:9], v[146:149], v[232:235], v[6:9]
	v_mfma_f32_16x16x32_bf16 v[2:5], v[154:157], v[232:235], v[2:5]
	v_mfma_f32_16x16x32_bf16 v[54:57], v[150:153], v[212:215], v[54:57]
	v_mfma_f32_16x16x32_bf16 v[50:53], v[158:161], v[212:215], v[50:53]
	v_mfma_f32_16x16x32_bf16 v[38:41], v[150:153], v[220:223], v[38:41]
	v_mfma_f32_16x16x32_bf16 v[34:37], v[158:161], v[220:223], v[34:37]
	v_mfma_f32_16x16x32_bf16 v[22:25], v[150:153], v[228:231], v[22:25]
	v_mfma_f32_16x16x32_bf16 v[18:21], v[158:161], v[228:231], v[18:21]
	v_mfma_f32_16x16x32_bf16 v[6:9], v[150:153], v[236:239], v[6:9]
	v_mfma_f32_16x16x32_bf16 v[2:5], v[158:161], v[236:239], v[2:5]
	s_setprio 0
	s_barrier
	s_add_i32 s7, s7, 2
	s_add_u32 s4, s4, 0x100
	s_addc_u32 s5, s5, 0
	s_cmp_gt_u32 s7, 41
	s_mov_b64 s[68:69], s[70:71]
	s_cbranch_scc0 .LBB0_1198
	s_and_b64 vcc, exec, s[40:41]
	s_cbranch_vccz .LBB0_1201
	s_barrier

;     __device__ __forceinline__ bool next(int i, Unit& u) const { if (!S.next(i, u)) return false; if (u.pn >= 4) u.pn += 2; return true; }
; #define PG8_STAGE(bufoff, gbase, voff) do { _Pragma("unroll") for (int _i = 0; _i < 2; ++_i) \
;         __builtin_amdgcn_global_load_lds((const unsigned*)((const char*)(gbase) + (voff)[_i]), (PG8_LAS unsigned*)(lds + (bufoff) + ldsw + _i * 8192), 16, 0, 0); } while (0)
; #define PG8_LDA(dst, b, h) do { _Pragma("unroll") for (int m = 0; m < 4; ++m) _Pragma("unroll") for (int k = 0; k < 2; ++k) dst[m][k] = *(const PG8_LAS bf16x8*)(lds + PG8_SA(b, h) + aoff + m * 2048 + k * 1024); } while (0)
; template <class Epi, class Sched, bool ALIGN_EPI = false, bool SP2 = false>
; __device__ __forceinline__ void gemm_phase(PG8_LAS unsigned char* lds, const Gemm g, const Sched& S, const Epi& E) {
;     ...
;         const bool has_next = S.next(ui + 1, nxt);
;         if constexpr (Epi::LDS_PF) { if (has_next) E.prefetch(nxt, lds + STAGE_BYTES + ((ui + 1) % 3) * 4096, wid, lane); }
;         const char* nA = has_next ? (const char*)g.A + (size_t)nxt.pm * tstepA : cA; const char* nB = has_next ? (const char*)g.Bt + (size_t)nxt.pn * tstepB : cB;
;         for (int t = 0; t < nt; t += 2) {
;             const bool last = (t == nt - 2);
;             const char* a1 = cA + (size_t)(t + 1) * kstep;
;             const char* a2 = last ? nA : cA + (size_t)(t + 2) * kstep; const char* b2 = last ? nB : cB + (size_t)(t + 2) * kstep;
;             const char* a3 = a2 + kstep; const char* b3 = b2 + kstep;
;             if (last && has_next) S.a_ready(nxt);
;             if constexpr (SP2) {
;             PG8_LDB(B0, 0, 0); PG8_LDB(B1, 0, 1); PG8_SCHED; PG8_LDA(At, 0, 0); PG8_STAGE(PG8_SA(1, 1), a1 + hstepA, voffA);
;             PG8_WAIT_V(8); PG8_WAIT_L(0); PG8_BAR; PG8_MMA(0, 0, At, B0); PG8_MMA(0, 1, At, B1); PG8_BAR; PG8_SCHED;
;             PG8_LDA(At, 0, 1); PG8_STAGE(PG8_SB(0, 0), b2, voffB); PG8_STAGE(PG8_SB(0, 1), b2 + hstepB, voffB); PG8_STAGE(PG8_SA(0, 0), a2, voffA);
;     ...
; #pragma unroll
;         for (int a = 0; a < 2; ++a)
; #pragma unroll
;             for (int b = 0; b < 2; ++b)
; #pragma unroll
;                 for (int m = 0; m < 4; ++m)
; #pragma unroll
;                     for (int n = 0; n < 2; ++n) acc[a][b][m][n] = (f32x4){0.f, 0.f, 0.f, 0.f};
;         cur = nxt; cA = nA; cB = nB; ++ui;
.LBB0_1341:
	s_mov_b32 s36, s0
	s_ashr_i32 s37, s0, 31
	s_mov_b32 s38, s1
	s_lshl_b64 s[0:1], s[36:37], 19
	v_readlane_b32 s4, v253, 23
	v_readlane_b32 s5, v253, 24
	s_add_u32 s42, s4, s0
	s_addc_u32 s43, s5, s1
	s_and_b64 s[0:1], s[40:41], exec
	s_cselect_b32 s4, s43, s51
	s_cselect_b32 s5, s42, s50
	s_ashr_i32 s39, s38, 31
	s_lshl_b64 s[0:1], s[38:39], 19
	s_add_u32 s44, s34, s0
	s_addc_u32 s45, s35, s1
	s_and_b64 s[0:1], s[40:41], exec
	s_cselect_b32 s18, s45, s67
	s_cselect_b32 s19, s44, s66
	s_add_u32 s50, s50, 0x40080
	s_addc_u32 s51, s51, 0
	s_add_u32 s37, s66, 0x100
	v_mov_b32_e32 v2, 0
	s_addc_u32 s39, s67, 0
	s_mov_b32 s79, -2
	v_mov_b32_e32 v3, v2
	v_mov_b32_e32 v4, v2
	v_mov_b32_e32 v5, v2
	v_mov_b32_e32 v6, v2
	v_mov_b32_e32 v7, v2
	v_mov_b32_e32 v8, v2
	v_mov_b32_e32 v9, v2
	v_mov_b32_e32 v10, v2
	v_mov_b32_e32 v11, v2
	v_mov_b32_e32 v12, v2
	v_mov_b32_e32 v13, v2
	v_mov_b32_e32 v18, v2
	v_mov_b32_e32 v19, v2
	v_mov_b32_e32 v20, v2
	v_mov_b32_e32 v21, v2
	v_mov_b32_e32 v26, v2
	v_mov_b32_e32 v27, v2
	v_mov_b32_e32 v28, v2
	v_mov_b32_e32 v29, v2
	v_mov_b32_e32 v34, v2
	v_mov_b32_e32 v35, v2
	v_mov_b32_e32 v36, v2
	v_mov_b32_e32 v37, v2
	v_mov_b32_e32 v42, v2
	v_mov_b32_e32 v43, v2
	v_mov_b32_e32 v44, v2
	v_mov_b32_e32 v45, v2
	v_mov_b32_e32 v50, v2
	v_mov_b32_e32 v51, v2
	v_mov_b32_e32 v52, v2
	v_mov_b32_e32 v53, v2
	v_mov_b32_e32 v14, v2
	v_mov_b32_e32 v15, v2
	v_mov_b32_e32 v16, v2
	v_mov_b32_e32 v17, v2
	v_mov_b32_e32 v22, v2
	v_mov_b32_e32 v23, v2
	v_mov_b32_e32 v24, v2
	v_mov_b32_e32 v25, v2
	v_mov_b32_e32 v30, v2
	v_mov_b32_e32 v31, v2
	v_mov_b32_e32 v32, v2
	v_mov_b32_e32 v33, v2
	v_mov_b32_e32 v38, v2
	v_mov_b32_e32 v39, v2
	v_mov_b32_e32 v40, v2
	v_mov_b32_e32 v41, v2
	v_mov_b32_e32 v46, v2
	v_mov_b32_e32 v47, v2
	v_mov_b32_e32 v48, v2
	v_mov_b32_e32 v49, v2
	v_mov_b32_e32 v54, v2
	v_mov_b32_e32 v55, v2
	v_mov_b32_e32 v56, v2
	v_mov_b32_e32 v57, v2
	v_mov_b32_e32 v58, v2
	v_mov_b32_e32 v59, v2
	v_mov_b32_e32 v60, v2
	v_mov_b32_e32 v61, v2
	v_mov_b32_e32 v62, v2
	v_mov_b32_e32 v63, v2
	v_mov_b32_e32 v64, v2
	v_mov_b32_e32 v65, v2
	v_mov_b32_e32 v66, v2
	v_mov_b32_e32 v67, v2
	v_mov_b32_e32 v68, v2
	v_mov_b32_e32 v69, v2
	v_mov_b32_e32 v70, v2
	v_mov_b32_e32 v71, v2
	v_mov_b32_e32 v72, v2
	v_mov_b32_e32 v73, v2
	v_mov_b32_e32 v74, v2
	v_mov_b32_e32 v75, v2
	v_mov_b32_e32 v76, v2
	v_mov_b32_e32 v77, v2
	v_mov_b32_e32 v82, v2
	v_mov_b32_e32 v83, v2
	v_mov_b32_e32 v84, v2
	v_mov_b32_e32 v85, v2
	v_mov_b32_e32 v90, v2
	v_mov_b32_e32 v91, v2
	v_mov_b32_e32 v92, v2
	v_mov_b32_e32 v93, v2
	v_mov_b32_e32 v98, v2
	v_mov_b32_e32 v99, v2
	v_mov_b32_e32 v100, v2
	v_mov_b32_e32 v101, v2
	v_mov_b32_e32 v106, v2
	v_mov_b32_e32 v107, v2
	v_mov_b32_e32 v108, v2
	v_mov_b32_e32 v109, v2
	v_mov_b32_e32 v114, v2
	v_mov_b32_e32 v115, v2
	v_mov_b32_e32 v116, v2
	v_mov_b32_e32 v117, v2
	v_mov_b32_e32 v78, v2
	v_mov_b32_e32 v79, v2
	v_mov_b32_e32 v80, v2
	v_mov_b32_e32 v81, v2
	v_mov_b32_e32 v86, v2
	v_mov_b32_e32 v87, v2
	v_mov_b32_e32 v88, v2
	v_mov_b32_e32 v89, v2
	v_mov_b32_e32 v94, v2
	v_mov_b32_e32 v95, v2
	v_mov_b32_e32 v96, v2
	v_mov_b32_e32 v97, v2
	v_mov_b32_e32 v102, v2
	v_mov_b32_e32 v103, v2
	v_mov_b32_e32 v104, v2
	v_mov_b32_e32 v105, v2
	v_mov_b32_e32 v110, v2
	v_mov_b32_e32 v111, v2
	v_mov_b32_e32 v112, v2
	v_mov_b32_e32 v113, v2
	v_mov_b32_e32 v118, v2
	v_mov_b32_e32 v119, v2
	v_mov_b32_e32 v120, v2
	v_mov_b32_e32 v121, v2
	v_mov_b32_e32 v122, v2
	v_mov_b32_e32 v123, v2
	v_mov_b32_e32 v124, v2
	v_mov_b32_e32 v125, v2
	v_mov_b32_e32 v126, v2
	v_mov_b32_e32 v127, v2
	v_mov_b32_e32 v128, v2
	v_mov_b32_e32 v129, v2
.LBB0_1342:
	ds_read_b128 v[144:147], v150
	ds_read_b128 v[156:159], v150 offset:1024
	ds_read_b128 v[160:163], v150 offset:2048
	ds_read_b128 v[164:167], v150 offset:3072
	ds_read_b128 v[168:171], v151
	ds_read_b128 v[172:175], v151 offset:1024
	ds_read_b128 v[176:179], v151 offset:2048
	ds_read_b128 v[180:183], v151 offset:3072
	s_add_u32 s0, s50, 0xfffc0080
	s_addc_u32 s1, s51, -1
	s_cmp_eq_u32 s79, 12
	s_cselect_b32 s69, s4, s1
	s_cselect_b32 s68, s5, s0
	s_cselect_b32 s67, s18, s39
	s_cselect_b32 s66, s19, s37
	v_lshl_add_u64 v[216:217], s[50:51], 0, v[138:139]
	s_add_i32 m0, s14, 0xc000
	ds_read_b128 v[184:187], v152
	ds_read_b128 v[188:191], v152 offset:1024
	ds_read_b128 v[192:195], v152 offset:2048
	ds_read_b128 v[196:199], v152 offset:3072
	ds_read_b128 v[200:203], v152 offset:4096
	ds_read_b128 v[204:207], v152 offset:5120
	ds_read_b128 v[208:211], v152 offset:6144
	ds_read_b128 v[212:215], v152 offset:7168
	global_load_lds_dwordx4 v[216:217], off
	v_lshl_add_u64 v[216:217], s[50:51], 0, v[140:141]
	s_add_i32 m0, s14, 0xe000
	s_nop 0
	global_load_lds_dwordx4 v[216:217], off
	s_waitcnt vmcnt(8)
	s_waitcnt lgkmcnt(0)
	s_setprio 1
	s_barrier
; #define PG8_STAGE(bufoff, gbase, voff) do { _Pragma("unroll") for (int _i = 0; _i < 2; ++_i) \
;         __builtin_amdgcn_global_load_lds((const unsigned*)((const char*)(gbase) + (voff)[_i]), (PG8_LAS unsigned*)(lds + (bufoff) + ldsw + _i * 8192), 16, 0, 0); } while (0)
; #define PG8_LDA(dst, b, h) do { _Pragma("unroll") for (int m = 0; m < 4; ++m) _Pragma("unroll") for (int k = 0; k < 2; ++k) dst[m][k] = *(const PG8_LAS bf16x8*)(lds + PG8_SA(b, h) + aoff + m * 2048 + k * 1024); } while (0)
; #define PG8_LDB(dst, b, h) do { _Pragma("unroll") for (int n = 0; n < 2; ++n) _Pragma("unroll") for (int k = 0; k < 2; ++k) dst[n][k] = *(const PG8_LAS bf16x8*)(lds + PG8_SB(b, h) + boff + n * 2048 + k * 1024); } while (0)
; #define PG8_MMA(ai, bj, At, Bt) do { __builtin_amdgcn_s_setprio(1); _Pragma("unroll") for (int m = 0; m < 4; ++m) _Pragma("unroll") for (int n = 0; n < 2; ++n) _Pragma("unroll") for (int k = 0; k < 2; ++k) \
;         acc[ai][bj][m][n] = __builtin_amdgcn_mfma_f32_16x16x32_bf16(Bt[n][k], At[m][k], acc[ai][bj][m][n], 0, 0, 0); __builtin_amdgcn_s_setprio(0); } while (0)
; #define PG8_WAIT_V(n) asm volatile("s_waitcnt vmcnt(" #n ")" ::: "memory")
; #define PG8_WAIT_L(n) asm volatile("s_waitcnt lgkmcnt(" #n ")" ::: "memory")
; #define PG8_BAR __builtin_amdgcn_s_barrier()
; #define PG8_SCHED __builtin_amdgcn_sched_barrier(0)
; template <class Epi, class Sched, bool ALIGN_EPI = false, bool SP2 = false>
; __device__ __forceinline__ void gemm_phase(PG8_LAS unsigned char* lds, const Gemm g, const Sched& S, const Epi& E) {
;     ...
;             PG8_LDB(B0, 0, 0); PG8_LDB(B1, 0, 1); PG8_SCHED; PG8_LDA(At, 0, 0); PG8_STAGE(PG8_SA(1, 1), a1 + hstepA, voffA);
;             PG8_WAIT_V(8); PG8_WAIT_L(0); PG8_BAR; PG8_MMA(0, 0, At, B0); PG8_MMA(0, 1, At, B1); PG8_BAR; PG8_SCHED;
;             PG8_LDA(At, 0, 1); PG8_STAGE(PG8_SB(0, 0), b2, voffB); PG8_STAGE(PG8_SB(0, 1), b2 + hstepB, voffB); PG8_STAGE(PG8_SA(0, 0), a2, voffA);
;             PG8_WAIT_V(8); PG8_WAIT_L(0); PG8_BAR; PG8_MMA(1, 0, At, B0); PG8_MMA(1, 1, At, B1); PG8_BAR; PG8_SCHED;
	v_mfma_f32_16x16x32_bf16 v[126:129], v[144:147], v[184:187], v[126:129]
	v_mfma_f32_16x16x32_bf16 v[122:125], v[160:163], v[184:187], v[122:125]
	v_mfma_f32_16x16x32_bf16 v[118:121], v[144:147], v[192:195], v[118:121]
	v_mfma_f32_16x16x32_bf16 v[110:113], v[160:163], v[192:195], v[110:113]
	v_mfma_f32_16x16x32_bf16 v[102:105], v[144:147], v[200:203], v[102:105]
	v_mfma_f32_16x16x32_bf16 v[94:97], v[160:163], v[200:203], v[94:97]
	v_mfma_f32_16x16x32_bf16 v[86:89], v[144:147], v[208:211], v[86:89]
	v_mfma_f32_16x16x32_bf16 v[78:81], v[160:163], v[208:211], v[78:81]
	v_mfma_f32_16x16x32_bf16 v[126:129], v[156:159], v[188:191], v[126:129]
	v_mfma_f32_16x16x32_bf16 v[122:125], v[164:167], v[188:191], v[122:125]
	v_mfma_f32_16x16x32_bf16 v[118:121], v[156:159], v[196:199], v[118:121]
	v_mfma_f32_16x16x32_bf16 v[110:113], v[164:167], v[196:199], v[110:113]
	v_mfma_f32_16x16x32_bf16 v[102:105], v[156:159], v[204:207], v[102:105]
	v_mfma_f32_16x16x32_bf16 v[94:97], v[164:167], v[204:207], v[94:97]
	v_mfma_f32_16x16x32_bf16 v[86:89], v[156:159], v[212:215], v[86:89]
	v_mfma_f32_16x16x32_bf16 v[78:81], v[164:167], v[212:215], v[78:81]
	s_setprio 0
	s_setprio 1
	v_mfma_f32_16x16x32_bf16 v[114:117], v[168:171], v[184:187], v[114:117]
	v_mfma_f32_16x16x32_bf16 v[106:109], v[176:179], v[184:187], v[106:109]
	v_mfma_f32_16x16x32_bf16 v[98:101], v[168:171], v[192:195], v[98:101]
	v_mfma_f32_16x16x32_bf16 v[90:93], v[176:179], v[192:195], v[90:93]
	v_mfma_f32_16x16x32_bf16 v[82:85], v[168:171], v[200:203], v[82:85]
	v_mfma_f32_16x16x32_bf16 v[74:77], v[176:179], v[200:203], v[74:77]
	v_mfma_f32_16x16x32_bf16 v[70:73], v[168:171], v[208:211], v[70:73]
	v_mfma_f32_16x16x32_bf16 v[66:69], v[176:179], v[208:211], v[66:69]
	v_mfma_f32_16x16x32_bf16 v[114:117], v[172:175], v[188:191], v[114:117]
	v_mfma_f32_16x16x32_bf16 v[106:109], v[180:183], v[188:191], v[106:109]
	v_mfma_f32_16x16x32_bf16 v[98:101], v[172:175], v[196:199], v[98:101]
	v_mfma_f32_16x16x32_bf16 v[90:93], v[180:183], v[196:199], v[90:93]
	v_mfma_f32_16x16x32_bf16 v[82:85], v[172:175], v[204:207], v[82:85]
	v_mfma_f32_16x16x32_bf16 v[74:77], v[180:183], v[204:207], v[74:77]
	v_mfma_f32_16x16x32_bf16 v[70:73], v[172:175], v[212:215], v[70:73]
	v_mfma_f32_16x16x32_bf16 v[66:69], v[180:183], v[212:215], v[66:69]
	s_setprio 0
	s_barrier
	s_add_i32 s0, s75, s3
	v_lshl_add_u64 v[216:217], s[66:67], 0, v[134:135]
	s_mov_b32 m0, s0
	ds_read_b128 v[184:187], v152 offset:16384
	ds_read_b128 v[188:191], v152 offset:17408
	ds_read_b128 v[192:195], v152 offset:18432
	ds_read_b128 v[196:199], v152 offset:19456
	ds_read_b128 v[200:203], v152 offset:20480
	ds_read_b128 v[204:207], v152 offset:21504
	ds_read_b128 v[208:211], v152 offset:22528
	ds_read_b128 v[212:215], v152 offset:23552
	global_load_lds_dwordx4 v[216:217], off
	s_add_i32 m0, s0, 0x2000
	s_add_u32 s0, s66, 0x40000
	v_lshl_add_u64 v[218:219], s[66:67], 0, v[130:131]
	s_addc_u32 s1, s67, 0
	s_add_i32 s2, s76, s3
	global_load_lds_dwordx4 v[218:219], off
	v_lshl_add_u64 v[220:221], s[0:1], 0, v[134:135]
	s_mov_b32 m0, s2
	v_lshl_add_u64 v[222:223], s[68:69], 0, v[132:133]
	global_load_lds_dwordx4 v[220:221], off
	v_lshl_add_u64 v[220:221], s[0:1], 0, v[130:131]
	s_add_i32 m0, s2, 0x2000
	s_nop 0
	global_load_lds_dwordx4 v[220:221], off
	v_lshl_add_u64 v[220:221], s[68:69], 0, v[136:137]
	s_mov_b32 m0, s14
	s_nop 0
	global_load_lds_dwordx4 v[220:221], off
	s_mov_b32 m0, s15
	s_nop 0
	global_load_lds_dwordx4 v[222:223], off
	s_waitcnt vmcnt(8)
	s_waitcnt lgkmcnt(0)
	s_setprio 1
	s_barrier
	v_mfma_f32_16x16x32_bf16 v[62:65], v[144:147], v[184:187], v[62:65]
	v_mfma_f32_16x16x32_bf16 v[58:61], v[160:163], v[184:187], v[58:61]
	v_mfma_f32_16x16x32_bf16 v[54:57], v[144:147], v[192:195], v[54:57]
	v_mfma_f32_16x16x32_bf16 v[46:49], v[160:163], v[192:195], v[46:49]
	v_mfma_f32_16x16x32_bf16 v[38:41], v[144:147], v[200:203], v[38:41]
	v_mfma_f32_16x16x32_bf16 v[30:33], v[160:163], v[200:203], v[30:33]
	v_mfma_f32_16x16x32_bf16 v[22:25], v[144:147], v[208:211], v[22:25]
	v_mfma_f32_16x16x32_bf16 v[14:17], v[160:163], v[208:211], v[14:17]
	v_mfma_f32_16x16x32_bf16 v[62:65], v[156:159], v[188:191], v[62:65]
	v_mfma_f32_16x16x32_bf16 v[58:61], v[164:167], v[188:191], v[58:61]
	v_mfma_f32_16x16x32_bf16 v[54:57], v[156:159], v[196:199], v[54:57]
	v_mfma_f32_16x16x32_bf16 v[46:49], v[164:167], v[196:199], v[46:49]
	v_mfma_f32_16x16x32_bf16 v[38:41], v[156:159], v[204:207], v[38:41]
	v_mfma_f32_16x16x32_bf16 v[30:33], v[164:167], v[204:207], v[30:33]
	v_mfma_f32_16x16x32_bf16 v[22:25], v[156:159], v[212:215], v[22:25]
	v_mfma_f32_16x16x32_bf16 v[14:17], v[164:167], v[212:215], v[14:17]
	s_setprio 0
	s_setprio 1
	v_mfma_f32_16x16x32_bf16 v[50:53], v[168:171], v[184:187], v[50:53]
	v_mfma_f32_16x16x32_bf16 v[42:45], v[176:179], v[184:187], v[42:45]
	v_mfma_f32_16x16x32_bf16 v[34:37], v[168:171], v[192:195], v[34:37]
	v_mfma_f32_16x16x32_bf16 v[26:29], v[176:179], v[192:195], v[26:29]
	v_mfma_f32_16x16x32_bf16 v[18:21], v[168:171], v[200:203], v[18:21]
	v_mfma_f32_16x16x32_bf16 v[10:13], v[176:179], v[200:203], v[10:13]
	v_mfma_f32_16x16x32_bf16 v[6:9], v[168:171], v[208:211], v[6:9]
	v_mfma_f32_16x16x32_bf16 v[2:5], v[176:179], v[208:211], v[2:5]
	v_mfma_f32_16x16x32_bf16 v[50:53], v[172:175], v[188:191], v[50:53]
	v_mfma_f32_16x16x32_bf16 v[42:45], v[180:183], v[188:191], v[42:45]
	v_mfma_f32_16x16x32_bf16 v[34:37], v[172:175], v[196:199], v[34:37]
	v_mfma_f32_16x16x32_bf16 v[26:29], v[180:183], v[196:199], v[26:29]
	v_mfma_f32_16x16x32_bf16 v[18:21], v[172:175], v[204:207], v[18:21]
	v_mfma_f32_16x16x32_bf16 v[10:13], v[180:183], v[204:207], v[10:13]
	v_mfma_f32_16x16x32_bf16 v[6:9], v[172:175], v[212:215], v[6:9]
	v_mfma_f32_16x16x32_bf16 v[2:5], v[180:183], v[212:215], v[2:5]
	s_setprio 0
	s_barrier
; #define PG8_STAGE(bufoff, gbase, voff) do { _Pragma("unroll") for (int _i = 0; _i < 2; ++_i) \
;         __builtin_amdgcn_global_load_lds((const unsigned*)((const char*)(gbase) + (voff)[_i]), (PG8_LAS unsigned*)(lds + (bufoff) + ldsw + _i * 8192), 16, 0, 0); } while (0)
; #define PG8_LDA(dst, b, h) do { _Pragma("unroll") for (int m = 0; m < 4; ++m) _Pragma("unroll") for (int k = 0; k < 2; ++k) dst[m][k] = *(const PG8_LAS bf16x8*)(lds + PG8_SA(b, h) + aoff + m * 2048 + k * 1024); } while (0)
; #define PG8_LDB(dst, b, h) do { _Pragma("unroll") for (int n = 0; n < 2; ++n) _Pragma("unroll") for (int k = 0; k < 2; ++k) dst[n][k] = *(const PG8_LAS bf16x8*)(lds + PG8_SB(b, h) + boff + n * 2048 + k * 1024); } while (0)
; #define PG8_MMA(ai, bj, At, Bt) do { __builtin_amdgcn_s_setprio(1); _Pragma("unroll") for (int m = 0; m < 4; ++m) _Pragma("unroll") for (int n = 0; n < 2; ++n) _Pragma("unroll") for (int k = 0; k < 2; ++k) \
;         acc[ai][bj][m][n] = __builtin_amdgcn_mfma_f32_16x16x32_bf16(Bt[n][k], At[m][k], acc[ai][bj][m][n], 0, 0, 0); __builtin_amdgcn_s_setprio(0); } while (0)
; #define PG8_WAIT_V(n) asm volatile("s_waitcnt vmcnt(" #n ")" ::: "memory")
; #define PG8_WAIT_L(n) asm volatile("s_waitcnt lgkmcnt(" #n ")" ::: "memory")
; #define PG8_BAR __builtin_amdgcn_s_barrier()
; #define PG8_SCHED __builtin_amdgcn_sched_barrier(0)
; template <class Epi, class Sched, bool ALIGN_EPI = false, bool SP2 = false>
; __device__ __forceinline__ void gemm_phase(PG8_LAS unsigned char* lds, const Gemm g, const Sched& S, const Epi& E) {
;     ...
;         for (int t = 0; t < nt; t += 2) {
;     ...
;             PG8_LDB(B0, 1, 0); PG8_LDB(B1, 1, 1); PG8_SCHED; PG8_LDA(At, 1, 0); PG8_STAGE(PG8_SA(0, 1), a2 + hstepA, voffA);
;             PG8_WAIT_V(8); PG8_WAIT_L(0); PG8_BAR; PG8_MMA(0, 0, At, B0); PG8_MMA(0, 1, At, B1); PG8_BAR; PG8_SCHED;
;             PG8_LDA(At, 1, 1); PG8_STAGE(PG8_SB(1, 0), b3, voffB); PG8_STAGE(PG8_SB(1, 1), b3 + hstepB, voffB); PG8_STAGE(PG8_SA(1, 0), a3, voffA);
;             PG8_WAIT_V(8); PG8_WAIT_L(0); PG8_BAR; PG8_MMA(1, 0, At, B0); PG8_MMA(1, 1, At, B1); PG8_BAR; PG8_SCHED;
;     ...
;         if constexpr (ALIGN_EPI) { if (wr == 0) PG8_BAR; }
	ds_read_b128 v[144:147], v153
	ds_read_b128 v[156:159], v153 offset:1024
	ds_read_b128 v[160:163], v153 offset:2048
	ds_read_b128 v[164:167], v153 offset:3072
	ds_read_b128 v[168:171], v154
	ds_read_b128 v[172:175], v154 offset:1024
	ds_read_b128 v[176:179], v154 offset:2048
	ds_read_b128 v[180:183], v154 offset:3072
	s_add_u32 s0, s68, 0x40000
	s_addc_u32 s1, s69, 0
	s_mov_b32 m0, s20
	v_lshl_add_u64 v[224:225], s[0:1], 0, v[136:137]
	ds_read_b128 v[184:187], v152 offset:32768
	ds_read_b128 v[188:191], v152 offset:33792
	ds_read_b128 v[192:195], v152 offset:34816
	ds_read_b128 v[196:199], v152 offset:35840
	ds_read_b128 v[200:203], v152 offset:36864
	ds_read_b128 v[204:207], v152 offset:37888
	ds_read_b128 v[208:211], v152 offset:38912
	ds_read_b128 v[212:215], v152 offset:39936
	global_load_lds_dwordx4 v[224:225], off
	v_lshl_add_u64 v[224:225], s[0:1], 0, v[132:133]
	s_mov_b32 m0, s21
	s_nop 0
	global_load_lds_dwordx4 v[224:225], off
	s_waitcnt vmcnt(8)
	s_waitcnt lgkmcnt(0)
	s_setprio 1
	s_barrier
	v_mfma_f32_16x16x32_bf16 v[126:129], v[144:147], v[184:187], v[126:129]
	v_mfma_f32_16x16x32_bf16 v[122:125], v[160:163], v[184:187], v[122:125]
	v_mfma_f32_16x16x32_bf16 v[118:121], v[144:147], v[192:195], v[118:121]
	v_mfma_f32_16x16x32_bf16 v[110:113], v[160:163], v[192:195], v[110:113]
	v_mfma_f32_16x16x32_bf16 v[102:105], v[144:147], v[200:203], v[102:105]
	v_mfma_f32_16x16x32_bf16 v[94:97], v[160:163], v[200:203], v[94:97]
	v_mfma_f32_16x16x32_bf16 v[86:89], v[144:147], v[208:211], v[86:89]
	v_mfma_f32_16x16x32_bf16 v[78:81], v[160:163], v[208:211], v[78:81]
	v_mfma_f32_16x16x32_bf16 v[126:129], v[156:159], v[188:191], v[126:129]
	v_mfma_f32_16x16x32_bf16 v[122:125], v[164:167], v[188:191], v[122:125]
	v_mfma_f32_16x16x32_bf16 v[118:121], v[156:159], v[196:199], v[118:121]
	v_mfma_f32_16x16x32_bf16 v[110:113], v[164:167], v[196:199], v[110:113]
	v_mfma_f32_16x16x32_bf16 v[102:105], v[156:159], v[204:207], v[102:105]
	v_mfma_f32_16x16x32_bf16 v[94:97], v[164:167], v[204:207], v[94:97]
	v_mfma_f32_16x16x32_bf16 v[86:89], v[156:159], v[212:215], v[86:89]
	v_mfma_f32_16x16x32_bf16 v[78:81], v[164:167], v[212:215], v[78:81]
	s_setprio 0
	s_setprio 1
	v_mfma_f32_16x16x32_bf16 v[114:117], v[168:171], v[184:187], v[114:117]
	v_mfma_f32_16x16x32_bf16 v[106:109], v[176:179], v[184:187], v[106:109]
	v_mfma_f32_16x16x32_bf16 v[98:101], v[168:171], v[192:195], v[98:101]
	v_mfma_f32_16x16x32_bf16 v[90:93], v[176:179], v[192:195], v[90:93]
	v_mfma_f32_16x16x32_bf16 v[82:85], v[168:171], v[200:203], v[82:85]
	v_mfma_f32_16x16x32_bf16 v[74:77], v[176:179], v[200:203], v[74:77]
	v_mfma_f32_16x16x32_bf16 v[70:73], v[168:171], v[208:211], v[70:73]
	v_mfma_f32_16x16x32_bf16 v[66:69], v[176:179], v[208:211], v[66:69]
	v_mfma_f32_16x16x32_bf16 v[114:117], v[172:175], v[188:191], v[114:117]
	v_mfma_f32_16x16x32_bf16 v[106:109], v[180:183], v[188:191], v[106:109]
	v_mfma_f32_16x16x32_bf16 v[98:101], v[172:175], v[196:199], v[98:101]
	v_mfma_f32_16x16x32_bf16 v[90:93], v[180:183], v[196:199], v[90:93]
	v_mfma_f32_16x16x32_bf16 v[82:85], v[172:175], v[204:207], v[82:85]
	v_mfma_f32_16x16x32_bf16 v[74:77], v[180:183], v[204:207], v[74:77]
	v_mfma_f32_16x16x32_bf16 v[70:73], v[172:175], v[212:215], v[70:73]
	v_mfma_f32_16x16x32_bf16 v[66:69], v[180:183], v[212:215], v[66:69]
	s_setprio 0
	s_barrier
	s_add_i32 s0, s77, s3
	v_lshl_add_u64 v[216:217], v[216:217], 0, s[8:9]
	s_mov_b32 m0, s0
	ds_read_b128 v[184:187], v152 offset:49152
	ds_read_b128 v[188:191], v152 offset:50176
	ds_read_b128 v[192:195], v152 offset:51200
	ds_read_b128 v[196:199], v152 offset:52224
	ds_read_b128 v[200:203], v152 offset:53248
	ds_read_b128 v[204:207], v152 offset:54272
	ds_read_b128 v[208:211], v152 offset:55296
	ds_read_b128 v[212:215], v152 offset:56320
	global_load_lds_dwordx4 v[216:217], off
	s_add_i32 m0, s0, 0x2000
	s_add_u32 s0, s66, 0x40080
	v_lshl_add_u64 v[216:217], v[218:219], 0, s[8:9]
	s_addc_u32 s1, s67, 0
	s_add_i32 s2, s78, s3
	global_load_lds_dwordx4 v[216:217], off
	v_lshl_add_u64 v[216:217], s[0:1], 0, v[134:135]
	s_mov_b32 m0, s2
	s_nop 0
	global_load_lds_dwordx4 v[216:217], off
	v_lshl_add_u64 v[216:217], s[0:1], 0, v[130:131]
	s_add_i32 m0, s2, 0x2000
	s_nop 0
	global_load_lds_dwordx4 v[216:217], off
	v_lshl_add_u64 v[216:217], v[220:221], 0, s[8:9]
	s_mov_b32 m0, s47
	s_nop 0
	global_load_lds_dwordx4 v[216:217], off
	v_lshl_add_u64 v[216:217], v[222:223], 0, s[8:9]
	s_mov_b32 m0, s49
	s_nop 0
	global_load_lds_dwordx4 v[216:217], off
	s_waitcnt vmcnt(8)
	s_waitcnt lgkmcnt(0)
	s_setprio 1
	s_barrier
	v_mfma_f32_16x16x32_bf16 v[62:65], v[144:147], v[184:187], v[62:65]
	v_mfma_f32_16x16x32_bf16 v[58:61], v[160:163], v[184:187], v[58:61]
	v_mfma_f32_16x16x32_bf16 v[54:57], v[144:147], v[192:195], v[54:57]
	v_mfma_f32_16x16x32_bf16 v[46:49], v[160:163], v[192:195], v[46:49]
	v_mfma_f32_16x16x32_bf16 v[38:41], v[144:147], v[200:203], v[38:41]
	v_mfma_f32_16x16x32_bf16 v[30:33], v[160:163], v[200:203], v[30:33]
	v_mfma_f32_16x16x32_bf16 v[22:25], v[144:147], v[208:211], v[22:25]
	v_mfma_f32_16x16x32_bf16 v[14:17], v[160:163], v[208:211], v[14:17]
	v_mfma_f32_16x16x32_bf16 v[62:65], v[156:159], v[188:191], v[62:65]
	v_mfma_f32_16x16x32_bf16 v[58:61], v[164:167], v[188:191], v[58:61]
	v_mfma_f32_16x16x32_bf16 v[54:57], v[156:159], v[196:199], v[54:57]
	v_mfma_f32_16x16x32_bf16 v[46:49], v[164:167], v[196:199], v[46:49]
	v_mfma_f32_16x16x32_bf16 v[38:41], v[156:159], v[204:207], v[38:41]
	v_mfma_f32_16x16x32_bf16 v[30:33], v[164:167], v[204:207], v[30:33]
	v_mfma_f32_16x16x32_bf16 v[22:25], v[156:159], v[212:215], v[22:25]
	v_mfma_f32_16x16x32_bf16 v[14:17], v[164:167], v[212:215], v[14:17]
	s_setprio 0
	s_setprio 1
	v_mfma_f32_16x16x32_bf16 v[50:53], v[168:171], v[184:187], v[50:53]
	v_mfma_f32_16x16x32_bf16 v[42:45], v[176:179], v[184:187], v[42:45]
	v_mfma_f32_16x16x32_bf16 v[34:37], v[168:171], v[192:195], v[34:37]
	v_mfma_f32_16x16x32_bf16 v[26:29], v[176:179], v[192:195], v[26:29]
	v_mfma_f32_16x16x32_bf16 v[18:21], v[168:171], v[200:203], v[18:21]
	v_mfma_f32_16x16x32_bf16 v[10:13], v[176:179], v[200:203], v[10:13]
	v_mfma_f32_16x16x32_bf16 v[6:9], v[168:171], v[208:211], v[6:9]
	v_mfma_f32_16x16x32_bf16 v[2:5], v[176:179], v[208:211], v[2:5]
	v_mfma_f32_16x16x32_bf16 v[50:53], v[172:175], v[188:191], v[50:53]
	v_mfma_f32_16x16x32_bf16 v[42:45], v[180:183], v[188:191], v[42:45]
	v_mfma_f32_16x16x32_bf16 v[34:37], v[172:175], v[196:199], v[34:37]
	v_mfma_f32_16x16x32_bf16 v[26:29], v[180:183], v[196:199], v[26:29]
	v_mfma_f32_16x16x32_bf16 v[18:21], v[172:175], v[204:207], v[18:21]
	v_mfma_f32_16x16x32_bf16 v[10:13], v[180:183], v[204:207], v[10:13]
	v_mfma_f32_16x16x32_bf16 v[6:9], v[172:175], v[212:215], v[6:9]
	v_mfma_f32_16x16x32_bf16 v[2:5], v[180:183], v[212:215], v[2:5]
	s_setprio 0
	s_barrier
	s_add_i32 s79, s79, 2
	s_add_u32 s50, s50, 0x100
	s_addc_u32 s51, s51, 0
	s_add_u32 s37, s37, 0x100
	s_addc_u32 s39, s39, 0
	s_cmp_gt_u32 s79, 13
	s_cbranch_scc0 .LBB0_1342
	s_and_b64 vcc, exec, s[12:13]
	s_cbranch_vccz .LBB0_1345
	s_barrier

; #define LAS __attribute__((address_space(3)))
; #define MFMA32(a, b, c) __builtin_amdgcn_mfma_f32_32x32x16_bf16((a), (b), (c), 0, 0, 0)
; __device__ __forceinline__ void mla_block(int bh, int sb, int tid, int lane, int wave, LAS unsigned char* lds, const bf16_t* __restrict__ QM, const bf16_t* __restrict__ KVM, const bf16_t* __restrict__ KPE, ...
;     ...
;     for (int step = 0; step < nsteps; ++step) {
;         const int nx = (step + 1 < nsteps) ? step + 1 : step;
;         rk = *(const v4u*)(gKn + (size_t)nx * 64 * 512); rr = *(const v4u*)(gKr + (size_t)nx * 64 * 32); rv = *(const v4u*)(gVt + nx * 64);
;         const LAS unsigned char* Kb = lds + (step & 1) * ML_STAGE;
;         const LAS unsigned char* Vb = Kb + MLK_BYTES;
;         if (64 * step <= q0) {
;             f32x16 acc[2];
;             {
;                 bf16x8 kf[2][6];
; #pragma unroll
;                 for (int sub = 0; sub < 2; ++sub)
; #pragma unroll
;                     for (int kk = 0; kk < 6; ++kk) kf[sub][kk] = *(const LAS bf16x8*)(Kb + (32 * sub + l31) * (MLK_PITCH * 2) + (16 * kk + 8 * hi) * 2);
;                 __builtin_amdgcn_sched_barrier(0);
; #pragma unroll
;                 for (int r = 0; r < 16; ++r) { acc[0][r] = 0.f; acc[1][r] = 0.f; }
; #pragma unroll
;                 for (int kk = 0; kk < 6; ++kk) { acc[0] = MFMA32(kf[0][kk], qf[kk], acc[0]); acc[1] = MFMA32(kf[1][kk], qf[kk], acc[1]); }
;             }
;             u32x2 vx[2][2][2][2];
; #pragma unroll
;             for (int sub = 0; sub < 2; ++sub)
; #pragma unroll
;                 for (int dt = 0; dt < 2; ++dt)
; #pragma unroll
;                     for (int ks = 0; ks < 2; ++ks) { const LAS unsigned char* vp = Vb + (32 * dt + l31) * (MLV_PITCH * 2) + (32 * sub + 16 * ks + 4 * hi) * 2;
;                         vx[sub][dt][ks][0] = *(const LAS u32x2*)vp; vx[sub][dt][ks][1] = *(const LAS u32x2*)(vp + 16); }
.Lmla_lead_in:
.LBB0_1593:
	s_add_i32 s41, s0, 1
	s_cmp_gt_i32 s40, s18
	s_cbranch_scc1 .Lmla_stage
	s_bitcmp1_b32 s0, 0
	s_cselect_b32 s0, 0x5600, 0
	s_add_i32 s0, s0, 0
	v_add_u32_e32 v3, s0, v138
	v_add_u32_e32 v36, v3, v151
	v_add_u32_e32 v3, v3, v176
	ds_read_b128 v[52:55], v36
	ds_read_b128 v[104:107], v36 offset:32
	ds_read_b128 v[108:111], v36 offset:64
	ds_read_b128 v[112:115], v36 offset:96
	ds_read_b128 v[116:119], v36 offset:128
	ds_read_b128 v[184:187], v36 offset:160
	ds_read_b128 v[36:39], v3
	ds_read_b128 v[56:59], v3 offset:32
	ds_read_b128 v[60:63], v3 offset:64
	ds_read_b128 v[64:67], v3 offset:96
	ds_read_b128 v[120:123], v3 offset:128
	ds_read_b128 v[124:127], v3 offset:160
	s_waitcnt lgkmcnt(5)
	s_setprio 2
	v_mfma_f32_32x32x16_bf16 v[36:51], v[36:39], v[68:71], 0
	v_add_u32_e32 v3, s0, v137
	s_waitcnt lgkmcnt(4)
	v_mfma_f32_32x32x16_bf16 v[36:51], v[56:59], v[72:75], v[36:51]
	s_waitcnt lgkmcnt(3)
	v_mfma_f32_32x32x16_bf16 v[36:51], v[60:63], v[76:79], v[36:51]
	s_waitcnt lgkmcnt(2)
	v_mfma_f32_32x32x16_bf16 v[36:51], v[64:67], v[80:83], v[36:51]
	v_mfma_f32_32x32x16_bf16 v[52:67], v[52:55], v[68:71], 0
	v_mfma_f32_32x32x16_bf16 v[52:67], v[104:107], v[72:75], v[52:67]
	v_add_u32_e32 v104, v3, v177
	v_add_u32_e32 v3, v3, v178
	v_add_u32_e32 v104, 0x3000, v104
	v_add_u32_e32 v3, 0x3000, v3
	v_mfma_f32_32x32x16_bf16 v[52:67], v[108:111], v[76:79], v[52:67]
	v_mfma_f32_32x32x16_bf16 v[52:67], v[112:115], v[80:83], v[52:67]
	s_waitcnt lgkmcnt(1)
	v_mfma_f32_32x32x16_bf16 v[36:51], v[120:123], v[88:91], v[36:51]
	v_mfma_f32_32x32x16_bf16 v[52:67], v[116:119], v[88:91], v[52:67]
	s_waitcnt lgkmcnt(0)
	v_mfma_f32_32x32x16_bf16 v[36:51], v[124:127], v[84:87], v[36:51]
	ds_read2_b64 v[132:135], v104 offset0:128 offset1:130
	ds_read2_b64 v[124:127], v104 offset0:132 offset1:134
	ds_read2_b64 v[128:131], v3 offset0:128 offset1:130
	ds_read2_b64 v[120:123], v3 offset0:132 offset1:134
	ds_read2_b64 v[116:119], v104 offset0:136 offset1:138
	ds_read2_b64 v[108:111], v104 offset0:140 offset1:142
	ds_read2_b64 v[112:115], v3 offset0:136 offset1:138
	ds_read2_b64 v[104:107], v3 offset0:140 offset1:142
	v_mfma_f32_32x32x16_bf16 v[52:67], v[184:187], v[84:87], v[52:67]
	s_setprio 0

;     __device__ __forceinline__ bool next(int i, Unit& u) const { if (!S.next(i, u)) return false; if (u.pn >= 4) u.pn += 2; return true; }
; #define PG8_STAGE(bufoff, gbase, voff) do { _Pragma("unroll") for (int _i = 0; _i < 2; ++_i) \
;         __builtin_amdgcn_global_load_lds((const unsigned*)((const char*)(gbase) + (voff)[_i]), (PG8_LAS unsigned*)(lds + (bufoff) + ldsw + _i * 8192), 16, 0, 0); } while (0)
; #define PG8_LDA(dst, b, h) do { _Pragma("unroll") for (int m = 0; m < 4; ++m) _Pragma("unroll") for (int k = 0; k < 2; ++k) dst[m][k] = *(const PG8_LAS bf16x8*)(lds + PG8_SA(b, h) + aoff + m * 2048 + k * 1024); } while (0)
; template <class Epi, class Sched, bool ALIGN_EPI = false, bool SP2 = false>
; __device__ __forceinline__ void gemm_phase(PG8_LAS unsigned char* lds, const Gemm g, const Sched& S, const Epi& E) {
;     ...
;         const bool has_next = S.next(ui + 1, nxt);
;         if constexpr (Epi::LDS_PF) { if (has_next) E.prefetch(nxt, lds + STAGE_BYTES + ((ui + 1) % 3) * 4096, wid, lane); }
;         const char* nA = has_next ? (const char*)g.A + (size_t)nxt.pm * tstepA : cA; const char* nB = has_next ? (const char*)g.Bt + (size_t)nxt.pn * tstepB : cB;
;         for (int t = 0; t < nt; t += 2) {
;             const bool last = (t == nt - 2);
;             const char* a1 = cA + (size_t)(t + 1) * kstep;
;             const char* a2 = last ? nA : cA + (size_t)(t + 2) * kstep; const char* b2 = last ? nB : cB + (size_t)(t + 2) * kstep;
;             const char* a3 = a2 + kstep; const char* b3 = b2 + kstep;
;             if (last && has_next) S.a_ready(nxt);
;             if constexpr (SP2) {
;             PG8_LDB(B0, 0, 0); PG8_LDB(B1, 0, 1); PG8_SCHED; PG8_LDA(At, 0, 0); PG8_STAGE(PG8_SA(1, 1), a1 + hstepA, voffA);
;             PG8_WAIT_V(8); PG8_WAIT_L(0); PG8_BAR; PG8_MMA(0, 0, At, B0); PG8_MMA(0, 1, At, B1); PG8_BAR; PG8_SCHED;
;             PG8_LDA(At, 0, 1); PG8_STAGE(PG8_SB(0, 0), b2, voffB); PG8_STAGE(PG8_SB(0, 1), b2 + hstepB, voffB); PG8_STAGE(PG8_SA(0, 0), a2, voffA);
;     ...
; #pragma unroll
;         for (int a = 0; a < 2; ++a)
; #pragma unroll
;             for (int b = 0; b < 2; ++b)
; #pragma unroll
;                 for (int m = 0; m < 4; ++m)
; #pragma unroll
;                     for (int n = 0; n < 2; ++n) acc[a][b][m][n] = (f32x4){0.f, 0.f, 0.f, 0.f};
;         cur = nxt; cA = nA; cB = nB; ++ui;
.LBB0_1682:
	s_ashr_i32 s49, s48, 31
	s_lshl_b64 s[0:1], s[48:49], 19
	s_add_u32 s66, s26, s0
	s_addc_u32 s67, s27, s1
	s_and_b64 s[0:1], s[12:13], exec
	s_cselect_b32 s4, s67, s73
	s_cselect_b32 s5, s66, s72
	s_add_u32 s12, s70, 0x40080
	s_addc_u32 s13, s71, 0
	s_add_u32 s7, s72, 0x100
	v_mov_b32_e32 v2, 0
	s_addc_u32 s14, s73, 0
	s_mov_b32 s15, -2
	v_mov_b32_e32 v3, v2
	v_mov_b32_e32 v4, v2
	v_mov_b32_e32 v5, v2
	v_mov_b32_e32 v6, v2
	v_mov_b32_e32 v7, v2
	v_mov_b32_e32 v8, v2
	v_mov_b32_e32 v9, v2
	v_mov_b32_e32 v18, v2
	v_mov_b32_e32 v19, v2
	v_mov_b32_e32 v20, v2
	v_mov_b32_e32 v21, v2
	v_mov_b32_e32 v22, v2
	v_mov_b32_e32 v23, v2
	v_mov_b32_e32 v24, v2
	v_mov_b32_e32 v25, v2
	s_waitcnt vmcnt(0)
	v_mov_b32_e32 v34, v2
	v_mov_b32_e32 v35, v2
	v_mov_b32_e32 v36, v2
	v_mov_b32_e32 v37, v2
	v_mov_b32_e32 v38, v2
	v_mov_b32_e32 v39, v2
	v_mov_b32_e32 v40, v2
	v_mov_b32_e32 v41, v2
	v_mov_b32_e32 v50, v2
	v_mov_b32_e32 v51, v2
	v_mov_b32_e32 v52, v2
	v_mov_b32_e32 v53, v2
	v_mov_b32_e32 v54, v2
	v_mov_b32_e32 v55, v2
	v_mov_b32_e32 v56, v2
	v_mov_b32_e32 v57, v2
	v_mov_b32_e32 v10, v2
	v_mov_b32_e32 v11, v2
	v_mov_b32_e32 v12, v2
	v_mov_b32_e32 v13, v2
	v_mov_b32_e32 v14, v2
	v_mov_b32_e32 v15, v2
	v_mov_b32_e32 v16, v2
	v_mov_b32_e32 v17, v2
	v_mov_b32_e32 v26, v2
	v_mov_b32_e32 v27, v2
	v_mov_b32_e32 v28, v2
	v_mov_b32_e32 v29, v2
	v_mov_b32_e32 v30, v2
	v_mov_b32_e32 v31, v2
	v_mov_b32_e32 v32, v2
	v_mov_b32_e32 v33, v2
	v_mov_b32_e32 v42, v2
	v_mov_b32_e32 v43, v2
	v_mov_b32_e32 v44, v2
	v_mov_b32_e32 v45, v2
	v_mov_b32_e32 v46, v2
	v_mov_b32_e32 v47, v2
	v_mov_b32_e32 v48, v2
	v_mov_b32_e32 v49, v2
	v_mov_b32_e32 v58, v2
	v_mov_b32_e32 v59, v2
	v_mov_b32_e32 v60, v2
	v_mov_b32_e32 v61, v2
	v_mov_b32_e32 v62, v2
	v_mov_b32_e32 v63, v2
	v_mov_b32_e32 v64, v2
	v_mov_b32_e32 v65, v2
	v_mov_b32_e32 v66, v2
	v_mov_b32_e32 v67, v2
	v_mov_b32_e32 v68, v2
	v_mov_b32_e32 v69, v2
	v_mov_b32_e32 v70, v2
	v_mov_b32_e32 v71, v2
	v_mov_b32_e32 v72, v2
	v_mov_b32_e32 v73, v2
	v_mov_b32_e32 v82, v2
	v_mov_b32_e32 v83, v2
	v_mov_b32_e32 v84, v2
	v_mov_b32_e32 v85, v2
	v_mov_b32_e32 v86, v2
	v_mov_b32_e32 v87, v2
	v_mov_b32_e32 v88, v2
	v_mov_b32_e32 v89, v2
	v_mov_b32_e32 v98, v2
	v_mov_b32_e32 v99, v2
	v_mov_b32_e32 v100, v2
	v_mov_b32_e32 v101, v2
	v_mov_b32_e32 v102, v2
	v_mov_b32_e32 v103, v2
	v_mov_b32_e32 v104, v2
	v_mov_b32_e32 v105, v2
	v_mov_b32_e32 v114, v2
	v_mov_b32_e32 v115, v2
	v_mov_b32_e32 v116, v2
	v_mov_b32_e32 v117, v2
	v_mov_b32_e32 v118, v2
	v_mov_b32_e32 v119, v2
	v_mov_b32_e32 v120, v2
	v_mov_b32_e32 v121, v2
	v_mov_b32_e32 v74, v2
	v_mov_b32_e32 v75, v2
	v_mov_b32_e32 v76, v2
	v_mov_b32_e32 v77, v2
	v_mov_b32_e32 v78, v2
	v_mov_b32_e32 v79, v2
	v_mov_b32_e32 v80, v2
	v_mov_b32_e32 v81, v2
	v_mov_b32_e32 v90, v2
	v_mov_b32_e32 v91, v2
	v_mov_b32_e32 v92, v2
	v_mov_b32_e32 v93, v2
	v_mov_b32_e32 v94, v2
	v_mov_b32_e32 v95, v2
	v_mov_b32_e32 v96, v2
	v_mov_b32_e32 v97, v2
	v_mov_b32_e32 v106, v2
	v_mov_b32_e32 v107, v2
	v_mov_b32_e32 v108, v2
	v_mov_b32_e32 v109, v2
	v_mov_b32_e32 v110, v2
	v_mov_b32_e32 v111, v2
	v_mov_b32_e32 v112, v2
	v_mov_b32_e32 v113, v2
	v_mov_b32_e32 v122, v2
	v_mov_b32_e32 v123, v2
	v_mov_b32_e32 v124, v2
	v_mov_b32_e32 v125, v2
	v_mov_b32_e32 v126, v2
	v_mov_b32_e32 v127, v2
	v_mov_b32_e32 v128, v2
	v_mov_b32_e32 v129, v2
.LBB0_1683:
	ds_read_b128 v[130:133], v189
	ds_read_b128 v[134:137], v189 offset:1024
	ds_read_b128 v[138:141], v189 offset:2048
	ds_read_b128 v[142:145], v189 offset:3072
	ds_read_b128 v[168:171], v190
	ds_read_b128 v[194:197], v190 offset:1024
	ds_read_b128 v[198:201], v190 offset:2048
	ds_read_b128 v[202:205], v190 offset:3072
	s_add_u32 s0, s12, 0xfffc0080
	s_addc_u32 s1, s13, -1
	s_cmp_eq_u32 s15, 12
	s_cselect_b32 s73, s63, s1
	s_cselect_b32 s72, s62, s0
	s_cselect_b32 s71, s4, s14
	s_cselect_b32 s70, s5, s7
	v_lshl_add_u64 v[238:239], s[12:13], 0, v[160:161]
	s_add_i32 m0, s74, 0xc000
	ds_read_b128 v[206:209], v191
	ds_read_b128 v[210:213], v191 offset:1024
	ds_read_b128 v[214:217], v191 offset:2048
	ds_read_b128 v[218:221], v191 offset:3072
	ds_read_b128 v[222:225], v191 offset:4096
	ds_read_b128 v[226:229], v191 offset:5120
	ds_read_b128 v[230:233], v191 offset:6144
	ds_read_b128 v[234:237], v191 offset:7168
	global_load_lds_dwordx4 v[238:239], off
	v_lshl_add_u64 v[238:239], s[12:13], 0, v[162:163]
	s_add_i32 m0, s74, 0xe000
	s_nop 0
	global_load_lds_dwordx4 v[238:239], off
	s_waitcnt vmcnt(8)
	s_waitcnt lgkmcnt(0)
	s_setprio 1
	s_barrier
; #define PG8_STAGE(bufoff, gbase, voff) do { _Pragma("unroll") for (int _i = 0; _i < 2; ++_i) \
;         __builtin_amdgcn_global_load_lds((const unsigned*)((const char*)(gbase) + (voff)[_i]), (PG8_LAS unsigned*)(lds + (bufoff) + ldsw + _i * 8192), 16, 0, 0); } while (0)
; #define PG8_LDA(dst, b, h) do { _Pragma("unroll") for (int m = 0; m < 4; ++m) _Pragma("unroll") for (int k = 0; k < 2; ++k) dst[m][k] = *(const PG8_LAS bf16x8*)(lds + PG8_SA(b, h) + aoff + m * 2048 + k * 1024); } while (0)
; #define PG8_LDB(dst, b, h) do { _Pragma("unroll") for (int n = 0; n < 2; ++n) _Pragma("unroll") for (int k = 0; k < 2; ++k) dst[n][k] = *(const PG8_LAS bf16x8*)(lds + PG8_SB(b, h) + boff + n * 2048 + k * 1024); } while (0)
; #define PG8_MMA(ai, bj, At, Bt) do { __builtin_amdgcn_s_setprio(1); _Pragma("unroll") for (int m = 0; m < 4; ++m) _Pragma("unroll") for (int n = 0; n < 2; ++n) _Pragma("unroll") for (int k = 0; k < 2; ++k) \
;         acc[ai][bj][m][n] = __builtin_amdgcn_mfma_f32_16x16x32_bf16(Bt[n][k], At[m][k], acc[ai][bj][m][n], 0, 0, 0); __builtin_amdgcn_s_setprio(0); } while (0)
; #define PG8_WAIT_V(n) asm volatile("s_waitcnt vmcnt(" #n ")" ::: "memory")
; #define PG8_WAIT_L(n) asm volatile("s_waitcnt lgkmcnt(" #n ")" ::: "memory")
; #define PG8_BAR __builtin_amdgcn_s_barrier()
; #define PG8_SCHED __builtin_amdgcn_sched_barrier(0)
; template <class Epi, class Sched, bool ALIGN_EPI = false, bool SP2 = false>
; __device__ __forceinline__ void gemm_phase(PG8_LAS unsigned char* lds, const Gemm g, const Sched& S, const Epi& E) {
;     ...
;             PG8_LDB(B0, 0, 0); PG8_LDB(B1, 0, 1); PG8_SCHED; PG8_LDA(At, 0, 0); PG8_STAGE(PG8_SA(1, 1), a1 + hstepA, voffA);
;             PG8_WAIT_V(8); PG8_WAIT_L(0); PG8_BAR; PG8_MMA(0, 0, At, B0); PG8_MMA(0, 1, At, B1); PG8_BAR; PG8_SCHED;
;             PG8_LDA(At, 0, 1); PG8_STAGE(PG8_SB(0, 0), b2, voffB); PG8_STAGE(PG8_SB(0, 1), b2 + hstepB, voffB); PG8_STAGE(PG8_SA(0, 0), a2, voffA);
;             PG8_WAIT_V(8); PG8_WAIT_L(0); PG8_BAR; PG8_MMA(1, 0, At, B0); PG8_MMA(1, 1, At, B1); PG8_BAR; PG8_SCHED;
	v_mfma_f32_16x16x32_bf16 v[126:129], v[130:133], v[206:209], v[126:129]
	v_mfma_f32_16x16x32_bf16 v[122:125], v[138:141], v[206:209], v[122:125]
	v_mfma_f32_16x16x32_bf16 v[110:113], v[130:133], v[214:217], v[110:113]
	v_mfma_f32_16x16x32_bf16 v[106:109], v[138:141], v[214:217], v[106:109]
	v_mfma_f32_16x16x32_bf16 v[94:97], v[130:133], v[222:225], v[94:97]
	v_mfma_f32_16x16x32_bf16 v[90:93], v[138:141], v[222:225], v[90:93]
	v_mfma_f32_16x16x32_bf16 v[78:81], v[130:133], v[230:233], v[78:81]
	v_mfma_f32_16x16x32_bf16 v[74:77], v[138:141], v[230:233], v[74:77]
	v_mfma_f32_16x16x32_bf16 v[126:129], v[134:137], v[210:213], v[126:129]
	v_mfma_f32_16x16x32_bf16 v[122:125], v[142:145], v[210:213], v[122:125]
	v_mfma_f32_16x16x32_bf16 v[110:113], v[134:137], v[218:221], v[110:113]
	v_mfma_f32_16x16x32_bf16 v[106:109], v[142:145], v[218:221], v[106:109]
	v_mfma_f32_16x16x32_bf16 v[94:97], v[134:137], v[226:229], v[94:97]
	v_mfma_f32_16x16x32_bf16 v[90:93], v[142:145], v[226:229], v[90:93]
	v_mfma_f32_16x16x32_bf16 v[78:81], v[134:137], v[234:237], v[78:81]
	v_mfma_f32_16x16x32_bf16 v[74:77], v[142:145], v[234:237], v[74:77]
	s_setprio 0
	s_setprio 1
	v_mfma_f32_16x16x32_bf16 v[118:121], v[168:171], v[206:209], v[118:121]
	v_mfma_f32_16x16x32_bf16 v[114:117], v[198:201], v[206:209], v[114:117]
	v_mfma_f32_16x16x32_bf16 v[102:105], v[168:171], v[214:217], v[102:105]
	v_mfma_f32_16x16x32_bf16 v[98:101], v[198:201], v[214:217], v[98:101]
	v_mfma_f32_16x16x32_bf16 v[86:89], v[168:171], v[222:225], v[86:89]
	v_mfma_f32_16x16x32_bf16 v[82:85], v[198:201], v[222:225], v[82:85]
	v_mfma_f32_16x16x32_bf16 v[70:73], v[168:171], v[230:233], v[70:73]
	v_mfma_f32_16x16x32_bf16 v[66:69], v[198:201], v[230:233], v[66:69]
	v_mfma_f32_16x16x32_bf16 v[118:121], v[194:197], v[210:213], v[118:121]
	v_mfma_f32_16x16x32_bf16 v[114:117], v[202:205], v[210:213], v[114:117]
	v_mfma_f32_16x16x32_bf16 v[102:105], v[194:197], v[218:221], v[102:105]
	v_mfma_f32_16x16x32_bf16 v[98:101], v[202:205], v[218:221], v[98:101]
	v_mfma_f32_16x16x32_bf16 v[86:89], v[194:197], v[226:229], v[86:89]
	v_mfma_f32_16x16x32_bf16 v[82:85], v[202:205], v[226:229], v[82:85]
	v_mfma_f32_16x16x32_bf16 v[70:73], v[194:197], v[234:237], v[70:73]
	v_mfma_f32_16x16x32_bf16 v[66:69], v[202:205], v[234:237], v[66:69]
	s_setprio 0
	s_barrier
	s_add_i32 s0, s80, s69
	v_lshl_add_u64 v[238:239], s[70:71], 0, v[146:147]
	s_mov_b32 m0, s0
	ds_read_b128 v[206:209], v191 offset:16384
	ds_read_b128 v[210:213], v191 offset:17408
	ds_read_b128 v[214:217], v191 offset:18432
	ds_read_b128 v[218:221], v191 offset:19456
	ds_read_b128 v[222:225], v191 offset:20480
	ds_read_b128 v[226:229], v191 offset:21504
	ds_read_b128 v[230:233], v191 offset:22528
	ds_read_b128 v[234:237], v191 offset:23552
	global_load_lds_dwordx4 v[238:239], off
	s_add_i32 m0, s0, 0x2000
	s_add_u32 s0, s70, 0x40000
	v_lshl_add_u64 v[240:241], s[70:71], 0, v[152:153]
	s_addc_u32 s1, s71, 0
	s_add_i32 s2, s81, s69
	global_load_lds_dwordx4 v[240:241], off
	v_lshl_add_u64 v[242:243], s[0:1], 0, v[146:147]
	s_mov_b32 m0, s2
	v_lshl_add_u64 v[244:245], s[72:73], 0, v[150:151]
	global_load_lds_dwordx4 v[242:243], off
	v_lshl_add_u64 v[242:243], s[0:1], 0, v[152:153]
	s_add_i32 m0, s2, 0x2000
	s_nop 0
	global_load_lds_dwordx4 v[242:243], off
	v_lshl_add_u64 v[242:243], s[72:73], 0, v[148:149]
	s_mov_b32 m0, s74
	s_nop 0
	global_load_lds_dwordx4 v[242:243], off
	s_mov_b32 m0, s75
	s_nop 0
	global_load_lds_dwordx4 v[244:245], off
	s_waitcnt vmcnt(8)
	s_waitcnt lgkmcnt(0)
	s_setprio 1
	s_barrier
	v_mfma_f32_16x16x32_bf16 v[62:65], v[130:133], v[206:209], v[62:65]
	v_mfma_f32_16x16x32_bf16 v[58:61], v[138:141], v[206:209], v[58:61]
	v_mfma_f32_16x16x32_bf16 v[46:49], v[130:133], v[214:217], v[46:49]
	v_mfma_f32_16x16x32_bf16 v[42:45], v[138:141], v[214:217], v[42:45]
	v_mfma_f32_16x16x32_bf16 v[30:33], v[130:133], v[222:225], v[30:33]
	v_mfma_f32_16x16x32_bf16 v[26:29], v[138:141], v[222:225], v[26:29]
	v_mfma_f32_16x16x32_bf16 v[14:17], v[130:133], v[230:233], v[14:17]
	v_mfma_f32_16x16x32_bf16 v[10:13], v[138:141], v[230:233], v[10:13]
	v_mfma_f32_16x16x32_bf16 v[62:65], v[134:137], v[210:213], v[62:65]
	v_mfma_f32_16x16x32_bf16 v[58:61], v[142:145], v[210:213], v[58:61]
	v_mfma_f32_16x16x32_bf16 v[46:49], v[134:137], v[218:221], v[46:49]
	v_mfma_f32_16x16x32_bf16 v[42:45], v[142:145], v[218:221], v[42:45]
	v_mfma_f32_16x16x32_bf16 v[30:33], v[134:137], v[226:229], v[30:33]
	v_mfma_f32_16x16x32_bf16 v[26:29], v[142:145], v[226:229], v[26:29]
	v_mfma_f32_16x16x32_bf16 v[14:17], v[134:137], v[234:237], v[14:17]
	v_mfma_f32_16x16x32_bf16 v[10:13], v[142:145], v[234:237], v[10:13]
	s_setprio 0
	s_setprio 1
	v_mfma_f32_16x16x32_bf16 v[54:57], v[168:171], v[206:209], v[54:57]
	v_mfma_f32_16x16x32_bf16 v[50:53], v[198:201], v[206:209], v[50:53]
	v_mfma_f32_16x16x32_bf16 v[38:41], v[168:171], v[214:217], v[38:41]
	v_mfma_f32_16x16x32_bf16 v[34:37], v[198:201], v[214:217], v[34:37]
	v_mfma_f32_16x16x32_bf16 v[22:25], v[168:171], v[222:225], v[22:25]
	v_mfma_f32_16x16x32_bf16 v[18:21], v[198:201], v[222:225], v[18:21]
	v_mfma_f32_16x16x32_bf16 v[6:9], v[168:171], v[230:233], v[6:9]
	v_mfma_f32_16x16x32_bf16 v[2:5], v[198:201], v[230:233], v[2:5]
	v_mfma_f32_16x16x32_bf16 v[54:57], v[194:197], v[210:213], v[54:57]
	v_mfma_f32_16x16x32_bf16 v[50:53], v[202:205], v[210:213], v[50:53]
	v_mfma_f32_16x16x32_bf16 v[38:41], v[194:197], v[218:221], v[38:41]
	v_mfma_f32_16x16x32_bf16 v[34:37], v[202:205], v[218:221], v[34:37]
	v_mfma_f32_16x16x32_bf16 v[22:25], v[194:197], v[226:229], v[22:25]
	v_mfma_f32_16x16x32_bf16 v[18:21], v[202:205], v[226:229], v[18:21]
	v_mfma_f32_16x16x32_bf16 v[6:9], v[194:197], v[234:237], v[6:9]
	v_mfma_f32_16x16x32_bf16 v[2:5], v[202:205], v[234:237], v[2:5]
	s_setprio 0
	s_barrier
; #define PG8_STAGE(bufoff, gbase, voff) do { _Pragma("unroll") for (int _i = 0; _i < 2; ++_i) \
;         __builtin_amdgcn_global_load_lds((const unsigned*)((const char*)(gbase) + (voff)[_i]), (PG8_LAS unsigned*)(lds + (bufoff) + ldsw + _i * 8192), 16, 0, 0); } while (0)
; #define PG8_LDA(dst, b, h) do { _Pragma("unroll") for (int m = 0; m < 4; ++m) _Pragma("unroll") for (int k = 0; k < 2; ++k) dst[m][k] = *(const PG8_LAS bf16x8*)(lds + PG8_SA(b, h) + aoff + m * 2048 + k * 1024); } while (0)
; #define PG8_LDB(dst, b, h) do { _Pragma("unroll") for (int n = 0; n < 2; ++n) _Pragma("unroll") for (int k = 0; k < 2; ++k) dst[n][k] = *(const PG8_LAS bf16x8*)(lds + PG8_SB(b, h) + boff + n * 2048 + k * 1024); } while (0)
; #define PG8_MMA(ai, bj, At, Bt) do { __builtin_amdgcn_s_setprio(1); _Pragma("unroll") for (int m = 0; m < 4; ++m) _Pragma("unroll") for (int n = 0; n < 2; ++n) _Pragma("unroll") for (int k = 0; k < 2; ++k) \
;         acc[ai][bj][m][n] = __builtin_amdgcn_mfma_f32_16x16x32_bf16(Bt[n][k], At[m][k], acc[ai][bj][m][n], 0, 0, 0); __builtin_amdgcn_s_setprio(0); } while (0)
; #define PG8_WAIT_V(n) asm volatile("s_waitcnt vmcnt(" #n ")" ::: "memory")
; #define PG8_WAIT_L(n) asm volatile("s_waitcnt lgkmcnt(" #n ")" ::: "memory")
; #define PG8_BAR __builtin_amdgcn_s_barrier()
; #define PG8_SCHED __builtin_amdgcn_sched_barrier(0)
; template <class Epi, class Sched, bool ALIGN_EPI = false, bool SP2 = false>
; __device__ __forceinline__ void gemm_phase(PG8_LAS unsigned char* lds, const Gemm g, const Sched& S, const Epi& E) {
;     ...
;             PG8_LDB(B0, 1, 0); PG8_LDB(B1, 1, 1); PG8_SCHED; PG8_LDA(At, 1, 0); PG8_STAGE(PG8_SA(0, 1), a2 + hstepA, voffA);
;             PG8_WAIT_V(8); PG8_WAIT_L(0); PG8_BAR; PG8_MMA(0, 0, At, B0); PG8_MMA(0, 1, At, B1); PG8_BAR; PG8_SCHED;
	ds_read_b128 v[130:133], v192
	ds_read_b128 v[134:137], v192 offset:1024
	ds_read_b128 v[138:141], v192 offset:2048
	ds_read_b128 v[142:145], v192 offset:3072
	ds_read_b128 v[168:171], v193
	ds_read_b128 v[194:197], v193 offset:1024
	ds_read_b128 v[198:201], v193 offset:2048
	ds_read_b128 v[202:205], v193 offset:3072
	s_add_u32 s0, s72, 0x40000
	s_addc_u32 s1, s73, 0
	s_mov_b32 m0, s76
	v_lshl_add_u64 v[246:247], s[0:1], 0, v[148:149]
	ds_read_b128 v[206:209], v191 offset:32768
	ds_read_b128 v[210:213], v191 offset:33792
	ds_read_b128 v[214:217], v191 offset:34816
	ds_read_b128 v[218:221], v191 offset:35840
	ds_read_b128 v[222:225], v191 offset:36864
	ds_read_b128 v[226:229], v191 offset:37888
	ds_read_b128 v[230:233], v191 offset:38912
	ds_read_b128 v[234:237], v191 offset:39936
	global_load_lds_dwordx4 v[246:247], off
	v_lshl_add_u64 v[246:247], s[0:1], 0, v[150:151]
	s_mov_b32 m0, s77
	s_nop 0
	global_load_lds_dwordx4 v[246:247], off
	s_waitcnt vmcnt(8)
	s_waitcnt lgkmcnt(0)
	s_setprio 1
	s_barrier
	v_mfma_f32_16x16x32_bf16 v[126:129], v[130:133], v[206:209], v[126:129]
	v_mfma_f32_16x16x32_bf16 v[122:125], v[138:141], v[206:209], v[122:125]
	v_mfma_f32_16x16x32_bf16 v[110:113], v[130:133], v[214:217], v[110:113]
	v_mfma_f32_16x16x32_bf16 v[106:109], v[138:141], v[214:217], v[106:109]
	v_mfma_f32_16x16x32_bf16 v[94:97], v[130:133], v[222:225], v[94:97]
	v_mfma_f32_16x16x32_bf16 v[90:93], v[138:141], v[222:225], v[90:93]
	v_mfma_f32_16x16x32_bf16 v[78:81], v[130:133], v[230:233], v[78:81]
	v_mfma_f32_16x16x32_bf16 v[74:77], v[138:141], v[230:233], v[74:77]
	v_mfma_f32_16x16x32_bf16 v[126:129], v[134:137], v[210:213], v[126:129]
	v_mfma_f32_16x16x32_bf16 v[122:125], v[142:145], v[210:213], v[122:125]
	v_mfma_f32_16x16x32_bf16 v[110:113], v[134:137], v[218:221], v[110:113]
	v_mfma_f32_16x16x32_bf16 v[106:109], v[142:145], v[218:221], v[106:109]
	v_mfma_f32_16x16x32_bf16 v[94:97], v[134:137], v[226:229], v[94:97]
	v_mfma_f32_16x16x32_bf16 v[90:93], v[142:145], v[226:229], v[90:93]
	v_mfma_f32_16x16x32_bf16 v[78:81], v[134:137], v[234:237], v[78:81]
	v_mfma_f32_16x16x32_bf16 v[74:77], v[142:145], v[234:237], v[74:77]
	s_setprio 0
	s_setprio 1
	v_mfma_f32_16x16x32_bf16 v[118:121], v[168:171], v[206:209], v[118:121]
	v_mfma_f32_16x16x32_bf16 v[114:117], v[198:201], v[206:209], v[114:117]
	v_mfma_f32_16x16x32_bf16 v[102:105], v[168:171], v[214:217], v[102:105]
	v_mfma_f32_16x16x32_bf16 v[98:101], v[198:201], v[214:217], v[98:101]
	v_mfma_f32_16x16x32_bf16 v[86:89], v[168:171], v[222:225], v[86:89]
	v_mfma_f32_16x16x32_bf16 v[82:85], v[198:201], v[222:225], v[82:85]
	v_mfma_f32_16x16x32_bf16 v[70:73], v[168:171], v[230:233], v[70:73]
	v_mfma_f32_16x16x32_bf16 v[66:69], v[198:201], v[230:233], v[66:69]
	v_mfma_f32_16x16x32_bf16 v[118:121], v[194:197], v[210:213], v[118:121]
	v_mfma_f32_16x16x32_bf16 v[114:117], v[202:205], v[210:213], v[114:117]
	v_mfma_f32_16x16x32_bf16 v[102:105], v[194:197], v[218:221], v[102:105]
	v_mfma_f32_16x16x32_bf16 v[98:101], v[202:205], v[218:221], v[98:101]
	v_mfma_f32_16x16x32_bf16 v[86:89], v[194:197], v[226:229], v[86:89]
	v_mfma_f32_16x16x32_bf16 v[82:85], v[202:205], v[226:229], v[82:85]
	v_mfma_f32_16x16x32_bf16 v[70:73], v[194:197], v[234:237], v[70:73]
	v_mfma_f32_16x16x32_bf16 v[66:69], v[202:205], v[234:237], v[66:69]
	s_setprio 0
	s_barrier
; #define PG8_STAGE(bufoff, gbase, voff) do { _Pragma("unroll") for (int _i = 0; _i < 2; ++_i) \
;         __builtin_amdgcn_global_load_lds((const unsigned*)((const char*)(gbase) + (voff)[_i]), (PG8_LAS unsigned*)(lds + (bufoff) + ldsw + _i * 8192), 16, 0, 0); } while (0)
; #define PG8_LDA(dst, b, h) do { _Pragma("unroll") for (int m = 0; m < 4; ++m) _Pragma("unroll") for (int k = 0; k < 2; ++k) dst[m][k] = *(const PG8_LAS bf16x8*)(lds + PG8_SA(b, h) + aoff + m * 2048 + k * 1024); } while (0)
; #define PG8_MMA(ai, bj, At, Bt) do { __builtin_amdgcn_s_setprio(1); _Pragma("unroll") for (int m = 0; m < 4; ++m) _Pragma("unroll") for (int n = 0; n < 2; ++n) _Pragma("unroll") for (int k = 0; k < 2; ++k) \
;         acc[ai][bj][m][n] = __builtin_amdgcn_mfma_f32_16x16x32_bf16(Bt[n][k], At[m][k], acc[ai][bj][m][n], 0, 0, 0); __builtin_amdgcn_s_setprio(0); } while (0)
; #define PG8_WAIT_V(n) asm volatile("s_waitcnt vmcnt(" #n ")" ::: "memory")
; #define PG8_WAIT_L(n) asm volatile("s_waitcnt lgkmcnt(" #n ")" ::: "memory")
; #define PG8_BAR __builtin_amdgcn_s_barrier()
; #define PG8_SCHED __builtin_amdgcn_sched_barrier(0)
; template <class Epi, class Sched, bool ALIGN_EPI = false, bool SP2 = false>
; __device__ __forceinline__ void gemm_phase(PG8_LAS unsigned char* lds, const Gemm g, const Sched& S, const Epi& E) {
;     ...
;         for (int t = 0; t < nt; t += 2) {
;     ...
;             PG8_LDA(At, 1, 1); PG8_STAGE(PG8_SB(1, 0), b3, voffB); PG8_STAGE(PG8_SB(1, 1), b3 + hstepB, voffB); PG8_STAGE(PG8_SA(1, 0), a3, voffA);
;             PG8_WAIT_V(8); PG8_WAIT_L(0); PG8_BAR; PG8_MMA(1, 0, At, B0); PG8_MMA(1, 1, At, B1); PG8_BAR; PG8_SCHED;
;     ...
;         if constexpr (ALIGN_EPI) { if (wr == 0) PG8_BAR; }
	s_add_i32 s0, s82, s69
	v_lshl_add_u64 v[238:239], v[238:239], 0, s[28:29]
	s_mov_b32 m0, s0
	ds_read_b128 v[206:209], v191 offset:49152
	ds_read_b128 v[210:213], v191 offset:50176
	ds_read_b128 v[214:217], v191 offset:51200
	ds_read_b128 v[218:221], v191 offset:52224
	ds_read_b128 v[222:225], v191 offset:53248
	ds_read_b128 v[226:229], v191 offset:54272
	ds_read_b128 v[230:233], v191 offset:55296
	ds_read_b128 v[234:237], v191 offset:56320
	global_load_lds_dwordx4 v[238:239], off
	s_add_i32 m0, s0, 0x2000
	s_add_u32 s0, s70, 0x40080
	v_lshl_add_u64 v[238:239], v[240:241], 0, s[28:29]
	s_addc_u32 s1, s71, 0
	s_add_i32 s2, s83, s69
	global_load_lds_dwordx4 v[238:239], off
	v_lshl_add_u64 v[238:239], s[0:1], 0, v[146:147]
	s_mov_b32 m0, s2
	s_nop 0
	global_load_lds_dwordx4 v[238:239], off
	v_lshl_add_u64 v[238:239], s[0:1], 0, v[152:153]
	s_add_i32 m0, s2, 0x2000
	s_nop 0
	global_load_lds_dwordx4 v[238:239], off
	v_lshl_add_u64 v[238:239], v[242:243], 0, s[28:29]
	s_mov_b32 m0, s78
	s_nop 0
	global_load_lds_dwordx4 v[238:239], off
	v_lshl_add_u64 v[238:239], v[244:245], 0, s[28:29]
	s_mov_b32 m0, s79
	s_nop 0
	global_load_lds_dwordx4 v[238:239], off
	s_waitcnt vmcnt(8)
	s_waitcnt lgkmcnt(0)
	s_setprio 1
	s_barrier
	v_mfma_f32_16x16x32_bf16 v[62:65], v[130:133], v[206:209], v[62:65]
	v_mfma_f32_16x16x32_bf16 v[58:61], v[138:141], v[206:209], v[58:61]
	v_mfma_f32_16x16x32_bf16 v[46:49], v[130:133], v[214:217], v[46:49]
	v_mfma_f32_16x16x32_bf16 v[42:45], v[138:141], v[214:217], v[42:45]
	v_mfma_f32_16x16x32_bf16 v[30:33], v[130:133], v[222:225], v[30:33]
	v_mfma_f32_16x16x32_bf16 v[26:29], v[138:141], v[222:225], v[26:29]
	v_mfma_f32_16x16x32_bf16 v[14:17], v[130:133], v[230:233], v[14:17]
	v_mfma_f32_16x16x32_bf16 v[10:13], v[138:141], v[230:233], v[10:13]
	v_mfma_f32_16x16x32_bf16 v[62:65], v[134:137], v[210:213], v[62:65]
	v_mfma_f32_16x16x32_bf16 v[58:61], v[142:145], v[210:213], v[58:61]
	v_mfma_f32_16x16x32_bf16 v[46:49], v[134:137], v[218:221], v[46:49]
	v_mfma_f32_16x16x32_bf16 v[42:45], v[142:145], v[218:221], v[42:45]
	v_mfma_f32_16x16x32_bf16 v[30:33], v[134:137], v[226:229], v[30:33]
	v_mfma_f32_16x16x32_bf16 v[26:29], v[142:145], v[226:229], v[26:29]
	v_mfma_f32_16x16x32_bf16 v[14:17], v[134:137], v[234:237], v[14:17]
	v_mfma_f32_16x16x32_bf16 v[10:13], v[142:145], v[234:237], v[10:13]
	s_setprio 0
	s_setprio 1
	v_mfma_f32_16x16x32_bf16 v[54:57], v[168:171], v[206:209], v[54:57]
	v_mfma_f32_16x16x32_bf16 v[50:53], v[198:201], v[206:209], v[50:53]
	v_mfma_f32_16x16x32_bf16 v[38:41], v[168:171], v[214:217], v[38:41]
	v_mfma_f32_16x16x32_bf16 v[34:37], v[198:201], v[214:217], v[34:37]
	v_mfma_f32_16x16x32_bf16 v[22:25], v[168:171], v[222:225], v[22:25]
	v_mfma_f32_16x16x32_bf16 v[18:21], v[198:201], v[222:225], v[18:21]
	v_mfma_f32_16x16x32_bf16 v[6:9], v[168:171], v[230:233], v[6:9]
	v_mfma_f32_16x16x32_bf16 v[2:5], v[198:201], v[230:233], v[2:5]
	v_mfma_f32_16x16x32_bf16 v[54:57], v[194:197], v[210:213], v[54:57]
	v_mfma_f32_16x16x32_bf16 v[50:53], v[202:205], v[210:213], v[50:53]
	v_mfma_f32_16x16x32_bf16 v[38:41], v[194:197], v[218:221], v[38:41]
	v_mfma_f32_16x16x32_bf16 v[34:37], v[202:205], v[218:221], v[34:37]
	v_mfma_f32_16x16x32_bf16 v[22:25], v[194:197], v[226:229], v[22:25]
	v_mfma_f32_16x16x32_bf16 v[18:21], v[202:205], v[226:229], v[18:21]
	v_mfma_f32_16x16x32_bf16 v[6:9], v[194:197], v[234:237], v[6:9]
	v_mfma_f32_16x16x32_bf16 v[2:5], v[202:205], v[234:237], v[2:5]
	s_setprio 0
	s_barrier
	s_add_i32 s15, s15, 2
	s_add_u32 s12, s12, 0x100
	s_addc_u32 s13, s13, 0
	s_add_u32 s7, s7, 0x100
	s_addc_u32 s14, s14, 0
	s_cmp_gt_u32 s15, 13
	s_cbranch_scc0 .LBB0_1683
	s_and_b64 vcc, exec, s[36:37]
	s_cbranch_vccz .LBB0_1686
	s_barrier

;     __device__ __forceinline__ bool next(int i, Unit& u) const { if (!S.next(i, u)) return false; if (u.pn >= 4) u.pn += 2; return true; }
; #define PG8_STAGE(bufoff, gbase, voff) do { _Pragma("unroll") for (int _i = 0; _i < 2; ++_i) \
;         __builtin_amdgcn_global_load_lds((const unsigned*)((const char*)(gbase) + (voff)[_i]), (PG8_LAS unsigned*)(lds + (bufoff) + ldsw + _i * 8192), 16, 0, 0); } while (0)
; #define PG8_WAIT_V(n) asm volatile("s_waitcnt vmcnt(" #n ")" ::: "memory")
; #define PG8_WAIT_L(n) asm volatile("s_waitcnt lgkmcnt(" #n ")" ::: "memory")
; template <class Epi, class Sched, bool ALIGN_EPI = false, bool SP2 = false>
; __device__ __forceinline__ void gemm_phase(PG8_LAS unsigned char* lds, const Gemm g, const Sched& S, const Epi& E) {
;     ...
;         const bool has_next = S.next(ui + 1, nxt);
;         if constexpr (Epi::LDS_PF) { if (has_next) E.prefetch(nxt, lds + STAGE_BYTES + ((ui + 1) % 3) * 4096, wid, lane); }
;         const char* nA = has_next ? (const char*)g.A + (size_t)nxt.pm * tstepA : cA; const char* nB = has_next ? (const char*)g.Bt + (size_t)nxt.pn * tstepB : cB;
;         for (int t = 0; t < nt; t += 2) {
;             const bool last = (t == nt - 2);
;             const char* a1 = cA + (size_t)(t + 1) * kstep;
;             const char* a2 = last ? nA : cA + (size_t)(t + 2) * kstep; const char* b2 = last ? nB : cB + (size_t)(t + 2) * kstep;
;             const char* a3 = a2 + kstep; const char* b3 = b2 + kstep;
;             if (last && has_next) S.a_ready(nxt);
;             if constexpr (SP2) {
;             PG8_LDB(B0, 0, 0); PG8_LDB(B1, 0, 1); PG8_SCHED; PG8_LDA(At, 0, 0); PG8_STAGE(PG8_SA(1, 1), a1 + hstepA, voffA);
;             PG8_WAIT_V(8); PG8_WAIT_L(0); PG8_BAR; PG8_MMA(0, 0, At, B0); PG8_MMA(0, 1, At, B1); PG8_BAR; PG8_SCHED;
;             PG8_LDA(At, 0, 1); PG8_STAGE(PG8_SB(0, 0), b2, voffB); PG8_STAGE(PG8_SB(0, 1), b2 + hstepB, voffB); PG8_STAGE(PG8_SA(0, 0), a2, voffA);
;             PG8_WAIT_V(8); PG8_WAIT_L(0); PG8_BAR; PG8_MMA(1, 0, At, B0); PG8_MMA(1, 1, At, B1); PG8_BAR; PG8_SCHED;
;     ...
; #pragma unroll
;         for (int a = 0; a < 2; ++a)
; #pragma unroll
;             for (int b = 0; b < 2; ++b)
; #pragma unroll
;                 for (int m = 0; m < 4; ++m)
; #pragma unroll
;                     for (int n = 0; n < 2; ++n) acc[a][b][m][n] = (f32x4){0.f, 0.f, 0.f, 0.f};
.LBB0_1845:
	s_ashr_i32 s35, s34, 31
	s_lshl_b64 s[0:1], s[34:35], 19
	s_add_u32 s40, s24, s0
	s_addc_u32 s41, s25, s1
	s_and_b64 s[0:1], s[14:15], exec
	s_cselect_b32 s5, s41, s47
	s_cselect_b32 s7, s40, s46
	s_add_u32 s18, s46, 0x100
	v_mov_b32_e32 v2, 0
	s_addc_u32 s19, s47, 0
	s_mov_b32 s35, -2
	v_mov_b32_e32 v3, v2
	v_mov_b32_e32 v4, v2
	v_mov_b32_e32 v5, v2
	v_mov_b32_e32 v6, v2
	v_mov_b32_e32 v7, v2
	v_mov_b32_e32 v8, v2
	v_mov_b32_e32 v9, v2
	v_mov_b32_e32 v22, v2
	v_mov_b32_e32 v23, v2
	v_mov_b32_e32 v24, v2
	v_mov_b32_e32 v25, v2
	v_mov_b32_e32 v38, v2
	v_mov_b32_e32 v39, v2
	v_mov_b32_e32 v40, v2
	v_mov_b32_e32 v41, v2
	v_mov_b32_e32 v46, v2
	v_mov_b32_e32 v47, v2
	v_mov_b32_e32 v48, v2
	v_mov_b32_e32 v49, v2
	v_mov_b32_e32 v54, v2
	v_mov_b32_e32 v55, v2
	v_mov_b32_e32 v56, v2
	v_mov_b32_e32 v57, v2
	v_mov_b32_e32 v58, v2
	v_mov_b32_e32 v59, v2
	v_mov_b32_e32 v60, v2
	v_mov_b32_e32 v61, v2
	v_mov_b32_e32 v62, v2
	v_mov_b32_e32 v63, v2
	v_mov_b32_e32 v64, v2
	v_mov_b32_e32 v65, v2
	v_mov_b32_e32 v10, v2
	v_mov_b32_e32 v11, v2
	v_mov_b32_e32 v12, v2
	v_mov_b32_e32 v13, v2
	v_mov_b32_e32 v26, v2
	v_mov_b32_e32 v27, v2
	v_mov_b32_e32 v28, v2
	v_mov_b32_e32 v29, v2
	v_mov_b32_e32 v14, v2
	v_mov_b32_e32 v15, v2
	v_mov_b32_e32 v16, v2
	v_mov_b32_e32 v17, v2
	v_mov_b32_e32 v30, v2
	v_mov_b32_e32 v31, v2
	v_mov_b32_e32 v32, v2
	v_mov_b32_e32 v33, v2
	v_mov_b32_e32 v18, v2
	v_mov_b32_e32 v19, v2
	v_mov_b32_e32 v20, v2
	v_mov_b32_e32 v21, v2
	v_mov_b32_e32 v34, v2
	v_mov_b32_e32 v35, v2
	v_mov_b32_e32 v36, v2
	v_mov_b32_e32 v37, v2
	v_mov_b32_e32 v42, v2
	v_mov_b32_e32 v43, v2
	v_mov_b32_e32 v44, v2
	v_mov_b32_e32 v45, v2
	v_mov_b32_e32 v50, v2
	v_mov_b32_e32 v51, v2
	v_mov_b32_e32 v52, v2
	v_mov_b32_e32 v53, v2
	v_mov_b32_e32 v66, v2
	v_mov_b32_e32 v67, v2
	v_mov_b32_e32 v68, v2
	v_mov_b32_e32 v69, v2
	v_mov_b32_e32 v70, v2
	v_mov_b32_e32 v71, v2
	v_mov_b32_e32 v72, v2
	v_mov_b32_e32 v73, v2
	v_mov_b32_e32 v86, v2
	v_mov_b32_e32 v87, v2
	v_mov_b32_e32 v88, v2
	v_mov_b32_e32 v89, v2
	v_mov_b32_e32 v102, v2
	v_mov_b32_e32 v103, v2
	v_mov_b32_e32 v104, v2
	v_mov_b32_e32 v105, v2
	v_mov_b32_e32 v110, v2
	v_mov_b32_e32 v111, v2
	v_mov_b32_e32 v112, v2
	v_mov_b32_e32 v113, v2
	v_mov_b32_e32 v118, v2
	v_mov_b32_e32 v119, v2
	v_mov_b32_e32 v120, v2
	v_mov_b32_e32 v121, v2
	v_mov_b32_e32 v122, v2
	v_mov_b32_e32 v123, v2
	v_mov_b32_e32 v124, v2
	v_mov_b32_e32 v125, v2
	v_mov_b32_e32 v158, v2
	v_mov_b32_e32 v159, v2
	v_mov_b32_e32 v160, v2
	v_mov_b32_e32 v161, v2
	v_mov_b32_e32 v74, v2
	v_mov_b32_e32 v75, v2
	v_mov_b32_e32 v76, v2
	v_mov_b32_e32 v77, v2
	v_mov_b32_e32 v90, v2
	v_mov_b32_e32 v91, v2
	v_mov_b32_e32 v92, v2
	v_mov_b32_e32 v93, v2
	v_mov_b32_e32 v78, v2
	v_mov_b32_e32 v79, v2
	v_mov_b32_e32 v80, v2
	v_mov_b32_e32 v81, v2
	v_mov_b32_e32 v94, v2
	v_mov_b32_e32 v95, v2
	v_mov_b32_e32 v96, v2
	v_mov_b32_e32 v97, v2
	v_mov_b32_e32 v82, v2
	v_mov_b32_e32 v83, v2
	v_mov_b32_e32 v84, v2
	v_mov_b32_e32 v85, v2
	v_mov_b32_e32 v98, v2
	v_mov_b32_e32 v99, v2
	v_mov_b32_e32 v100, v2
	v_mov_b32_e32 v101, v2
	v_mov_b32_e32 v106, v2
	v_mov_b32_e32 v107, v2
	v_mov_b32_e32 v108, v2
	v_mov_b32_e32 v109, v2
	v_mov_b32_e32 v114, v2
	v_mov_b32_e32 v115, v2
	v_mov_b32_e32 v116, v2
	v_mov_b32_e32 v117, v2
.LBB0_1846:
	ds_read_b128 v[126:129], v205
	ds_read_b128 v[130:133], v205 offset:1024
	ds_read_b128 v[134:137], v205 offset:2048
	ds_read_b128 v[138:141], v205 offset:3072
	ds_read_b128 v[142:145], v206
	ds_read_b128 v[146:149], v206 offset:1024
	ds_read_b128 v[150:153], v206 offset:2048
	ds_read_b128 v[154:157], v206 offset:3072
	s_add_u32 s14, s44, 0x100
	s_addc_u32 s15, s45, 0
	s_cmp_eq_u32 s35, 12
	s_cselect_b32 s49, s39, s15
	s_cselect_b32 s48, s38, s14
	s_cselect_b32 s47, s5, s19
	s_cselect_b32 s46, s7, s18
	v_lshl_add_u64 v[226:227], s[44:45], 0, v[192:193]
	s_add_i32 m0, s50, 0xc000
	ds_read_b128 v[162:165], v207
	ds_read_b128 v[166:169], v207 offset:1024
	ds_read_b128 v[170:173], v207 offset:2048
	ds_read_b128 v[174:177], v207 offset:3072
	ds_read_b128 v[210:213], v207 offset:4096
	ds_read_b128 v[214:217], v207 offset:5120
	ds_read_b128 v[218:221], v207 offset:6144
	ds_read_b128 v[222:225], v207 offset:7168
	global_load_lds_dwordx4 v[226:227], off
	v_lshl_add_u64 v[226:227], s[44:45], 0, v[194:195]
	s_add_i32 m0, s50, 0xe000
	s_nop 0
	global_load_lds_dwordx4 v[226:227], off
	s_waitcnt vmcnt(8)
	s_waitcnt lgkmcnt(0)
	s_setprio 1
	s_barrier
	v_mfma_f32_16x16x32_bf16 v[114:117], v[126:129], v[162:165], v[114:117]
	v_mfma_f32_16x16x32_bf16 v[106:109], v[134:137], v[162:165], v[106:109]
	v_mfma_f32_16x16x32_bf16 v[98:101], v[126:129], v[170:173], v[98:101]
	v_mfma_f32_16x16x32_bf16 v[82:85], v[134:137], v[170:173], v[82:85]
	v_mfma_f32_16x16x32_bf16 v[94:97], v[126:129], v[210:213], v[94:97]
	v_mfma_f32_16x16x32_bf16 v[78:81], v[134:137], v[210:213], v[78:81]
	v_mfma_f32_16x16x32_bf16 v[90:93], v[126:129], v[218:221], v[90:93]
	v_mfma_f32_16x16x32_bf16 v[74:77], v[134:137], v[218:221], v[74:77]
	v_mfma_f32_16x16x32_bf16 v[114:117], v[130:133], v[166:169], v[114:117]
	v_mfma_f32_16x16x32_bf16 v[106:109], v[138:141], v[166:169], v[106:109]
	v_mfma_f32_16x16x32_bf16 v[98:101], v[130:133], v[174:177], v[98:101]
	v_mfma_f32_16x16x32_bf16 v[82:85], v[138:141], v[174:177], v[82:85]
	v_mfma_f32_16x16x32_bf16 v[94:97], v[130:133], v[214:217], v[94:97]
	v_mfma_f32_16x16x32_bf16 v[78:81], v[138:141], v[214:217], v[78:81]
	v_mfma_f32_16x16x32_bf16 v[90:93], v[130:133], v[222:225], v[90:93]
	v_mfma_f32_16x16x32_bf16 v[74:77], v[138:141], v[222:225], v[74:77]
	s_setprio 0
	s_setprio 1
	v_mfma_f32_16x16x32_bf16 v[158:161], v[142:145], v[162:165], v[158:161]
	v_mfma_f32_16x16x32_bf16 v[122:125], v[150:153], v[162:165], v[122:125]
	v_mfma_f32_16x16x32_bf16 v[118:121], v[142:145], v[170:173], v[118:121]
	v_mfma_f32_16x16x32_bf16 v[110:113], v[150:153], v[170:173], v[110:113]
	v_mfma_f32_16x16x32_bf16 v[102:105], v[142:145], v[210:213], v[102:105]
	v_mfma_f32_16x16x32_bf16 v[86:89], v[150:153], v[210:213], v[86:89]
	v_mfma_f32_16x16x32_bf16 v[70:73], v[142:145], v[218:221], v[70:73]
	v_mfma_f32_16x16x32_bf16 v[66:69], v[150:153], v[218:221], v[66:69]
	v_mfma_f32_16x16x32_bf16 v[158:161], v[146:149], v[166:169], v[158:161]
	v_mfma_f32_16x16x32_bf16 v[122:125], v[154:157], v[166:169], v[122:125]
	v_mfma_f32_16x16x32_bf16 v[118:121], v[146:149], v[174:177], v[118:121]
	v_mfma_f32_16x16x32_bf16 v[110:113], v[154:157], v[174:177], v[110:113]
	v_mfma_f32_16x16x32_bf16 v[102:105], v[146:149], v[214:217], v[102:105]
	v_mfma_f32_16x16x32_bf16 v[86:89], v[154:157], v[214:217], v[86:89]
	v_mfma_f32_16x16x32_bf16 v[70:73], v[146:149], v[222:225], v[70:73]
	v_mfma_f32_16x16x32_bf16 v[66:69], v[154:157], v[222:225], v[66:69]
	s_setprio 0
	s_barrier
; #define PG8_STAGE(bufoff, gbase, voff) do { _Pragma("unroll") for (int _i = 0; _i < 2; ++_i) \
;         __builtin_amdgcn_global_load_lds((const unsigned*)((const char*)(gbase) + (voff)[_i]), (PG8_LAS unsigned*)(lds + (bufoff) + ldsw + _i * 8192), 16, 0, 0); } while (0)
; #define PG8_LDA(dst, b, h) do { _Pragma("unroll") for (int m = 0; m < 4; ++m) _Pragma("unroll") for (int k = 0; k < 2; ++k) dst[m][k] = *(const PG8_LAS bf16x8*)(lds + PG8_SA(b, h) + aoff + m * 2048 + k * 1024); } while (0)
; #define PG8_LDB(dst, b, h) do { _Pragma("unroll") for (int n = 0; n < 2; ++n) _Pragma("unroll") for (int k = 0; k < 2; ++k) dst[n][k] = *(const PG8_LAS bf16x8*)(lds + PG8_SB(b, h) + boff + n * 2048 + k * 1024); } while (0)
; #define PG8_MMA(ai, bj, At, Bt) do { __builtin_amdgcn_s_setprio(1); _Pragma("unroll") for (int m = 0; m < 4; ++m) _Pragma("unroll") for (int n = 0; n < 2; ++n) _Pragma("unroll") for (int k = 0; k < 2; ++k) \
;         acc[ai][bj][m][n] = __builtin_amdgcn_mfma_f32_16x16x32_bf16(Bt[n][k], At[m][k], acc[ai][bj][m][n], 0, 0, 0); __builtin_amdgcn_s_setprio(0); } while (0)
; #define PG8_WAIT_V(n) asm volatile("s_waitcnt vmcnt(" #n ")" ::: "memory")
; #define PG8_WAIT_L(n) asm volatile("s_waitcnt lgkmcnt(" #n ")" ::: "memory")
; #define PG8_BAR __builtin_amdgcn_s_barrier()
; #define PG8_SCHED __builtin_amdgcn_sched_barrier(0)
; template <class Epi, class Sched, bool ALIGN_EPI = false, bool SP2 = false>
; __device__ __forceinline__ void gemm_phase(PG8_LAS unsigned char* lds, const Gemm g, const Sched& S, const Epi& E) {
;     ...
;             PG8_LDA(At, 0, 1); PG8_STAGE(PG8_SB(0, 0), b2, voffB); PG8_STAGE(PG8_SB(0, 1), b2 + hstepB, voffB); PG8_STAGE(PG8_SA(0, 0), a2, voffA);
;             PG8_WAIT_V(8); PG8_WAIT_L(0); PG8_BAR; PG8_MMA(1, 0, At, B0); PG8_MMA(1, 1, At, B1); PG8_BAR; PG8_SCHED;
;             PG8_LDB(B0, 1, 0); PG8_LDB(B1, 1, 1); PG8_SCHED; PG8_LDA(At, 1, 0); PG8_STAGE(PG8_SA(0, 1), a2 + hstepA, voffA);
;             PG8_WAIT_V(8); PG8_WAIT_L(0); PG8_BAR; PG8_MMA(0, 0, At, B0); PG8_MMA(0, 1, At, B1); PG8_BAR; PG8_SCHED;
	s_add_i32 s0, s70, s43
	v_lshl_add_u64 v[226:227], s[46:47], 0, v[180:181]
	s_mov_b32 m0, s0
	ds_read_b128 v[162:165], v207 offset:16384
	ds_read_b128 v[166:169], v207 offset:17408
	ds_read_b128 v[170:173], v207 offset:18432
	ds_read_b128 v[174:177], v207 offset:19456
	ds_read_b128 v[210:213], v207 offset:20480
	ds_read_b128 v[214:217], v207 offset:21504
	ds_read_b128 v[218:221], v207 offset:22528
	ds_read_b128 v[222:225], v207 offset:23552
	global_load_lds_dwordx4 v[226:227], off
	s_add_i32 m0, s0, 0x2000
	s_add_u32 s0, s46, 0x40000
	v_lshl_add_u64 v[228:229], s[46:47], 0, v[184:185]
	s_addc_u32 s1, s47, 0
	s_add_i32 s2, s71, s43
	global_load_lds_dwordx4 v[228:229], off
	v_lshl_add_u64 v[230:231], s[0:1], 0, v[180:181]
	s_mov_b32 m0, s2
	v_lshl_add_u64 v[232:233], s[48:49], 0, v[182:183]
	global_load_lds_dwordx4 v[230:231], off
	v_lshl_add_u64 v[230:231], s[0:1], 0, v[184:185]
	s_add_i32 m0, s2, 0x2000
	s_nop 0
	global_load_lds_dwordx4 v[230:231], off
	v_lshl_add_u64 v[230:231], s[48:49], 0, v[178:179]
	s_mov_b32 m0, s50
	s_nop 0
	global_load_lds_dwordx4 v[230:231], off
	s_mov_b32 m0, s51
	s_nop 0
	global_load_lds_dwordx4 v[232:233], off
	s_waitcnt vmcnt(8)
	s_waitcnt lgkmcnt(0)
	s_setprio 1
	s_barrier
	v_mfma_f32_16x16x32_bf16 v[50:53], v[126:129], v[162:165], v[50:53]
	v_mfma_f32_16x16x32_bf16 v[42:45], v[134:137], v[162:165], v[42:45]
	v_mfma_f32_16x16x32_bf16 v[34:37], v[126:129], v[170:173], v[34:37]
	v_mfma_f32_16x16x32_bf16 v[18:21], v[134:137], v[170:173], v[18:21]
	v_mfma_f32_16x16x32_bf16 v[30:33], v[126:129], v[210:213], v[30:33]
	v_mfma_f32_16x16x32_bf16 v[14:17], v[134:137], v[210:213], v[14:17]
	v_mfma_f32_16x16x32_bf16 v[26:29], v[126:129], v[218:221], v[26:29]
	v_mfma_f32_16x16x32_bf16 v[10:13], v[134:137], v[218:221], v[10:13]
	v_mfma_f32_16x16x32_bf16 v[50:53], v[130:133], v[166:169], v[50:53]
	v_mfma_f32_16x16x32_bf16 v[42:45], v[138:141], v[166:169], v[42:45]
	v_mfma_f32_16x16x32_bf16 v[34:37], v[130:133], v[174:177], v[34:37]
	v_mfma_f32_16x16x32_bf16 v[18:21], v[138:141], v[174:177], v[18:21]
	v_mfma_f32_16x16x32_bf16 v[30:33], v[130:133], v[214:217], v[30:33]
	v_mfma_f32_16x16x32_bf16 v[14:17], v[138:141], v[214:217], v[14:17]
	v_mfma_f32_16x16x32_bf16 v[26:29], v[130:133], v[222:225], v[26:29]
	v_mfma_f32_16x16x32_bf16 v[10:13], v[138:141], v[222:225], v[10:13]
	s_setprio 0
	s_setprio 1
	v_mfma_f32_16x16x32_bf16 v[62:65], v[142:145], v[162:165], v[62:65]
	v_mfma_f32_16x16x32_bf16 v[58:61], v[150:153], v[162:165], v[58:61]
	v_mfma_f32_16x16x32_bf16 v[54:57], v[142:145], v[170:173], v[54:57]
	v_mfma_f32_16x16x32_bf16 v[46:49], v[150:153], v[170:173], v[46:49]
	v_mfma_f32_16x16x32_bf16 v[38:41], v[142:145], v[210:213], v[38:41]
	v_mfma_f32_16x16x32_bf16 v[22:25], v[150:153], v[210:213], v[22:25]
	v_mfma_f32_16x16x32_bf16 v[6:9], v[142:145], v[218:221], v[6:9]
	v_mfma_f32_16x16x32_bf16 v[2:5], v[150:153], v[218:221], v[2:5]
	v_mfma_f32_16x16x32_bf16 v[62:65], v[146:149], v[166:169], v[62:65]
	v_mfma_f32_16x16x32_bf16 v[58:61], v[154:157], v[166:169], v[58:61]
	v_mfma_f32_16x16x32_bf16 v[54:57], v[146:149], v[174:177], v[54:57]
	v_mfma_f32_16x16x32_bf16 v[46:49], v[154:157], v[174:177], v[46:49]
	v_mfma_f32_16x16x32_bf16 v[38:41], v[146:149], v[214:217], v[38:41]
	v_mfma_f32_16x16x32_bf16 v[22:25], v[154:157], v[214:217], v[22:25]
	v_mfma_f32_16x16x32_bf16 v[6:9], v[146:149], v[222:225], v[6:9]
	v_mfma_f32_16x16x32_bf16 v[2:5], v[154:157], v[222:225], v[2:5]
	s_setprio 0
	s_barrier
	ds_read_b128 v[126:129], v208
	ds_read_b128 v[130:133], v208 offset:1024
	ds_read_b128 v[134:137], v208 offset:2048
	ds_read_b128 v[138:141], v208 offset:3072
	ds_read_b128 v[142:145], v209
	ds_read_b128 v[146:149], v209 offset:1024
	ds_read_b128 v[150:153], v209 offset:2048
	ds_read_b128 v[154:157], v209 offset:3072
	s_add_u32 s0, s48, 0x40000
	s_addc_u32 s1, s49, 0
	s_mov_b32 m0, s62
	v_lshl_add_u64 v[234:235], s[0:1], 0, v[178:179]
	ds_read_b128 v[162:165], v207 offset:32768
	ds_read_b128 v[166:169], v207 offset:33792
	ds_read_b128 v[170:173], v207 offset:34816
	ds_read_b128 v[174:177], v207 offset:35840
	ds_read_b128 v[210:213], v207 offset:36864
	ds_read_b128 v[214:217], v207 offset:37888
	ds_read_b128 v[218:221], v207 offset:38912
	ds_read_b128 v[222:225], v207 offset:39936
	global_load_lds_dwordx4 v[234:235], off
	v_lshl_add_u64 v[234:235], s[0:1], 0, v[182:183]
	s_mov_b32 m0, s63
	s_nop 0
	global_load_lds_dwordx4 v[234:235], off
	s_waitcnt vmcnt(8)
	s_waitcnt lgkmcnt(0)
	s_setprio 1
	s_barrier
; #define PG8_STAGE(bufoff, gbase, voff) do { _Pragma("unroll") for (int _i = 0; _i < 2; ++_i) \
;         __builtin_amdgcn_global_load_lds((const unsigned*)((const char*)(gbase) + (voff)[_i]), (PG8_LAS unsigned*)(lds + (bufoff) + ldsw + _i * 8192), 16, 0, 0); } while (0)
; #define PG8_LDA(dst, b, h) do { _Pragma("unroll") for (int m = 0; m < 4; ++m) _Pragma("unroll") for (int k = 0; k < 2; ++k) dst[m][k] = *(const PG8_LAS bf16x8*)(lds + PG8_SA(b, h) + aoff + m * 2048 + k * 1024); } while (0)
; #define PG8_MMA(ai, bj, At, Bt) do { __builtin_amdgcn_s_setprio(1); _Pragma("unroll") for (int m = 0; m < 4; ++m) _Pragma("unroll") for (int n = 0; n < 2; ++n) _Pragma("unroll") for (int k = 0; k < 2; ++k) \
;         acc[ai][bj][m][n] = __builtin_amdgcn_mfma_f32_16x16x32_bf16(Bt[n][k], At[m][k], acc[ai][bj][m][n], 0, 0, 0); __builtin_amdgcn_s_setprio(0); } while (0)
; #define PG8_WAIT_V(n) asm volatile("s_waitcnt vmcnt(" #n ")" ::: "memory")
; #define PG8_WAIT_L(n) asm volatile("s_waitcnt lgkmcnt(" #n ")" ::: "memory")
; #define PG8_BAR __builtin_amdgcn_s_barrier()
; #define PG8_SCHED __builtin_amdgcn_sched_barrier(0)
; template <class Epi, class Sched, bool ALIGN_EPI = false, bool SP2 = false>
; __device__ __forceinline__ void gemm_phase(PG8_LAS unsigned char* lds, const Gemm g, const Sched& S, const Epi& E) {
;     ...
;             PG8_WAIT_V(8); PG8_WAIT_L(0); PG8_BAR; PG8_MMA(0, 0, At, B0); PG8_MMA(0, 1, At, B1); PG8_BAR; PG8_SCHED;
;             PG8_LDA(At, 1, 1); PG8_STAGE(PG8_SB(1, 0), b3, voffB); PG8_STAGE(PG8_SB(1, 1), b3 + hstepB, voffB); PG8_STAGE(PG8_SA(1, 0), a3, voffA);
;             PG8_WAIT_V(8); PG8_WAIT_L(0); PG8_BAR; PG8_MMA(1, 0, At, B0); PG8_MMA(1, 1, At, B1); PG8_BAR; PG8_SCHED;
;     ...
;         if constexpr (ALIGN_EPI) { if (wr == 0) PG8_BAR; }
	v_mfma_f32_16x16x32_bf16 v[114:117], v[126:129], v[162:165], v[114:117]
	v_mfma_f32_16x16x32_bf16 v[106:109], v[134:137], v[162:165], v[106:109]
	v_mfma_f32_16x16x32_bf16 v[98:101], v[126:129], v[170:173], v[98:101]
	v_mfma_f32_16x16x32_bf16 v[82:85], v[134:137], v[170:173], v[82:85]
	v_mfma_f32_16x16x32_bf16 v[94:97], v[126:129], v[210:213], v[94:97]
	v_mfma_f32_16x16x32_bf16 v[78:81], v[134:137], v[210:213], v[78:81]
	v_mfma_f32_16x16x32_bf16 v[90:93], v[126:129], v[218:221], v[90:93]
	v_mfma_f32_16x16x32_bf16 v[74:77], v[134:137], v[218:221], v[74:77]
	v_mfma_f32_16x16x32_bf16 v[114:117], v[130:133], v[166:169], v[114:117]
	v_mfma_f32_16x16x32_bf16 v[106:109], v[138:141], v[166:169], v[106:109]
	v_mfma_f32_16x16x32_bf16 v[98:101], v[130:133], v[174:177], v[98:101]
	v_mfma_f32_16x16x32_bf16 v[82:85], v[138:141], v[174:177], v[82:85]
	v_mfma_f32_16x16x32_bf16 v[94:97], v[130:133], v[214:217], v[94:97]
	v_mfma_f32_16x16x32_bf16 v[78:81], v[138:141], v[214:217], v[78:81]
	v_mfma_f32_16x16x32_bf16 v[90:93], v[130:133], v[222:225], v[90:93]
	v_mfma_f32_16x16x32_bf16 v[74:77], v[138:141], v[222:225], v[74:77]
	s_setprio 0
	s_setprio 1
	v_mfma_f32_16x16x32_bf16 v[158:161], v[142:145], v[162:165], v[158:161]
	v_mfma_f32_16x16x32_bf16 v[122:125], v[150:153], v[162:165], v[122:125]
	v_mfma_f32_16x16x32_bf16 v[118:121], v[142:145], v[170:173], v[118:121]
	v_mfma_f32_16x16x32_bf16 v[110:113], v[150:153], v[170:173], v[110:113]
	v_mfma_f32_16x16x32_bf16 v[102:105], v[142:145], v[210:213], v[102:105]
	v_mfma_f32_16x16x32_bf16 v[86:89], v[150:153], v[210:213], v[86:89]
	v_mfma_f32_16x16x32_bf16 v[70:73], v[142:145], v[218:221], v[70:73]
	v_mfma_f32_16x16x32_bf16 v[66:69], v[150:153], v[218:221], v[66:69]
	v_mfma_f32_16x16x32_bf16 v[158:161], v[146:149], v[166:169], v[158:161]
	v_mfma_f32_16x16x32_bf16 v[122:125], v[154:157], v[166:169], v[122:125]
	v_mfma_f32_16x16x32_bf16 v[118:121], v[146:149], v[174:177], v[118:121]
	v_mfma_f32_16x16x32_bf16 v[110:113], v[154:157], v[174:177], v[110:113]
	v_mfma_f32_16x16x32_bf16 v[102:105], v[146:149], v[214:217], v[102:105]
	v_mfma_f32_16x16x32_bf16 v[86:89], v[154:157], v[214:217], v[86:89]
	v_mfma_f32_16x16x32_bf16 v[70:73], v[146:149], v[222:225], v[70:73]
	v_mfma_f32_16x16x32_bf16 v[66:69], v[154:157], v[222:225], v[66:69]
	s_setprio 0
	s_barrier
	s_add_i32 s0, s72, s43
	v_lshl_add_u64 v[226:227], v[226:227], 0, s[20:21]
	s_mov_b32 m0, s0
	ds_read_b128 v[162:165], v207 offset:49152
	ds_read_b128 v[166:169], v207 offset:50176
	ds_read_b128 v[170:173], v207 offset:51200
	ds_read_b128 v[174:177], v207 offset:52224
	ds_read_b128 v[210:213], v207 offset:53248
	ds_read_b128 v[214:217], v207 offset:54272
	ds_read_b128 v[218:221], v207 offset:55296
	ds_read_b128 v[222:225], v207 offset:56320
	global_load_lds_dwordx4 v[226:227], off
	s_add_i32 m0, s0, 0x2000
	s_add_u32 s0, s46, 0x40080
	v_lshl_add_u64 v[226:227], v[228:229], 0, s[20:21]
	s_addc_u32 s1, s47, 0
	s_add_i32 s2, s73, s43
	global_load_lds_dwordx4 v[226:227], off
	v_lshl_add_u64 v[226:227], s[0:1], 0, v[180:181]
	s_mov_b32 m0, s2
	s_nop 0
	global_load_lds_dwordx4 v[226:227], off
	v_lshl_add_u64 v[226:227], s[0:1], 0, v[184:185]
	s_add_i32 m0, s2, 0x2000
	s_nop 0
	global_load_lds_dwordx4 v[226:227], off
	v_lshl_add_u64 v[226:227], v[230:231], 0, s[20:21]
	s_mov_b32 m0, s66
	s_nop 0
	global_load_lds_dwordx4 v[226:227], off
	v_lshl_add_u64 v[226:227], v[232:233], 0, s[20:21]
	s_mov_b32 m0, s67
	s_nop 0
	global_load_lds_dwordx4 v[226:227], off
	s_waitcnt vmcnt(8)
	s_waitcnt lgkmcnt(0)
	s_setprio 1
	s_barrier
	v_mfma_f32_16x16x32_bf16 v[50:53], v[126:129], v[162:165], v[50:53]
	v_mfma_f32_16x16x32_bf16 v[42:45], v[134:137], v[162:165], v[42:45]
	v_mfma_f32_16x16x32_bf16 v[34:37], v[126:129], v[170:173], v[34:37]
	v_mfma_f32_16x16x32_bf16 v[18:21], v[134:137], v[170:173], v[18:21]
	v_mfma_f32_16x16x32_bf16 v[30:33], v[126:129], v[210:213], v[30:33]
	v_mfma_f32_16x16x32_bf16 v[14:17], v[134:137], v[210:213], v[14:17]
	v_mfma_f32_16x16x32_bf16 v[26:29], v[126:129], v[218:221], v[26:29]
	v_mfma_f32_16x16x32_bf16 v[10:13], v[134:137], v[218:221], v[10:13]
	v_mfma_f32_16x16x32_bf16 v[50:53], v[130:133], v[166:169], v[50:53]
	v_mfma_f32_16x16x32_bf16 v[42:45], v[138:141], v[166:169], v[42:45]
	v_mfma_f32_16x16x32_bf16 v[34:37], v[130:133], v[174:177], v[34:37]
	v_mfma_f32_16x16x32_bf16 v[18:21], v[138:141], v[174:177], v[18:21]
	v_mfma_f32_16x16x32_bf16 v[30:33], v[130:133], v[214:217], v[30:33]
	v_mfma_f32_16x16x32_bf16 v[14:17], v[138:141], v[214:217], v[14:17]
	v_mfma_f32_16x16x32_bf16 v[26:29], v[130:133], v[222:225], v[26:29]
	v_mfma_f32_16x16x32_bf16 v[10:13], v[138:141], v[222:225], v[10:13]
	s_setprio 0
	s_setprio 1
	v_mfma_f32_16x16x32_bf16 v[62:65], v[142:145], v[162:165], v[62:65]
	v_mfma_f32_16x16x32_bf16 v[58:61], v[150:153], v[162:165], v[58:61]
	v_mfma_f32_16x16x32_bf16 v[54:57], v[142:145], v[170:173], v[54:57]
	v_mfma_f32_16x16x32_bf16 v[46:49], v[150:153], v[170:173], v[46:49]
	v_mfma_f32_16x16x32_bf16 v[38:41], v[142:145], v[210:213], v[38:41]
	v_mfma_f32_16x16x32_bf16 v[22:25], v[150:153], v[210:213], v[22:25]
	v_mfma_f32_16x16x32_bf16 v[6:9], v[142:145], v[218:221], v[6:9]
	v_mfma_f32_16x16x32_bf16 v[2:5], v[150:153], v[218:221], v[2:5]
	v_mfma_f32_16x16x32_bf16 v[62:65], v[146:149], v[166:169], v[62:65]
	v_mfma_f32_16x16x32_bf16 v[58:61], v[154:157], v[166:169], v[58:61]
	v_mfma_f32_16x16x32_bf16 v[54:57], v[146:149], v[174:177], v[54:57]
	v_mfma_f32_16x16x32_bf16 v[46:49], v[154:157], v[174:177], v[46:49]
	v_mfma_f32_16x16x32_bf16 v[38:41], v[146:149], v[214:217], v[38:41]
	v_mfma_f32_16x16x32_bf16 v[22:25], v[154:157], v[214:217], v[22:25]
	v_mfma_f32_16x16x32_bf16 v[6:9], v[146:149], v[222:225], v[6:9]
	v_mfma_f32_16x16x32_bf16 v[2:5], v[154:157], v[222:225], v[2:5]
	s_setprio 0
	s_barrier
	s_add_i32 s35, s35, 2
	s_add_u32 s18, s18, 0x100
	s_addc_u32 s19, s19, 0
	s_cmp_gt_u32 s35, 13
	s_mov_b64 s[44:45], s[14:15]
	s_cbranch_scc0 .LBB0_1846
	s_and_b64 vcc, exec, s[28:29]
	s_cbranch_vccz .LBB0_1849
	s_barrier

;     __device__ __forceinline__ bool next(int i, Unit& u) const { if (!S.next(i, u)) return false; if (u.pn >= 4) u.pn += 2; return true; }
; #define PG8_STAGE(bufoff, gbase, voff) do { _Pragma("unroll") for (int _i = 0; _i < 2; ++_i) \
;         __builtin_amdgcn_global_load_lds((const unsigned*)((const char*)(gbase) + (voff)[_i]), (PG8_LAS unsigned*)(lds + (bufoff) + ldsw + _i * 8192), 16, 0, 0); } while (0)
; #define PG8_WAIT_V(n) asm volatile("s_waitcnt vmcnt(" #n ")" ::: "memory")
; #define PG8_WAIT_L(n) asm volatile("s_waitcnt lgkmcnt(" #n ")" ::: "memory")
; template <class Epi, class Sched, bool ALIGN_EPI = false, bool SP2 = false>
; __device__ __forceinline__ void gemm_phase(PG8_LAS unsigned char* lds, const Gemm g, const Sched& S, const Epi& E) {
;     ...
;         const bool has_next = S.next(ui + 1, nxt);
;         if constexpr (Epi::LDS_PF) { if (has_next) E.prefetch(nxt, lds + STAGE_BYTES + ((ui + 1) % 3) * 4096, wid, lane); }
;         const char* nA = has_next ? (const char*)g.A + (size_t)nxt.pm * tstepA : cA; const char* nB = has_next ? (const char*)g.Bt + (size_t)nxt.pn * tstepB : cB;
;         for (int t = 0; t < nt; t += 2) {
;             const bool last = (t == nt - 2);
;             const char* a1 = cA + (size_t)(t + 1) * kstep;
;             const char* a2 = last ? nA : cA + (size_t)(t + 2) * kstep; const char* b2 = last ? nB : cB + (size_t)(t + 2) * kstep;
;             const char* a3 = a2 + kstep; const char* b3 = b2 + kstep;
;             if (last && has_next) S.a_ready(nxt);
;             if constexpr (SP2) {
;             PG8_LDB(B0, 0, 0); PG8_LDB(B1, 0, 1); PG8_SCHED; PG8_LDA(At, 0, 0); PG8_STAGE(PG8_SA(1, 1), a1 + hstepA, voffA);
;             PG8_WAIT_V(8); PG8_WAIT_L(0); PG8_BAR; PG8_MMA(0, 0, At, B0); PG8_MMA(0, 1, At, B1); PG8_BAR; PG8_SCHED;
;             PG8_LDA(At, 0, 1); PG8_STAGE(PG8_SB(0, 0), b2, voffB); PG8_STAGE(PG8_SB(0, 1), b2 + hstepB, voffB); PG8_STAGE(PG8_SA(0, 0), a2, voffA);
;             PG8_WAIT_V(8); PG8_WAIT_L(0); PG8_BAR; PG8_MMA(1, 0, At, B0); PG8_MMA(1, 1, At, B1); PG8_BAR; PG8_SCHED;
;     ...
; #pragma unroll
;         for (int a = 0; a < 2; ++a)
; #pragma unroll
;             for (int b = 0; b < 2; ++b)
; #pragma unroll
;                 for (int m = 0; m < 4; ++m)
; #pragma unroll
;                     for (int n = 0; n < 2; ++n) acc[a][b][m][n] = (f32x4){0.f, 0.f, 0.f, 0.f};
.LBB0_1936:
	s_add_u32 s4, s42, 0x100
	v_mov_b32_e32 v2, 0
	s_addc_u32 s5, s43, 0
	s_mov_b32 s35, -2
	v_mov_b32_e32 v3, v2
	v_mov_b32_e32 v4, v2
	v_mov_b32_e32 v5, v2
	v_mov_b32_e32 v6, v2
	v_mov_b32_e32 v7, v2
	v_mov_b32_e32 v8, v2
	v_mov_b32_e32 v9, v2
	v_mov_b32_e32 v18, v2
	v_mov_b32_e32 v19, v2
	v_mov_b32_e32 v20, v2
	v_mov_b32_e32 v21, v2
	v_mov_b32_e32 v22, v2
	v_mov_b32_e32 v23, v2
	v_mov_b32_e32 v24, v2
	v_mov_b32_e32 v25, v2
	v_mov_b32_e32 v34, v2
	v_mov_b32_e32 v35, v2
	v_mov_b32_e32 v36, v2
	v_mov_b32_e32 v37, v2
	v_mov_b32_e32 v38, v2
	v_mov_b32_e32 v39, v2
	v_mov_b32_e32 v40, v2
	v_mov_b32_e32 v41, v2
	v_mov_b32_e32 v50, v2
	v_mov_b32_e32 v51, v2
	v_mov_b32_e32 v52, v2
	v_mov_b32_e32 v53, v2
	v_mov_b32_e32 v54, v2
	v_mov_b32_e32 v55, v2
	v_mov_b32_e32 v56, v2
	v_mov_b32_e32 v57, v2
	v_mov_b32_e32 v10, v2
	v_mov_b32_e32 v11, v2
	v_mov_b32_e32 v12, v2
	v_mov_b32_e32 v13, v2
	v_mov_b32_e32 v14, v2
	v_mov_b32_e32 v15, v2
	v_mov_b32_e32 v16, v2
	v_mov_b32_e32 v17, v2
	v_mov_b32_e32 v26, v2
	v_mov_b32_e32 v27, v2
	v_mov_b32_e32 v28, v2
	v_mov_b32_e32 v29, v2
	v_mov_b32_e32 v30, v2
	v_mov_b32_e32 v31, v2
	v_mov_b32_e32 v32, v2
	v_mov_b32_e32 v33, v2
	v_mov_b32_e32 v42, v2
	v_mov_b32_e32 v43, v2
	v_mov_b32_e32 v44, v2
	v_mov_b32_e32 v45, v2
	v_mov_b32_e32 v46, v2
	v_mov_b32_e32 v47, v2
	v_mov_b32_e32 v48, v2
	v_mov_b32_e32 v49, v2
	v_mov_b32_e32 v58, v2
	v_mov_b32_e32 v59, v2
	v_mov_b32_e32 v60, v2
	v_mov_b32_e32 v61, v2
	v_mov_b32_e32 v62, v2
	v_mov_b32_e32 v63, v2
	v_mov_b32_e32 v64, v2
	v_mov_b32_e32 v65, v2
	v_mov_b32_e32 v66, v2
	v_mov_b32_e32 v67, v2
	v_mov_b32_e32 v68, v2
	v_mov_b32_e32 v69, v2
	v_mov_b32_e32 v70, v2
	v_mov_b32_e32 v71, v2
	v_mov_b32_e32 v72, v2
	v_mov_b32_e32 v73, v2
	v_mov_b32_e32 v82, v2
	v_mov_b32_e32 v83, v2
	v_mov_b32_e32 v84, v2
	v_mov_b32_e32 v85, v2
	v_mov_b32_e32 v86, v2
	v_mov_b32_e32 v87, v2
	v_mov_b32_e32 v88, v2
	v_mov_b32_e32 v89, v2
	v_mov_b32_e32 v98, v2
	v_mov_b32_e32 v99, v2
	v_mov_b32_e32 v100, v2
	v_mov_b32_e32 v101, v2
	v_mov_b32_e32 v102, v2
	v_mov_b32_e32 v103, v2
	v_mov_b32_e32 v104, v2
	v_mov_b32_e32 v105, v2
	v_mov_b32_e32 v114, v2
	v_mov_b32_e32 v115, v2
	v_mov_b32_e32 v116, v2
	v_mov_b32_e32 v117, v2
	v_mov_b32_e32 v118, v2
	v_mov_b32_e32 v119, v2
	v_mov_b32_e32 v120, v2
	v_mov_b32_e32 v121, v2
	v_mov_b32_e32 v74, v2
	v_mov_b32_e32 v75, v2
	v_mov_b32_e32 v76, v2
	v_mov_b32_e32 v77, v2
	v_mov_b32_e32 v78, v2
	v_mov_b32_e32 v79, v2
	v_mov_b32_e32 v80, v2
	v_mov_b32_e32 v81, v2
	v_mov_b32_e32 v90, v2
	v_mov_b32_e32 v91, v2
	v_mov_b32_e32 v92, v2
	v_mov_b32_e32 v93, v2
	v_mov_b32_e32 v94, v2
	v_mov_b32_e32 v95, v2
	v_mov_b32_e32 v96, v2
	v_mov_b32_e32 v97, v2
	v_mov_b32_e32 v106, v2
	v_mov_b32_e32 v107, v2
	v_mov_b32_e32 v108, v2
	v_mov_b32_e32 v109, v2
	v_mov_b32_e32 v110, v2
	v_mov_b32_e32 v111, v2
	v_mov_b32_e32 v112, v2
	v_mov_b32_e32 v113, v2
	v_mov_b32_e32 v122, v2
	v_mov_b32_e32 v123, v2
	v_mov_b32_e32 v124, v2
	v_mov_b32_e32 v125, v2
	v_mov_b32_e32 v126, v2
	v_mov_b32_e32 v127, v2
	v_mov_b32_e32 v128, v2
	v_mov_b32_e32 v129, v2
.LBB0_1937:
	ds_read_b128 v[130:133], v189
	ds_read_b128 v[134:137], v189 offset:1024
	ds_read_b128 v[138:141], v189 offset:2048
	ds_read_b128 v[142:145], v189 offset:3072
	ds_read_b128 v[168:171], v190
	ds_read_b128 v[194:197], v190 offset:1024
	ds_read_b128 v[198:201], v190 offset:2048
	ds_read_b128 v[202:205], v190 offset:3072
	s_add_u32 s42, s40, 0x100
	s_addc_u32 s43, s41, 0
	s_cmp_eq_u32 s35, 40
	s_cselect_b32 s47, s11, s43
	s_cselect_b32 s46, s10, s42
	s_cselect_b32 s45, s37, s5
	s_cselect_b32 s44, s36, s4
	v_lshl_add_u64 v[238:239], s[40:41], 0, v[160:161]
	s_add_i32 m0, s48, 0xc000
	ds_read_b128 v[206:209], v191
	ds_read_b128 v[210:213], v191 offset:1024
	ds_read_b128 v[214:217], v191 offset:2048
	ds_read_b128 v[218:221], v191 offset:3072
	ds_read_b128 v[222:225], v191 offset:4096
	ds_read_b128 v[226:229], v191 offset:5120
	ds_read_b128 v[230:233], v191 offset:6144
	ds_read_b128 v[234:237], v191 offset:7168
	global_load_lds_dwordx4 v[238:239], off
	v_lshl_add_u64 v[238:239], s[40:41], 0, v[162:163]
	s_add_i32 m0, s48, 0xe000
	s_nop 0
	global_load_lds_dwordx4 v[238:239], off
	s_waitcnt vmcnt(8)
	s_waitcnt lgkmcnt(0)
	s_setprio 1
	s_barrier
	v_mfma_f32_16x16x32_bf16 v[126:129], v[130:133], v[206:209], v[126:129]
	v_mfma_f32_16x16x32_bf16 v[122:125], v[138:141], v[206:209], v[122:125]
	v_mfma_f32_16x16x32_bf16 v[110:113], v[130:133], v[214:217], v[110:113]
	v_mfma_f32_16x16x32_bf16 v[106:109], v[138:141], v[214:217], v[106:109]
	v_mfma_f32_16x16x32_bf16 v[94:97], v[130:133], v[222:225], v[94:97]
	v_mfma_f32_16x16x32_bf16 v[90:93], v[138:141], v[222:225], v[90:93]
	v_mfma_f32_16x16x32_bf16 v[78:81], v[130:133], v[230:233], v[78:81]
	v_mfma_f32_16x16x32_bf16 v[74:77], v[138:141], v[230:233], v[74:77]
	v_mfma_f32_16x16x32_bf16 v[126:129], v[134:137], v[210:213], v[126:129]
	v_mfma_f32_16x16x32_bf16 v[122:125], v[142:145], v[210:213], v[122:125]
	v_mfma_f32_16x16x32_bf16 v[110:113], v[134:137], v[218:221], v[110:113]
	v_mfma_f32_16x16x32_bf16 v[106:109], v[142:145], v[218:221], v[106:109]
	v_mfma_f32_16x16x32_bf16 v[94:97], v[134:137], v[226:229], v[94:97]
	v_mfma_f32_16x16x32_bf16 v[90:93], v[142:145], v[226:229], v[90:93]
	v_mfma_f32_16x16x32_bf16 v[78:81], v[134:137], v[234:237], v[78:81]
	v_mfma_f32_16x16x32_bf16 v[74:77], v[142:145], v[234:237], v[74:77]
	s_setprio 0
	s_setprio 1
	v_mfma_f32_16x16x32_bf16 v[118:121], v[168:171], v[206:209], v[118:121]
	v_mfma_f32_16x16x32_bf16 v[114:117], v[198:201], v[206:209], v[114:117]
	v_mfma_f32_16x16x32_bf16 v[102:105], v[168:171], v[214:217], v[102:105]
	v_mfma_f32_16x16x32_bf16 v[98:101], v[198:201], v[214:217], v[98:101]
	v_mfma_f32_16x16x32_bf16 v[86:89], v[168:171], v[222:225], v[86:89]
	v_mfma_f32_16x16x32_bf16 v[82:85], v[198:201], v[222:225], v[82:85]
	v_mfma_f32_16x16x32_bf16 v[70:73], v[168:171], v[230:233], v[70:73]
	v_mfma_f32_16x16x32_bf16 v[66:69], v[198:201], v[230:233], v[66:69]
	v_mfma_f32_16x16x32_bf16 v[118:121], v[194:197], v[210:213], v[118:121]
	v_mfma_f32_16x16x32_bf16 v[114:117], v[202:205], v[210:213], v[114:117]
	v_mfma_f32_16x16x32_bf16 v[102:105], v[194:197], v[218:221], v[102:105]
	v_mfma_f32_16x16x32_bf16 v[98:101], v[202:205], v[218:221], v[98:101]
	v_mfma_f32_16x16x32_bf16 v[86:89], v[194:197], v[226:229], v[86:89]
	v_mfma_f32_16x16x32_bf16 v[82:85], v[202:205], v[226:229], v[82:85]
	v_mfma_f32_16x16x32_bf16 v[70:73], v[194:197], v[234:237], v[70:73]
	v_mfma_f32_16x16x32_bf16 v[66:69], v[202:205], v[234:237], v[66:69]
	s_setprio 0
	s_barrier
; #define PG8_STAGE(bufoff, gbase, voff) do { _Pragma("unroll") for (int _i = 0; _i < 2; ++_i) \
;         __builtin_amdgcn_global_load_lds((const unsigned*)((const char*)(gbase) + (voff)[_i]), (PG8_LAS unsigned*)(lds + (bufoff) + ldsw + _i * 8192), 16, 0, 0); } while (0)
; #define PG8_LDA(dst, b, h) do { _Pragma("unroll") for (int m = 0; m < 4; ++m) _Pragma("unroll") for (int k = 0; k < 2; ++k) dst[m][k] = *(const PG8_LAS bf16x8*)(lds + PG8_SA(b, h) + aoff + m * 2048 + k * 1024); } while (0)
; #define PG8_LDB(dst, b, h) do { _Pragma("unroll") for (int n = 0; n < 2; ++n) _Pragma("unroll") for (int k = 0; k < 2; ++k) dst[n][k] = *(const PG8_LAS bf16x8*)(lds + PG8_SB(b, h) + boff + n * 2048 + k * 1024); } while (0)
; #define PG8_MMA(ai, bj, At, Bt) do { __builtin_amdgcn_s_setprio(1); _Pragma("unroll") for (int m = 0; m < 4; ++m) _Pragma("unroll") for (int n = 0; n < 2; ++n) _Pragma("unroll") for (int k = 0; k < 2; ++k) \
;         acc[ai][bj][m][n] = __builtin_amdgcn_mfma_f32_16x16x32_bf16(Bt[n][k], At[m][k], acc[ai][bj][m][n], 0, 0, 0); __builtin_amdgcn_s_setprio(0); } while (0)
; #define PG8_WAIT_V(n) asm volatile("s_waitcnt vmcnt(" #n ")" ::: "memory")
; #define PG8_WAIT_L(n) asm volatile("s_waitcnt lgkmcnt(" #n ")" ::: "memory")
; #define PG8_BAR __builtin_amdgcn_s_barrier()
; #define PG8_SCHED __builtin_amdgcn_sched_barrier(0)
; template <class Epi, class Sched, bool ALIGN_EPI = false, bool SP2 = false>
; __device__ __forceinline__ void gemm_phase(PG8_LAS unsigned char* lds, const Gemm g, const Sched& S, const Epi& E) {
;     ...
;             PG8_LDA(At, 0, 1); PG8_STAGE(PG8_SB(0, 0), b2, voffB); PG8_STAGE(PG8_SB(0, 1), b2 + hstepB, voffB); PG8_STAGE(PG8_SA(0, 0), a2, voffA);
;             PG8_WAIT_V(8); PG8_WAIT_L(0); PG8_BAR; PG8_MMA(1, 0, At, B0); PG8_MMA(1, 1, At, B1); PG8_BAR; PG8_SCHED;
;             PG8_LDB(B0, 1, 0); PG8_LDB(B1, 1, 1); PG8_SCHED; PG8_LDA(At, 1, 0); PG8_STAGE(PG8_SA(0, 1), a2 + hstepA, voffA);
;             PG8_WAIT_V(8); PG8_WAIT_L(0); PG8_BAR; PG8_MMA(0, 0, At, B0); PG8_MMA(0, 1, At, B1); PG8_BAR; PG8_SCHED;
	s_add_i32 s0, s66, s39
	v_lshl_add_u64 v[238:239], s[44:45], 0, v[146:147]
	s_mov_b32 m0, s0
	ds_read_b128 v[206:209], v191 offset:16384
	ds_read_b128 v[210:213], v191 offset:17408
	ds_read_b128 v[214:217], v191 offset:18432
	ds_read_b128 v[218:221], v191 offset:19456
	ds_read_b128 v[222:225], v191 offset:20480
	ds_read_b128 v[226:229], v191 offset:21504
	ds_read_b128 v[230:233], v191 offset:22528
	ds_read_b128 v[234:237], v191 offset:23552
	global_load_lds_dwordx4 v[238:239], off
	s_add_i32 m0, s0, 0x2000
	s_add_u32 s0, s44, 0xb0000
	v_lshl_add_u64 v[240:241], s[44:45], 0, v[152:153]
	s_addc_u32 s1, s45, 0
	s_add_i32 s2, s67, s39
	global_load_lds_dwordx4 v[240:241], off
	v_lshl_add_u64 v[242:243], s[0:1], 0, v[146:147]
	s_mov_b32 m0, s2
	v_lshl_add_u64 v[244:245], s[46:47], 0, v[150:151]
	global_load_lds_dwordx4 v[242:243], off
	v_lshl_add_u64 v[242:243], s[0:1], 0, v[152:153]
	s_add_i32 m0, s2, 0x2000
	s_nop 0
	global_load_lds_dwordx4 v[242:243], off
	v_lshl_add_u64 v[242:243], s[46:47], 0, v[148:149]
	s_mov_b32 m0, s48
	s_nop 0
	global_load_lds_dwordx4 v[242:243], off
	s_mov_b32 m0, s49
	s_nop 0
	global_load_lds_dwordx4 v[244:245], off
	s_waitcnt vmcnt(8)
	s_waitcnt lgkmcnt(0)
	s_setprio 1
	s_barrier
	v_mfma_f32_16x16x32_bf16 v[62:65], v[130:133], v[206:209], v[62:65]
	v_mfma_f32_16x16x32_bf16 v[58:61], v[138:141], v[206:209], v[58:61]
	v_mfma_f32_16x16x32_bf16 v[46:49], v[130:133], v[214:217], v[46:49]
	v_mfma_f32_16x16x32_bf16 v[42:45], v[138:141], v[214:217], v[42:45]
	v_mfma_f32_16x16x32_bf16 v[30:33], v[130:133], v[222:225], v[30:33]
	v_mfma_f32_16x16x32_bf16 v[26:29], v[138:141], v[222:225], v[26:29]
	v_mfma_f32_16x16x32_bf16 v[14:17], v[130:133], v[230:233], v[14:17]
	v_mfma_f32_16x16x32_bf16 v[10:13], v[138:141], v[230:233], v[10:13]
	v_mfma_f32_16x16x32_bf16 v[62:65], v[134:137], v[210:213], v[62:65]
	v_mfma_f32_16x16x32_bf16 v[58:61], v[142:145], v[210:213], v[58:61]
	v_mfma_f32_16x16x32_bf16 v[46:49], v[134:137], v[218:221], v[46:49]
	v_mfma_f32_16x16x32_bf16 v[42:45], v[142:145], v[218:221], v[42:45]
	v_mfma_f32_16x16x32_bf16 v[30:33], v[134:137], v[226:229], v[30:33]
	v_mfma_f32_16x16x32_bf16 v[26:29], v[142:145], v[226:229], v[26:29]
	v_mfma_f32_16x16x32_bf16 v[14:17], v[134:137], v[234:237], v[14:17]
	v_mfma_f32_16x16x32_bf16 v[10:13], v[142:145], v[234:237], v[10:13]
	s_setprio 0
	s_setprio 1
	v_mfma_f32_16x16x32_bf16 v[54:57], v[168:171], v[206:209], v[54:57]
	v_mfma_f32_16x16x32_bf16 v[50:53], v[198:201], v[206:209], v[50:53]
	v_mfma_f32_16x16x32_bf16 v[38:41], v[168:171], v[214:217], v[38:41]
	v_mfma_f32_16x16x32_bf16 v[34:37], v[198:201], v[214:217], v[34:37]
	v_mfma_f32_16x16x32_bf16 v[22:25], v[168:171], v[222:225], v[22:25]
	v_mfma_f32_16x16x32_bf16 v[18:21], v[198:201], v[222:225], v[18:21]
	v_mfma_f32_16x16x32_bf16 v[6:9], v[168:171], v[230:233], v[6:9]
	v_mfma_f32_16x16x32_bf16 v[2:5], v[198:201], v[230:233], v[2:5]
	v_mfma_f32_16x16x32_bf16 v[54:57], v[194:197], v[210:213], v[54:57]
	v_mfma_f32_16x16x32_bf16 v[50:53], v[202:205], v[210:213], v[50:53]
	v_mfma_f32_16x16x32_bf16 v[38:41], v[194:197], v[218:221], v[38:41]
	v_mfma_f32_16x16x32_bf16 v[34:37], v[202:205], v[218:221], v[34:37]
	v_mfma_f32_16x16x32_bf16 v[22:25], v[194:197], v[226:229], v[22:25]
	v_mfma_f32_16x16x32_bf16 v[18:21], v[202:205], v[226:229], v[18:21]
	v_mfma_f32_16x16x32_bf16 v[6:9], v[194:197], v[234:237], v[6:9]
	v_mfma_f32_16x16x32_bf16 v[2:5], v[202:205], v[234:237], v[2:5]
	s_setprio 0
	s_barrier
	ds_read_b128 v[130:133], v192
	ds_read_b128 v[134:137], v192 offset:1024
	ds_read_b128 v[138:141], v192 offset:2048
	ds_read_b128 v[142:145], v192 offset:3072
	ds_read_b128 v[168:171], v193
	ds_read_b128 v[194:197], v193 offset:1024
	ds_read_b128 v[198:201], v193 offset:2048
	ds_read_b128 v[202:205], v193 offset:3072
	s_add_u32 s0, s46, 0xb0000
	s_addc_u32 s1, s47, 0
	s_mov_b32 m0, s50
	v_lshl_add_u64 v[246:247], s[0:1], 0, v[148:149]
	ds_read_b128 v[206:209], v191 offset:32768
	ds_read_b128 v[210:213], v191 offset:33792
	ds_read_b128 v[214:217], v191 offset:34816
	ds_read_b128 v[218:221], v191 offset:35840
	ds_read_b128 v[222:225], v191 offset:36864
	ds_read_b128 v[226:229], v191 offset:37888
	ds_read_b128 v[230:233], v191 offset:38912
	ds_read_b128 v[234:237], v191 offset:39936
	global_load_lds_dwordx4 v[246:247], off
	v_lshl_add_u64 v[246:247], s[0:1], 0, v[150:151]
	s_mov_b32 m0, s51
	s_nop 0
	global_load_lds_dwordx4 v[246:247], off
	s_waitcnt vmcnt(8)
	s_waitcnt lgkmcnt(0)
	s_setprio 1
	s_barrier
; #define PG8_STAGE(bufoff, gbase, voff) do { _Pragma("unroll") for (int _i = 0; _i < 2; ++_i) \
;         __builtin_amdgcn_global_load_lds((const unsigned*)((const char*)(gbase) + (voff)[_i]), (PG8_LAS unsigned*)(lds + (bufoff) + ldsw + _i * 8192), 16, 0, 0); } while (0)
; #define PG8_LDA(dst, b, h) do { _Pragma("unroll") for (int m = 0; m < 4; ++m) _Pragma("unroll") for (int k = 0; k < 2; ++k) dst[m][k] = *(const PG8_LAS bf16x8*)(lds + PG8_SA(b, h) + aoff + m * 2048 + k * 1024); } while (0)
; #define PG8_MMA(ai, bj, At, Bt) do { __builtin_amdgcn_s_setprio(1); _Pragma("unroll") for (int m = 0; m < 4; ++m) _Pragma("unroll") for (int n = 0; n < 2; ++n) _Pragma("unroll") for (int k = 0; k < 2; ++k) \
;         acc[ai][bj][m][n] = __builtin_amdgcn_mfma_f32_16x16x32_bf16(Bt[n][k], At[m][k], acc[ai][bj][m][n], 0, 0, 0); __builtin_amdgcn_s_setprio(0); } while (0)
; #define PG8_WAIT_V(n) asm volatile("s_waitcnt vmcnt(" #n ")" ::: "memory")
; #define PG8_WAIT_L(n) asm volatile("s_waitcnt lgkmcnt(" #n ")" ::: "memory")
; #define PG8_BAR __builtin_amdgcn_s_barrier()
; #define PG8_SCHED __builtin_amdgcn_sched_barrier(0)
; template <class Epi, class Sched, bool ALIGN_EPI = false, bool SP2 = false>
; __device__ __forceinline__ void gemm_phase(PG8_LAS unsigned char* lds, const Gemm g, const Sched& S, const Epi& E) {
;     ...
;             PG8_WAIT_V(8); PG8_WAIT_L(0); PG8_BAR; PG8_MMA(0, 0, At, B0); PG8_MMA(0, 1, At, B1); PG8_BAR; PG8_SCHED;
;             PG8_LDA(At, 1, 1); PG8_STAGE(PG8_SB(1, 0), b3, voffB); PG8_STAGE(PG8_SB(1, 1), b3 + hstepB, voffB); PG8_STAGE(PG8_SA(1, 0), a3, voffA);
;             PG8_WAIT_V(8); PG8_WAIT_L(0); PG8_BAR; PG8_MMA(1, 0, At, B0); PG8_MMA(1, 1, At, B1); PG8_BAR; PG8_SCHED;
;     ...
;         if constexpr (ALIGN_EPI) { if (wr == 0) PG8_BAR; }
	v_mfma_f32_16x16x32_bf16 v[126:129], v[130:133], v[206:209], v[126:129]
	v_mfma_f32_16x16x32_bf16 v[122:125], v[138:141], v[206:209], v[122:125]
	v_mfma_f32_16x16x32_bf16 v[110:113], v[130:133], v[214:217], v[110:113]
	v_mfma_f32_16x16x32_bf16 v[106:109], v[138:141], v[214:217], v[106:109]
	v_mfma_f32_16x16x32_bf16 v[94:97], v[130:133], v[222:225], v[94:97]
	v_mfma_f32_16x16x32_bf16 v[90:93], v[138:141], v[222:225], v[90:93]
	v_mfma_f32_16x16x32_bf16 v[78:81], v[130:133], v[230:233], v[78:81]
	v_mfma_f32_16x16x32_bf16 v[74:77], v[138:141], v[230:233], v[74:77]
	v_mfma_f32_16x16x32_bf16 v[126:129], v[134:137], v[210:213], v[126:129]
	v_mfma_f32_16x16x32_bf16 v[122:125], v[142:145], v[210:213], v[122:125]
	v_mfma_f32_16x16x32_bf16 v[110:113], v[134:137], v[218:221], v[110:113]
	v_mfma_f32_16x16x32_bf16 v[106:109], v[142:145], v[218:221], v[106:109]
	v_mfma_f32_16x16x32_bf16 v[94:97], v[134:137], v[226:229], v[94:97]
	v_mfma_f32_16x16x32_bf16 v[90:93], v[142:145], v[226:229], v[90:93]
	v_mfma_f32_16x16x32_bf16 v[78:81], v[134:137], v[234:237], v[78:81]
	v_mfma_f32_16x16x32_bf16 v[74:77], v[142:145], v[234:237], v[74:77]
	s_setprio 0
	s_setprio 1
	v_mfma_f32_16x16x32_bf16 v[118:121], v[168:171], v[206:209], v[118:121]
	v_mfma_f32_16x16x32_bf16 v[114:117], v[198:201], v[206:209], v[114:117]
	v_mfma_f32_16x16x32_bf16 v[102:105], v[168:171], v[214:217], v[102:105]
	v_mfma_f32_16x16x32_bf16 v[98:101], v[198:201], v[214:217], v[98:101]
	v_mfma_f32_16x16x32_bf16 v[86:89], v[168:171], v[222:225], v[86:89]
	v_mfma_f32_16x16x32_bf16 v[82:85], v[198:201], v[222:225], v[82:85]
	v_mfma_f32_16x16x32_bf16 v[70:73], v[168:171], v[230:233], v[70:73]
	v_mfma_f32_16x16x32_bf16 v[66:69], v[198:201], v[230:233], v[66:69]
	v_mfma_f32_16x16x32_bf16 v[118:121], v[194:197], v[210:213], v[118:121]
	v_mfma_f32_16x16x32_bf16 v[114:117], v[202:205], v[210:213], v[114:117]
	v_mfma_f32_16x16x32_bf16 v[102:105], v[194:197], v[218:221], v[102:105]
	v_mfma_f32_16x16x32_bf16 v[98:101], v[202:205], v[218:221], v[98:101]
	v_mfma_f32_16x16x32_bf16 v[86:89], v[194:197], v[226:229], v[86:89]
	v_mfma_f32_16x16x32_bf16 v[82:85], v[202:205], v[226:229], v[82:85]
	v_mfma_f32_16x16x32_bf16 v[70:73], v[194:197], v[234:237], v[70:73]
	v_mfma_f32_16x16x32_bf16 v[66:69], v[202:205], v[234:237], v[66:69]
	s_setprio 0
	s_barrier
	s_add_i32 s0, s68, s39
	v_lshl_add_u64 v[238:239], v[238:239], 0, s[12:13]
	s_mov_b32 m0, s0
	ds_read_b128 v[206:209], v191 offset:49152
	ds_read_b128 v[210:213], v191 offset:50176
	ds_read_b128 v[214:217], v191 offset:51200
	ds_read_b128 v[218:221], v191 offset:52224
	ds_read_b128 v[222:225], v191 offset:53248
	ds_read_b128 v[226:229], v191 offset:54272
	ds_read_b128 v[230:233], v191 offset:55296
	ds_read_b128 v[234:237], v191 offset:56320
	global_load_lds_dwordx4 v[238:239], off
	s_add_i32 m0, s0, 0x2000
	s_add_u32 s0, s44, 0xb0080
	v_lshl_add_u64 v[238:239], v[240:241], 0, s[12:13]
	s_addc_u32 s1, s45, 0
	s_add_i32 s2, s69, s39
	global_load_lds_dwordx4 v[238:239], off
	v_lshl_add_u64 v[238:239], s[0:1], 0, v[146:147]
	s_mov_b32 m0, s2
	s_nop 0
	global_load_lds_dwordx4 v[238:239], off
	v_lshl_add_u64 v[238:239], s[0:1], 0, v[152:153]
	s_add_i32 m0, s2, 0x2000
	s_nop 0
	global_load_lds_dwordx4 v[238:239], off
	v_lshl_add_u64 v[238:239], v[242:243], 0, s[12:13]
	s_mov_b32 m0, s62
	s_nop 0
	global_load_lds_dwordx4 v[238:239], off
	v_lshl_add_u64 v[238:239], v[244:245], 0, s[12:13]
	s_mov_b32 m0, s63
	s_nop 0
	global_load_lds_dwordx4 v[238:239], off
	s_waitcnt vmcnt(8)
	s_waitcnt lgkmcnt(0)
	s_setprio 1
	s_barrier
	v_mfma_f32_16x16x32_bf16 v[62:65], v[130:133], v[206:209], v[62:65]
	v_mfma_f32_16x16x32_bf16 v[58:61], v[138:141], v[206:209], v[58:61]
	v_mfma_f32_16x16x32_bf16 v[46:49], v[130:133], v[214:217], v[46:49]
	v_mfma_f32_16x16x32_bf16 v[42:45], v[138:141], v[214:217], v[42:45]
	v_mfma_f32_16x16x32_bf16 v[30:33], v[130:133], v[222:225], v[30:33]
	v_mfma_f32_16x16x32_bf16 v[26:29], v[138:141], v[222:225], v[26:29]
	v_mfma_f32_16x16x32_bf16 v[14:17], v[130:133], v[230:233], v[14:17]
	v_mfma_f32_16x16x32_bf16 v[10:13], v[138:141], v[230:233], v[10:13]
	v_mfma_f32_16x16x32_bf16 v[62:65], v[134:137], v[210:213], v[62:65]
	v_mfma_f32_16x16x32_bf16 v[58:61], v[142:145], v[210:213], v[58:61]
	v_mfma_f32_16x16x32_bf16 v[46:49], v[134:137], v[218:221], v[46:49]
	v_mfma_f32_16x16x32_bf16 v[42:45], v[142:145], v[218:221], v[42:45]
	v_mfma_f32_16x16x32_bf16 v[30:33], v[134:137], v[226:229], v[30:33]
	v_mfma_f32_16x16x32_bf16 v[26:29], v[142:145], v[226:229], v[26:29]
	v_mfma_f32_16x16x32_bf16 v[14:17], v[134:137], v[234:237], v[14:17]
	v_mfma_f32_16x16x32_bf16 v[10:13], v[142:145], v[234:237], v[10:13]
	s_setprio 0
	s_setprio 1
	v_mfma_f32_16x16x32_bf16 v[54:57], v[168:171], v[206:209], v[54:57]
	v_mfma_f32_16x16x32_bf16 v[50:53], v[198:201], v[206:209], v[50:53]
	v_mfma_f32_16x16x32_bf16 v[38:41], v[168:171], v[214:217], v[38:41]
	v_mfma_f32_16x16x32_bf16 v[34:37], v[198:201], v[214:217], v[34:37]
	v_mfma_f32_16x16x32_bf16 v[22:25], v[168:171], v[222:225], v[22:25]
	v_mfma_f32_16x16x32_bf16 v[18:21], v[198:201], v[222:225], v[18:21]
	v_mfma_f32_16x16x32_bf16 v[6:9], v[168:171], v[230:233], v[6:9]
	v_mfma_f32_16x16x32_bf16 v[2:5], v[198:201], v[230:233], v[2:5]
	v_mfma_f32_16x16x32_bf16 v[54:57], v[194:197], v[210:213], v[54:57]
	v_mfma_f32_16x16x32_bf16 v[50:53], v[202:205], v[210:213], v[50:53]
	v_mfma_f32_16x16x32_bf16 v[38:41], v[194:197], v[218:221], v[38:41]
	v_mfma_f32_16x16x32_bf16 v[34:37], v[202:205], v[218:221], v[34:37]
	v_mfma_f32_16x16x32_bf16 v[22:25], v[194:197], v[226:229], v[22:25]
	v_mfma_f32_16x16x32_bf16 v[18:21], v[202:205], v[226:229], v[18:21]
	v_mfma_f32_16x16x32_bf16 v[6:9], v[194:197], v[234:237], v[6:9]
	v_mfma_f32_16x16x32_bf16 v[2:5], v[202:205], v[234:237], v[2:5]
	s_setprio 0
	s_barrier
	s_add_i32 s35, s35, 2
	s_add_u32 s4, s4, 0x100
	s_addc_u32 s5, s5, 0
	s_cmp_gt_u32 s35, 41
	s_mov_b64 s[40:41], s[42:43]
	s_cbranch_scc0 .LBB0_1937
	s_and_b64 vcc, exec, s[18:19]
	s_cbranch_vccz .LBB0_1940
	s_barrier
